# FFN-up epilogues: removed 512 dead zero-inits of full-row DPP destinations (hazard distances re-checked)
# speedup vs baseline: 1.0170x; 1.0170x over previous
; __device__ __forceinline__ unsigned cvt_pk_bf16(float lo, float hi) { unsigned r; asm volatile("v_cvt_pk_bf16_f32 %0, %1, %2" : "=v"(r) : "v"(lo), "v"(hi)); return r; }
;     __device__ __forceinline__ void operator()(const f32x4 (&acc)[2][2][4][2], const pg8::Unit& u, int wr, int wc, int fr, int fq) const {
;         u32x2 held[2][4];
; #pragma unroll
;         for (int n = 0; n < 2; ++n) {
;             const int f0 = u.pn * 128 + wc * 32 + 8 * fq + 4 * n;
;             f32x4 w[2][3], bb[2];
; #pragma unroll
;             for (int bj = 0; bj < 2; ++bj) { const int col = bj * FFN + f0; bb[bj] = *(const f32x4*)(cb + col);
; #pragma unroll
;                 for (int tp = 0; tp < 3; ++tp) w[bj][tp] = *(const f32x4*)(cw + tp * FFN2 + col); }
; #pragma unroll
;             for (int ai = 0; ai < 2; ++ai) {
;                 const int wb = (u.pm * 2 + ai) * 2 + wr;
;                 f32x4 p1[2], p2[2];
;                 p1[0] = p1[1] = p2[0] = p2[1] = (f32x4){0.f, 0.f, 0.f, 0.f};
; #pragma unroll
;                 for (int m = 0; m < 4; ++m) {
;                     f32x4 y[2];
; #pragma unroll
;                     for (int bj = 0; bj < 2; ++bj) {
;                         const f32x4 cur = acc[ai][bj][m][n]; f32x4 r1, r2;
; #pragma unroll
;                         for (int j = 0; j < 4; ++j) { r1[j] = dpp_ror<0x121>(cur[j]); r2[j] = dpp_ror<0x122>(cur[j]); }
;                         const f32x4 s1 = (fr >= 1) ? r1 : p1[bj], s2 = (fr >= 2) ? r2 : p2[bj];
;                         y[bj] = bb[bj] + w[bj][0] * s2 + w[bj][1] * s1 + w[bj][2] * cur;
;                         p1[bj] = r1; p2[bj] = r2;
;                         if (m == 0 && fr < 2) *(f32x4*)(hf + (size_t)(wb * 2 + fr) * FFN2 + bj * FFN + f0) = cur;
;                         if (m == 3 && fr >= 14) *(f32x4*)(hl + (size_t)(wb * 2 + fr - 14) * FFN2 + bj * FFN + f0) = cur;
;                     }
;                     u32x2 o; o.x = pg8::cvt_pk_bf16(silu_f(y[0][0]) * y[1][0], silu_f(y[0][1]) * y[1][1]); o.y = pg8::cvt_pk_bf16(silu_f(y[0][2]) * y[1][2], silu_f(y[0][3]) * y[1][3]);
;                     if (n == 0) held[ai][m] = o;
;                     else *(u32x4*)(act + (size_t)(wb * 64 + m * 16 + fr) * FFN + f0 - 4) = (u32x4){held[ai][m].x, held[ai][m].y, o.x, o.y};
;                 }
.LBB0_490:
	v_lshl_or_b32 v176, s48, 7, v199
	v_ashrrev_i32_e32 v177, 31, v176
	v_lshlrev_b64 v[112:113], 2, v[176:177]
	v_lshl_add_u64 v[180:181], s[16:17], 0, v[112:113]
	v_lshl_add_u64 v[182:183], s[18:19], 0, v[112:113]
	v_add_co_u32_e32 v112, vcc, 0x5000, v180
	global_load_dwordx4 v[120:123], v[182:183], off
	s_nop 0
	v_addc_co_u32_e32 v113, vcc, 0, v181, vcc
	v_add_co_u32_e32 v116, vcc, 0xb000, v180
	global_load_dwordx4 v[124:127], v[180:181], off
	s_nop 0
	global_load_dwordx4 v[112:115], v[112:113], off offset:2048
	v_addc_co_u32_e32 v117, vcc, 0, v181, vcc
	v_add_co_u32_e32 v184, vcc, s57, v182
	global_load_dwordx4 v[116:119], v[116:117], off
	s_nop 0
	v_addc_co_u32_e32 v185, vcc, 0, v183, vcc
	v_add_co_u32_e32 v186, vcc, s57, v180
	global_load_dwordx4 v[132:135], v[184:185], off offset:3072
	s_nop 0
	v_addc_co_u32_e32 v187, vcc, 0, v181, vcc
	v_add_co_u32_e32 v188, vcc, s61, v180
	s_lshl_b32 s39, s46, 2
	s_nop 0
	v_addc_co_u32_e32 v189, vcc, 0, v181, vcc
	v_add_co_u32_e32 v190, vcc, s70, v180
	global_load_dwordx4 v[144:147], v[186:187], off offset:3072
	global_load_dwordx4 v[136:139], v[188:189], off offset:1024
	v_addc_co_u32_e32 v191, vcc, 0, v181, vcc
	global_load_dwordx4 v[140:143], v[190:191], off offset:3072
	s_add_i32 s39, s39, s7
	s_lshl_b32 s3, s39, 1
	v_add_u32_e32 v178, s3, v196
	v_mad_i64_i32 v[178:179], s[46:47], v178, s71, 0
	v_lshl_add_u64 v[178:179], s[26:27], 0, v[178:179]
	v_mov_b32_dpp v210, v108 row_ror:1 row_mask:0xf bank_mask:0xf
	v_mov_b32_dpp v211, v108 row_ror:2 row_mask:0xf bank_mask:0xf
	v_mov_b32_dpp v213, v109 row_ror:1 row_mask:0xf bank_mask:0xf
	v_mov_b32_dpp v214, v109 row_ror:2 row_mask:0xf bank_mask:0xf
	v_mov_b32_dpp v216, v110 row_ror:1 row_mask:0xf bank_mask:0xf
	v_mov_b32_dpp v215, v110 row_ror:2 row_mask:0xf bank_mask:0xf
	v_mov_b32_dpp v218, v111 row_ror:1 row_mask:0xf bank_mask:0xf
	v_mov_b32_dpp v217, v111 row_ror:2 row_mask:0xf bank_mask:0xf
	v_lshl_add_u64 v[192:193], v[176:177], 2, v[178:179]
	s_and_saveexec_b64 s[46:47], s[10:11]
	s_cbranch_execz .LBB0_492
	global_store_dwordx4 v[192:193], v[108:111], off
.LBB0_492:
	s_or_b64 exec, exec, s[46:47]
	v_mov_b32_dpp v203, v156 row_ror:1 row_mask:0xf bank_mask:0xf
	v_mov_b32_dpp v204, v156 row_ror:2 row_mask:0xf bank_mask:0xf
	v_mov_b32_dpp v205, v157 row_ror:1 row_mask:0xf bank_mask:0xf
	v_mov_b32_dpp v206, v157 row_ror:2 row_mask:0xf bank_mask:0xf
	v_mov_b32_dpp v208, v158 row_ror:1 row_mask:0xf bank_mask:0xf
	v_mov_b32_dpp v207, v158 row_ror:2 row_mask:0xf bank_mask:0xf
	v_mov_b32_dpp v212, v159 row_ror:1 row_mask:0xf bank_mask:0xf
	v_mov_b32_dpp v209, v159 row_ror:2 row_mask:0xf bank_mask:0xf
	s_and_saveexec_b64 s[46:47], s[10:11]
	s_cbranch_execz .LBB0_494
	v_add_co_u32_e32 v220, vcc, 0x2000, v192
	s_nop 1
	v_addc_co_u32_e32 v221, vcc, 0, v193, vcc
	global_store_dwordx4 v[220:221], v[156:159], off offset:3072
.LBB0_494:
	s_or_b64 exec, exec, s[46:47]
	v_cndmask_b32_e64 v227, 0, v209, s[8:9]
	v_cndmask_b32_e64 v226, 0, v207, s[8:9]
	v_cndmask_b32_e64 v221, v212, 0, s[4:5]
	v_cndmask_b32_e64 v220, v208, 0, s[4:5]
	v_cndmask_b32_e64 v225, 0, v206, s[8:9]
	v_cndmask_b32_e64 v224, 0, v204, s[8:9]
	s_waitcnt vmcnt(0)
	v_pk_fma_f32 v[226:227], v[146:147], v[226:227], v[134:135]
	v_cndmask_b32_e64 v223, v205, 0, s[4:5]
	v_cndmask_b32_e64 v222, v203, 0, s[4:5]
	v_pk_fma_f32 v[224:225], v[144:145], v[224:225], v[132:133]
	v_pk_fma_f32 v[220:221], v[138:139], v[220:221], v[226:227]
	v_cndmask_b32_e64 v227, 0, v214, s[8:9]
	v_cndmask_b32_e64 v226, 0, v211, s[8:9]
	v_pk_fma_f32 v[222:223], v[136:137], v[222:223], v[224:225]
	v_cndmask_b32_e64 v225, v213, 0, s[4:5]
	v_cndmask_b32_e64 v224, v210, 0, s[4:5]
	v_pk_fma_f32 v[226:227], v[124:125], v[226:227], v[120:121]
	v_cndmask_b32_e64 v229, 0, v217, s[8:9]
	v_pk_fma_f32 v[224:225], v[112:113], v[224:225], v[226:227]
	v_cndmask_b32_e64 v228, 0, v215, s[8:9]
	v_pk_fma_f32 v[108:109], v[108:109], v[116:117], v[224:225]
	v_pk_fma_f32 v[158:159], v[158:159], v[142:143], v[220:221]
	v_mul_f32_e32 v219, 0xbfb8aa3b, v108
	v_pk_fma_f32 v[220:221], v[156:157], v[140:141], v[222:223]
	v_cndmask_b32_e64 v223, v218, 0, s[4:5]
	v_cndmask_b32_e64 v222, v216, 0, s[4:5]
	v_pk_fma_f32 v[228:229], v[126:127], v[228:229], v[122:123]
	v_exp_f32_e32 v219, v219
	v_pk_fma_f32 v[222:223], v[114:115], v[222:223], v[228:229]
	v_mul_f32_e32 v224, 0xbfb8aa3b, v109
	v_pk_fma_f32 v[222:223], v[110:111], v[118:119], v[222:223]
	v_exp_f32_e32 v224, v224
	v_mul_f32_e32 v110, 0xbfb8aa3b, v222
	v_add_f32_e32 v219, 1.0, v219
	v_exp_f32_e32 v110, v110
	v_mul_f32_e32 v111, 0xbfb8aa3b, v223
	v_rcp_f32_e32 v219, v219
	v_exp_f32_e32 v111, v111
	v_add_f32_e32 v224, 1.0, v224
	v_rcp_f32_e32 v224, v224
	v_add_f32_e32 v110, 1.0, v110
	v_mul_f32_e32 v108, v108, v219
	v_rcp_f32_e32 v219, v110
	v_add_f32_e32 v110, 1.0, v111
	v_rcp_f32_e32 v111, v110
	v_mul_f32_e32 v109, v109, v224
	v_mul_f32_e32 v109, v109, v221
	v_mul_f32_e32 v108, v108, v220
	v_cvt_pk_bf16_f32 v110, v108, v109
	v_mul_f32_e32 v109, v223, v111
	v_mul_f32_e32 v108, v222, v219
	v_mul_f32_e32 v109, v109, v159
	v_mov_b32_dpp v220, v152 row_ror:1 row_mask:0xf bank_mask:0xf
	v_mov_b32_dpp v221, v152 row_ror:2 row_mask:0xf bank_mask:0xf
	v_mov_b32_dpp v223, v153 row_ror:2 row_mask:0xf bank_mask:0xf
	v_mov_b32_dpp v225, v154 row_ror:2 row_mask:0xf bank_mask:0xf
	v_mov_b32_dpp v226, v155 row_ror:1 row_mask:0xf bank_mask:0xf
	v_mov_b32_dpp v227, v155 row_ror:2 row_mask:0xf bank_mask:0xf
	v_mul_f32_e32 v108, v108, v158
	v_cvt_pk_bf16_f32 v111, v108, v109
	v_mov_b32_dpp v222, v153 row_ror:1 row_mask:0xf bank_mask:0xf
	v_mov_b32_dpp v224, v154 row_ror:1 row_mask:0xf bank_mask:0xf
; __device__ __forceinline__ unsigned cvt_pk_bf16(float lo, float hi) { unsigned r; asm volatile("v_cvt_pk_bf16_f32 %0, %1, %2" : "=v"(r) : "v"(lo), "v"(hi)); return r; }
; template <int CTRL> __device__ __forceinline__ float dpp_ror(float v) { return __builtin_bit_cast(float, __builtin_amdgcn_update_dpp(0, __builtin_bit_cast(int, v), CTRL, 0xf, 0xf, false)); }
; __device__ __forceinline__ float silu_f(float g) { return g * __builtin_amdgcn_rcpf(1.f + __builtin_amdgcn_exp2f(-g * LOG2E)); }
;     __device__ __forceinline__ void operator()(const f32x4 (&acc)[2][2][4][2], const pg8::Unit& u, int wr, int wc, int fr, int fq) const {
;     ...
;                 for (int m = 0; m < 4; ++m) {
;                     f32x4 y[2];
; #pragma unroll
;                     for (int bj = 0; bj < 2; ++bj) {
;                         const f32x4 cur = acc[ai][bj][m][n]; f32x4 r1, r2;
; #pragma unroll
;                         for (int j = 0; j < 4; ++j) { r1[j] = dpp_ror<0x121>(cur[j]); r2[j] = dpp_ror<0x122>(cur[j]); }
;                         const f32x4 s1 = (fr >= 1) ? r1 : p1[bj], s2 = (fr >= 2) ? r2 : p2[bj];
;                         y[bj] = bb[bj] + w[bj][0] * s2 + w[bj][1] * s1 + w[bj][2] * cur;
;                         p1[bj] = r1; p2[bj] = r2;
;                         if (m == 0 && fr < 2) *(f32x4*)(hf + (size_t)(wb * 2 + fr) * FFN2 + bj * FFN + f0) = cur;
;                         if (m == 3 && fr >= 14) *(f32x4*)(hl + (size_t)(wb * 2 + fr - 14) * FFN2 + bj * FFN + f0) = cur;
;                     }
;                     u32x2 o; o.x = pg8::cvt_pk_bf16(silu_f(y[0][0]) * y[1][0], silu_f(y[0][1]) * y[1][1]); o.y = pg8::cvt_pk_bf16(silu_f(y[0][2]) * y[1][2], silu_f(y[0][3]) * y[1][3]);
;                     if (n == 0) held[ai][m] = o;
;                     else *(u32x4*)(act + (size_t)(wb * 64 + m * 16 + fr) * FFN + f0 - 4) = (u32x4){held[ai][m].x, held[ai][m].y, o.x, o.y};
	v_cndmask_b32_e64 v109, v226, v218, s[4:5]
	v_cndmask_b32_e64 v158, v220, v210, s[4:5]
	v_cndmask_b32_e64 v219, v214, v223, s[8:9]
	v_cndmask_b32_e64 v218, v211, v221, s[8:9]
	v_cndmask_b32_e64 v211, v217, v227, s[8:9]
	v_cndmask_b32_e64 v210, v215, v225, s[8:9]
	v_cndmask_b32_e64 v108, v224, v216, s[4:5]
	v_cndmask_b32_e64 v159, v222, v213, s[4:5]
	v_pk_fma_f32 v[210:211], v[126:127], v[210:211], v[122:123]
	v_pk_fma_f32 v[214:215], v[124:125], v[218:219], v[120:121]
	v_pk_fma_f32 v[108:109], v[114:115], v[108:109], v[210:211]
	v_pk_fma_f32 v[158:159], v[112:113], v[158:159], v[214:215]
	v_pk_fma_f32 v[154:155], v[154:155], v[118:119], v[108:109]
	v_pk_fma_f32 v[108:109], v[152:153], v[116:117], v[158:159]
	v_mov_b32_dpp v214, v148 row_ror:1 row_mask:0xf bank_mask:0xf
	v_cndmask_b32_e64 v158, v214, v203, s[4:5]
	v_mul_f32_e32 v203, 0xbfb8aa3b, v108
	v_mov_b32_dpp v210, v150 row_ror:1 row_mask:0xf bank_mask:0xf
	v_mov_b32_dpp v218, v150 row_ror:2 row_mask:0xf bank_mask:0xf
	v_mov_b32_dpp v217, v151 row_ror:2 row_mask:0xf bank_mask:0xf
	v_exp_f32_e32 v203, v203
	v_mov_b32_dpp v216, v148 row_ror:2 row_mask:0xf bank_mask:0xf
	v_mov_b32_dpp v213, v149 row_ror:1 row_mask:0xf bank_mask:0xf
	v_mov_b32_dpp v215, v149 row_ror:2 row_mask:0xf bank_mask:0xf
	v_mov_b32_dpp v211, v151 row_ror:1 row_mask:0xf bank_mask:0xf
	v_cndmask_b32_e64 v152, v210, v208, s[4:5]
	v_cndmask_b32_e64 v209, v209, v217, s[8:9]
	v_cndmask_b32_e64 v208, v207, v218, s[8:9]
	v_cndmask_b32_e64 v153, v211, v212, s[4:5]
	v_cndmask_b32_e64 v159, v213, v205, s[4:5]
	v_cndmask_b32_e64 v205, v206, v215, s[8:9]
	v_cndmask_b32_e64 v204, v204, v216, s[8:9]
	v_pk_fma_f32 v[206:207], v[146:147], v[208:209], v[134:135]
	v_pk_fma_f32 v[204:205], v[144:145], v[204:205], v[132:133]
	v_pk_fma_f32 v[152:153], v[138:139], v[152:153], v[206:207]
	v_pk_fma_f32 v[158:159], v[136:137], v[158:159], v[204:205]
	v_mul_f32_e32 v204, 0xbfb8aa3b, v109
	v_pk_fma_f32 v[150:151], v[150:151], v[142:143], v[152:153]
	v_add_f32_e32 v152, 1.0, v203
	v_exp_f32_e32 v204, v204
	v_rcp_f32_e32 v152, v152
	v_pk_fma_f32 v[148:149], v[148:149], v[140:141], v[158:159]
	v_add_f32_e32 v153, 1.0, v204
	v_mul_f32_e32 v108, v108, v152
	v_rcp_f32_e32 v153, v153
	v_mul_f32_e32 v108, v108, v148
	v_mul_f32_e32 v148, 0xbfb8aa3b, v154
	v_mul_f32_e32 v152, 0xbfb8aa3b, v155
	v_exp_f32_e32 v148, v148
	v_exp_f32_e32 v152, v152
	v_mul_f32_e32 v109, v109, v153
	v_mul_f32_e32 v109, v109, v149
	v_add_f32_e32 v148, 1.0, v148
	v_add_f32_e32 v149, 1.0, v152
	v_rcp_f32_e32 v148, v148
	v_rcp_f32_e32 v149, v149
	v_cvt_pk_bf16_f32 v108, v108, v109
	v_mul_f32_e32 v109, v154, v148
	v_mul_f32_e32 v148, v155, v149
	v_mul_f32_e32 v148, v148, v151
	v_mul_f32_e32 v109, v109, v150
	v_mov_b32_dpp v151, v128 row_ror:2 row_mask:0xf bank_mask:0xf
	v_mov_b32_dpp v153, v129 row_ror:2 row_mask:0xf bank_mask:0xf
	v_mov_b32_dpp v158, v130 row_ror:2 row_mask:0xf bank_mask:0xf
	v_mov_b32_dpp v203, v131 row_ror:2 row_mask:0xf bank_mask:0xf
	v_mov_b32_dpp v150, v128 row_ror:1 row_mask:0xf bank_mask:0xf
	v_mov_b32_dpp v152, v129 row_ror:1 row_mask:0xf bank_mask:0xf
	v_mov_b32_dpp v159, v130 row_ror:1 row_mask:0xf bank_mask:0xf
	v_mov_b32_dpp v204, v131 row_ror:1 row_mask:0xf bank_mask:0xf
	v_cndmask_b32_e64 v207, v223, v153, s[8:9]
	v_cndmask_b32_e64 v206, v221, v151, s[8:9]
	v_cndmask_b32_e64 v209, v227, v203, s[8:9]
	v_cndmask_b32_e64 v208, v225, v158, s[8:9]
	v_cvt_pk_bf16_f32 v109, v109, v148
	v_cndmask_b32_e64 v149, v204, v226, s[4:5]
	v_cndmask_b32_e64 v148, v159, v224, s[4:5]
	v_cndmask_b32_e64 v155, v152, v222, s[4:5]
	v_cndmask_b32_e64 v154, v150, v220, s[4:5]
	v_pk_fma_f32 v[208:209], v[126:127], v[208:209], v[122:123]
	v_pk_fma_f32 v[206:207], v[124:125], v[206:207], v[120:121]
	v_pk_fma_f32 v[148:149], v[114:115], v[148:149], v[208:209]
	v_pk_fma_f32 v[154:155], v[112:113], v[154:155], v[206:207]
	v_pk_fma_f32 v[148:149], v[130:131], v[118:119], v[148:149]
	v_pk_fma_f32 v[154:155], v[128:129], v[116:117], v[154:155]
	v_mov_b32_dpp v128, v104 row_ror:1 row_mask:0xf bank_mask:0xf
	v_mov_b32_dpp v129, v104 row_ror:2 row_mask:0xf bank_mask:0xf
	v_mov_b32_dpp v131, v105 row_ror:2 row_mask:0xf bank_mask:0xf
	v_cndmask_b32_e64 v212, v128, v214, s[4:5]
	v_mov_b32_dpp v130, v105 row_ror:1 row_mask:0xf bank_mask:0xf
	v_cndmask_b32_e64 v215, v215, v131, s[8:9]
	v_cndmask_b32_e64 v214, v216, v129, s[8:9]
	v_cndmask_b32_e64 v213, v130, v213, s[4:5]
	v_pk_fma_f32 v[214:215], v[144:145], v[214:215], v[132:133]
	v_mul_f32_e32 v209, 0xbfb8aa3b, v154
	v_pk_fma_f32 v[212:213], v[136:137], v[212:213], v[214:215]
	v_exp_f32_e32 v209, v209
	v_mul_f32_e32 v214, 0xbfb8aa3b, v155
	v_mov_b32_dpp v205, v106 row_ror:2 row_mask:0xf bank_mask:0xf
	v_mov_b32_dpp v207, v107 row_ror:2 row_mask:0xf bank_mask:0xf
	v_exp_f32_e32 v214, v214
	v_mov_b32_dpp v206, v106 row_ror:1 row_mask:0xf bank_mask:0xf
	v_mov_b32_dpp v208, v107 row_ror:1 row_mask:0xf bank_mask:0xf
	v_cndmask_b32_e64 v217, v217, v207, s[8:9]
	v_cndmask_b32_e64 v216, v218, v205, s[8:9]
	v_cndmask_b32_e64 v211, v208, v211, s[4:5]
	v_cndmask_b32_e64 v210, v206, v210, s[4:5]
	v_pk_fma_f32 v[216:217], v[146:147], v[216:217], v[134:135]
	v_add_f32_e32 v209, 1.0, v209
	v_pk_fma_f32 v[210:211], v[138:139], v[210:211], v[216:217]
	v_rcp_f32_e32 v209, v209
	v_pk_fma_f32 v[106:107], v[106:107], v[142:143], v[210:211]
	v_add_f32_e32 v210, 1.0, v214
	v_rcp_f32_e32 v210, v210
	v_pk_fma_f32 v[104:105], v[104:105], v[140:141], v[212:213]
	v_mul_f32_e32 v154, v154, v209
	v_mul_f32_e32 v104, v154, v104
	v_mul_f32_e32 v154, v155, v210
	v_mul_f32_e32 v155, 0xbfb8aa3b, v148
	v_exp_f32_e32 v155, v155
	v_mul_f32_e32 v209, 0xbfb8aa3b, v149
	v_exp_f32_e32 v209, v209
	v_mul_f32_e32 v105, v154, v105
	v_add_f32_e32 v154, 1.0, v155
	v_rcp_f32_e32 v154, v154
	v_add_f32_e32 v155, 1.0, v209
	v_rcp_f32_e32 v155, v155
	v_cvt_pk_bf16_f32 v104, v104, v105
	v_mul_f32_e32 v105, v148, v154
	v_add_u32_e32 v156, s3, v198
	v_mul_f32_e32 v105, v105, v106
	v_mul_f32_e32 v106, v149, v155
	v_mad_i64_i32 v[156:157], s[46:47], v156, s71, 0
	v_mul_f32_e32 v106, v106, v107
	v_cvt_pk_bf16_f32 v105, v105, v106
	v_lshl_add_u64 v[148:149], s[28:29], 0, v[156:157]
	v_mov_b32_dpp v106, v96 row_ror:1 row_mask:0xf bank_mask:0xf
	v_mov_b32_dpp v107, v96 row_ror:2 row_mask:0xf bank_mask:0xf
	v_mov_b32_dpp v209, v97 row_ror:1 row_mask:0xf bank_mask:0xf
	v_mov_b32_dpp v210, v97 row_ror:2 row_mask:0xf bank_mask:0xf
	v_mov_b32_dpp v212, v98 row_ror:1 row_mask:0xf bank_mask:0xf
	v_mov_b32_dpp v211, v98 row_ror:2 row_mask:0xf bank_mask:0xf
	v_mov_b32_dpp v214, v99 row_ror:1 row_mask:0xf bank_mask:0xf
	v_mov_b32_dpp v213, v99 row_ror:2 row_mask:0xf bank_mask:0xf
	v_lshl_add_u64 v[154:155], v[176:177], 2, v[148:149]
	s_and_saveexec_b64 s[46:47], s[12:13]
	s_cbranch_execz .LBB0_496
	global_store_dwordx4 v[154:155], v[96:99], off
; __device__ __forceinline__ unsigned cvt_pk_bf16(float lo, float hi) { unsigned r; asm volatile("v_cvt_pk_bf16_f32 %0, %1, %2" : "=v"(r) : "v"(lo), "v"(hi)); return r; }
; template <int CTRL> __device__ __forceinline__ float dpp_ror(float v) { return __builtin_bit_cast(float, __builtin_amdgcn_update_dpp(0, __builtin_bit_cast(int, v), CTRL, 0xf, 0xf, false)); }
; __device__ __forceinline__ float silu_f(float g) { return g * __builtin_amdgcn_rcpf(1.f + __builtin_amdgcn_exp2f(-g * LOG2E)); }
;     __device__ __forceinline__ void operator()(const f32x4 (&acc)[2][2][4][2], const pg8::Unit& u, int wr, int wc, int fr, int fq) const {
;     ...
;                 for (int m = 0; m < 4; ++m) {
;                     f32x4 y[2];
; #pragma unroll
;                     for (int bj = 0; bj < 2; ++bj) {
;                         const f32x4 cur = acc[ai][bj][m][n]; f32x4 r1, r2;
; #pragma unroll
;                         for (int j = 0; j < 4; ++j) { r1[j] = dpp_ror<0x121>(cur[j]); r2[j] = dpp_ror<0x122>(cur[j]); }
;                         const f32x4 s1 = (fr >= 1) ? r1 : p1[bj], s2 = (fr >= 2) ? r2 : p2[bj];
;                         y[bj] = bb[bj] + w[bj][0] * s2 + w[bj][1] * s1 + w[bj][2] * cur;
;                         p1[bj] = r1; p2[bj] = r2;
;                         if (m == 0 && fr < 2) *(f32x4*)(hf + (size_t)(wb * 2 + fr) * FFN2 + bj * FFN + f0) = cur;
;                         if (m == 3 && fr >= 14) *(f32x4*)(hl + (size_t)(wb * 2 + fr - 14) * FFN2 + bj * FFN + f0) = cur;
;                     }
;                     u32x2 o; o.x = pg8::cvt_pk_bf16(silu_f(y[0][0]) * y[1][0], silu_f(y[0][1]) * y[1][1]); o.y = pg8::cvt_pk_bf16(silu_f(y[0][2]) * y[1][2], silu_f(y[0][3]) * y[1][3]);
;                     if (n == 0) held[ai][m] = o;
;                     else *(u32x4*)(act + (size_t)(wb * 64 + m * 16 + fr) * FFN + f0 - 4) = (u32x4){held[ai][m].x, held[ai][m].y, o.x, o.y};
.LBB0_496:
	s_or_b64 exec, exec, s[46:47]
	v_mov_b32_dpp v156, v100 row_ror:1 row_mask:0xf bank_mask:0xf
	v_mov_b32_dpp v157, v100 row_ror:2 row_mask:0xf bank_mask:0xf
	v_mov_b32_dpp v215, v101 row_ror:1 row_mask:0xf bank_mask:0xf
	v_mov_b32_dpp v216, v101 row_ror:2 row_mask:0xf bank_mask:0xf
	v_mov_b32_dpp v218, v102 row_ror:1 row_mask:0xf bank_mask:0xf
	v_mov_b32_dpp v217, v102 row_ror:2 row_mask:0xf bank_mask:0xf
	v_mov_b32_dpp v220, v103 row_ror:1 row_mask:0xf bank_mask:0xf
	v_mov_b32_dpp v219, v103 row_ror:2 row_mask:0xf bank_mask:0xf
	s_and_saveexec_b64 s[46:47], s[12:13]
	s_cbranch_execz .LBB0_498
	v_add_co_u32_e32 v222, vcc, 0x2000, v154
	s_nop 1
	v_addc_co_u32_e32 v223, vcc, 0, v155, vcc
	global_store_dwordx4 v[222:223], v[100:103], off offset:3072
.LBB0_498:
	s_or_b64 exec, exec, s[46:47]
	v_cndmask_b32_e64 v223, v215, v130, s[4:5]
	v_cndmask_b32_e64 v131, v131, v216, s[8:9]
	v_cndmask_b32_e64 v130, v129, v157, s[8:9]
	v_cndmask_b32_e64 v222, v156, v128, s[4:5]
	v_pk_fma_f32 v[130:131], v[144:145], v[130:131], v[132:133]
	v_cndmask_b32_e64 v153, v153, v210, s[8:9]
	v_pk_fma_f32 v[130:131], v[136:137], v[222:223], v[130:131]
	v_cndmask_b32_e64 v129, v207, v219, s[8:9]
	v_pk_fma_f32 v[100:101], v[100:101], v[140:141], v[130:131]
	v_cndmask_b32_e64 v131, v209, v152, s[4:5]
	v_cndmask_b32_e64 v152, v151, v107, s[8:9]
	v_cndmask_b32_e64 v130, v106, v150, s[4:5]
	v_pk_fma_f32 v[150:151], v[124:125], v[152:153], v[120:121]
	v_cndmask_b32_e64 v128, v205, v217, s[8:9]
	v_pk_fma_f32 v[130:131], v[112:113], v[130:131], v[150:151]
	v_cndmask_b32_e64 v221, v220, v208, s[4:5]
	v_pk_fma_f32 v[96:97], v[96:97], v[116:117], v[130:131]
	v_cndmask_b32_e64 v220, v218, v206, s[4:5]
	v_mul_f32_e32 v130, 0xbfb8aa3b, v96
	v_exp_f32_e32 v130, v130
	v_pk_fma_f32 v[128:129], v[146:147], v[128:129], v[134:135]
	v_cndmask_b32_e64 v107, v203, v213, s[8:9]
	v_pk_fma_f32 v[128:129], v[138:139], v[220:221], v[128:129]
	v_cndmask_b32_e64 v106, v158, v211, s[8:9]
	v_pk_fma_f32 v[102:103], v[102:103], v[142:143], v[128:129]
	v_cndmask_b32_e64 v129, v214, v204, s[4:5]
	v_cndmask_b32_e64 v128, v212, v159, s[4:5]
	v_pk_fma_f32 v[106:107], v[126:127], v[106:107], v[122:123]
	v_mul_f32_e32 v131, 0xbfb8aa3b, v97
	v_pk_fma_f32 v[106:107], v[114:115], v[128:129], v[106:107]
	v_add_f32_e32 v128, 1.0, v130
	v_exp_f32_e32 v131, v131
	v_rcp_f32_e32 v128, v128
	v_pk_fma_f32 v[98:99], v[98:99], v[118:119], v[106:107]
	s_add_i32 s37, s39, 2
	v_add_f32_e32 v129, 1.0, v131
	v_mul_f32_e32 v96, v96, v128
	v_rcp_f32_e32 v129, v129
	v_mul_f32_e32 v96, v96, v100
	v_mul_f32_e32 v100, 0xbfb8aa3b, v98
	v_mul_f32_e32 v106, 0xbfb8aa3b, v99
	v_exp_f32_e32 v100, v100
	v_exp_f32_e32 v106, v106
	v_mul_f32_e32 v97, v97, v129
	v_mul_f32_e32 v97, v97, v101
	v_add_f32_e32 v100, 1.0, v100
	v_add_f32_e32 v101, 1.0, v106
	v_rcp_f32_e32 v100, v100
	v_rcp_f32_e32 v101, v101
	v_cvt_pk_bf16_f32 v96, v96, v97
	s_lshl_b32 s3, s37, 1
	v_mul_f32_e32 v97, v98, v100
	v_mul_f32_e32 v98, v99, v101
	v_mul_f32_e32 v97, v97, v102
	v_mul_f32_e32 v98, v98, v103
	v_cvt_pk_bf16_f32 v97, v97, v98
	v_add_u32_e32 v98, s3, v196
	v_mad_i64_i32 v[98:99], s[46:47], v98, s71, 0
	v_lshl_add_u64 v[130:131], s[26:27], 0, v[98:99]
	v_mov_b32_dpp v107, v88 row_ror:1 row_mask:0xf bank_mask:0xf
	v_mov_b32_dpp v128, v88 row_ror:2 row_mask:0xf bank_mask:0xf
	v_mov_b32_dpp v150, v89 row_ror:1 row_mask:0xf bank_mask:0xf
	v_mov_b32_dpp v151, v89 row_ror:2 row_mask:0xf bank_mask:0xf
	v_mov_b32_dpp v157, v90 row_ror:1 row_mask:0xf bank_mask:0xf
	v_mov_b32_dpp v156, v90 row_ror:2 row_mask:0xf bank_mask:0xf
	v_mov_b32_dpp v159, v91 row_ror:1 row_mask:0xf bank_mask:0xf
	v_mov_b32_dpp v158, v91 row_ror:2 row_mask:0xf bank_mask:0xf
	v_lshl_add_u64 v[152:153], v[176:177], 2, v[130:131]
	s_and_saveexec_b64 s[46:47], s[10:11]
	s_cbranch_execz .LBB0_500
	global_store_dwordx4 v[152:153], v[88:91], off
.LBB0_500:
	s_or_b64 exec, exec, s[46:47]
	v_mov_b32_dpp v98, v92 row_ror:1 row_mask:0xf bank_mask:0xf
	v_mov_b32_dpp v99, v92 row_ror:2 row_mask:0xf bank_mask:0xf
	v_mov_b32_dpp v100, v93 row_ror:1 row_mask:0xf bank_mask:0xf
	v_mov_b32_dpp v101, v93 row_ror:2 row_mask:0xf bank_mask:0xf
	v_mov_b32_dpp v103, v94 row_ror:1 row_mask:0xf bank_mask:0xf
	v_mov_b32_dpp v102, v94 row_ror:2 row_mask:0xf bank_mask:0xf
	v_mov_b32_dpp v129, v95 row_ror:1 row_mask:0xf bank_mask:0xf
	v_mov_b32_dpp v106, v95 row_ror:2 row_mask:0xf bank_mask:0xf
	s_and_saveexec_b64 s[46:47], s[10:11]
	s_cbranch_execz .LBB0_502
	v_add_co_u32_e32 v204, vcc, 0x2000, v152
	s_nop 1
	v_addc_co_u32_e32 v205, vcc, 0, v153, vcc
	global_store_dwordx4 v[204:205], v[92:95], off offset:3072
; __device__ __forceinline__ unsigned cvt_pk_bf16(float lo, float hi) { unsigned r; asm volatile("v_cvt_pk_bf16_f32 %0, %1, %2" : "=v"(r) : "v"(lo), "v"(hi)); return r; }
; template <int CTRL> __device__ __forceinline__ float dpp_ror(float v) { return __builtin_bit_cast(float, __builtin_amdgcn_update_dpp(0, __builtin_bit_cast(int, v), CTRL, 0xf, 0xf, false)); }
; __device__ __forceinline__ float silu_f(float g) { return g * __builtin_amdgcn_rcpf(1.f + __builtin_amdgcn_exp2f(-g * LOG2E)); }
;     __device__ __forceinline__ void operator()(const f32x4 (&acc)[2][2][4][2], const pg8::Unit& u, int wr, int wc, int fr, int fq) const {
;     ...
;                 for (int m = 0; m < 4; ++m) {
;                     f32x4 y[2];
; #pragma unroll
;                     for (int bj = 0; bj < 2; ++bj) {
;                         const f32x4 cur = acc[ai][bj][m][n]; f32x4 r1, r2;
; #pragma unroll
;                         for (int j = 0; j < 4; ++j) { r1[j] = dpp_ror<0x121>(cur[j]); r2[j] = dpp_ror<0x122>(cur[j]); }
;                         const f32x4 s1 = (fr >= 1) ? r1 : p1[bj], s2 = (fr >= 2) ? r2 : p2[bj];
;                         y[bj] = bb[bj] + w[bj][0] * s2 + w[bj][1] * s1 + w[bj][2] * cur;
;                         p1[bj] = r1; p2[bj] = r2;
;                         if (m == 0 && fr < 2) *(f32x4*)(hf + (size_t)(wb * 2 + fr) * FFN2 + bj * FFN + f0) = cur;
;                         if (m == 3 && fr >= 14) *(f32x4*)(hl + (size_t)(wb * 2 + fr - 14) * FFN2 + bj * FFN + f0) = cur;
;                     }
;                     u32x2 o; o.x = pg8::cvt_pk_bf16(silu_f(y[0][0]) * y[1][0], silu_f(y[0][1]) * y[1][1]); o.y = pg8::cvt_pk_bf16(silu_f(y[0][2]) * y[1][2], silu_f(y[0][3]) * y[1][3]);
;                     if (n == 0) held[ai][m] = o;
;                     else *(u32x4*)(act + (size_t)(wb * 64 + m * 16 + fr) * FFN + f0 - 4) = (u32x4){held[ai][m].x, held[ai][m].y, o.x, o.y};
.LBB0_502:
	s_or_b64 exec, exec, s[46:47]
	v_cndmask_b32_e64 v211, 0, v106, s[8:9]
	v_cndmask_b32_e64 v210, 0, v102, s[8:9]
	v_cndmask_b32_e64 v205, v129, 0, s[4:5]
	v_cndmask_b32_e64 v204, v103, 0, s[4:5]
	v_cndmask_b32_e64 v209, 0, v101, s[8:9]
	v_cndmask_b32_e64 v208, 0, v99, s[8:9]
	v_pk_fma_f32 v[210:211], v[146:147], v[210:211], v[134:135]
	v_cndmask_b32_e64 v207, v100, 0, s[4:5]
	v_cndmask_b32_e64 v206, v98, 0, s[4:5]
	v_pk_fma_f32 v[208:209], v[144:145], v[208:209], v[132:133]
	v_pk_fma_f32 v[204:205], v[138:139], v[204:205], v[210:211]
	v_cndmask_b32_e64 v211, 0, v151, s[8:9]
	v_cndmask_b32_e64 v210, 0, v128, s[8:9]
	v_pk_fma_f32 v[206:207], v[136:137], v[206:207], v[208:209]
	v_cndmask_b32_e64 v209, v150, 0, s[4:5]
	v_cndmask_b32_e64 v208, v107, 0, s[4:5]
	v_pk_fma_f32 v[210:211], v[124:125], v[210:211], v[120:121]
	v_cndmask_b32_e64 v213, 0, v158, s[8:9]
	v_pk_fma_f32 v[208:209], v[112:113], v[208:209], v[210:211]
	v_cndmask_b32_e64 v212, 0, v156, s[8:9]
	v_pk_fma_f32 v[88:89], v[88:89], v[116:117], v[208:209]
	v_pk_fma_f32 v[94:95], v[94:95], v[142:143], v[204:205]
	v_mul_f32_e32 v203, 0xbfb8aa3b, v88
	v_exp_f32_e32 v203, v203
	v_pk_fma_f32 v[204:205], v[92:93], v[140:141], v[206:207]
	v_cndmask_b32_e64 v207, v159, 0, s[4:5]
	v_cndmask_b32_e64 v206, v157, 0, s[4:5]
	v_add_f32_e32 v203, 1.0, v203
	v_rcp_f32_e32 v203, v203
	v_pk_fma_f32 v[212:213], v[126:127], v[212:213], v[122:123]
	v_mul_f32_e32 v208, 0xbfb8aa3b, v89
	v_pk_fma_f32 v[206:207], v[114:115], v[206:207], v[212:213]
	v_exp_f32_e32 v208, v208
	v_pk_fma_f32 v[90:91], v[90:91], v[118:119], v[206:207]
	v_mul_f32_e32 v88, v88, v203
	v_mul_f32_e32 v88, v88, v204
	v_mul_f32_e32 v203, 0xbfb8aa3b, v90
	v_mul_f32_e32 v204, 0xbfb8aa3b, v91
	v_exp_f32_e32 v203, v203
	v_exp_f32_e32 v204, v204
	v_add_f32_e32 v208, 1.0, v208
	v_rcp_f32_e32 v208, v208
	v_add_f32_e32 v203, 1.0, v203
	v_add_f32_e32 v204, 1.0, v204
	v_rcp_f32_e32 v203, v203
	v_rcp_f32_e32 v204, v204
	v_mul_f32_e32 v89, v89, v208
	v_mul_f32_e32 v89, v89, v205
	v_cvt_pk_bf16_f32 v88, v88, v89
	v_mul_f32_e32 v89, v90, v203
	v_mul_f32_e32 v90, v91, v204
	v_mov_b32_dpp v204, v84 row_ror:2 row_mask:0xf bank_mask:0xf
	v_mov_b32_dpp v205, v85 row_ror:1 row_mask:0xf bank_mask:0xf
	v_mov_b32_dpp v206, v85 row_ror:2 row_mask:0xf bank_mask:0xf
	v_mul_f32_e32 v89, v89, v94
	v_mul_f32_e32 v90, v90, v95
	v_mov_b32_dpp v203, v84 row_ror:1 row_mask:0xf bank_mask:0xf
	v_mov_b32_dpp v207, v86 row_ror:1 row_mask:0xf bank_mask:0xf
	v_mov_b32_dpp v208, v86 row_ror:2 row_mask:0xf bank_mask:0xf
	v_mov_b32_dpp v210, v87 row_ror:2 row_mask:0xf bank_mask:0xf
	v_cndmask_b32_e64 v95, v205, v150, s[4:5]
	v_cndmask_b32_e64 v151, v151, v206, s[8:9]
	v_cndmask_b32_e64 v150, v128, v204, s[8:9]
	v_cvt_pk_bf16_f32 v89, v89, v90
	v_mov_b32_dpp v209, v87 row_ror:1 row_mask:0xf bank_mask:0xf
	v_cndmask_b32_e64 v90, v207, v157, s[4:5]
	v_cndmask_b32_e64 v94, v203, v107, s[4:5]
	v_cndmask_b32_e64 v157, v158, v210, s[8:9]
	v_cndmask_b32_e64 v156, v156, v208, s[8:9]
	v_pk_fma_f32 v[150:151], v[124:125], v[150:151], v[120:121]
	v_cndmask_b32_e64 v91, v209, v159, s[4:5]
	v_pk_fma_f32 v[156:157], v[126:127], v[156:157], v[122:123]
	v_pk_fma_f32 v[94:95], v[112:113], v[94:95], v[150:151]
	v_pk_fma_f32 v[90:91], v[114:115], v[90:91], v[156:157]
	v_mov_b32_dpp v128, v80 row_ror:1 row_mask:0xf bank_mask:0xf
	v_mov_b32_dpp v150, v80 row_ror:2 row_mask:0xf bank_mask:0xf
	v_mov_b32_dpp v151, v81 row_ror:1 row_mask:0xf bank_mask:0xf
	v_mov_b32_dpp v158, v82 row_ror:2 row_mask:0xf bank_mask:0xf
	v_mov_b32_dpp v159, v83 row_ror:2 row_mask:0xf bank_mask:0xf
	v_pk_fma_f32 v[84:85], v[84:85], v[116:117], v[94:95]
	v_mov_b32_dpp v157, v82 row_ror:1 row_mask:0xf bank_mask:0xf
	v_mov_b32_dpp v107, v83 row_ror:1 row_mask:0xf bank_mask:0xf
	v_cndmask_b32_e64 v95, v151, v100, s[4:5]
	v_cndmask_b32_e64 v94, v128, v98, s[4:5]
	v_cndmask_b32_e64 v100, v99, v150, s[8:9]
	v_cndmask_b32_e64 v99, v106, v159, s[8:9]
	v_cndmask_b32_e64 v98, v102, v158, s[8:9]
	v_pk_fma_f32 v[86:87], v[86:87], v[118:119], v[90:91]
	v_cndmask_b32_e64 v91, v107, v129, s[4:5]
	v_cndmask_b32_e64 v90, v157, v103, s[4:5]
	v_pk_fma_f32 v[98:99], v[146:147], v[98:99], v[134:135]
	v_pk_fma_f32 v[90:91], v[138:139], v[90:91], v[98:99]
	v_mul_f32_e32 v98, 0xbfb8aa3b, v84
	v_exp_f32_e32 v98, v98
	v_mul_f32_e32 v99, 0xbfb8aa3b, v85
	v_exp_f32_e32 v99, v99
	v_pk_fma_f32 v[82:83], v[82:83], v[142:143], v[90:91]
	v_add_f32_e32 v90, 1.0, v98
	v_mov_b32_dpp v156, v81 row_ror:2 row_mask:0xf bank_mask:0xf
	v_rcp_f32_e32 v90, v90
	v_add_f32_e32 v91, 1.0, v99
	v_cndmask_b32_e64 v101, v101, v156, s[8:9]
	v_rcp_f32_e32 v91, v91
	v_pk_fma_f32 v[100:101], v[144:145], v[100:101], v[132:133]
	v_mul_f32_e32 v84, v84, v90
	v_pk_fma_f32 v[94:95], v[136:137], v[94:95], v[100:101]
	v_mul_f32_e32 v90, 0xbfb8aa3b, v87
	v_pk_fma_f32 v[80:81], v[80:81], v[140:141], v[94:95]
	v_exp_f32_e32 v90, v90
	v_mul_f32_e32 v80, v84, v80
	v_mul_f32_e32 v84, v85, v91
	v_mul_f32_e32 v85, 0xbfb8aa3b, v86
	v_exp_f32_e32 v85, v85
	v_mul_f32_e32 v81, v84, v81
	v_cvt_pk_bf16_f32 v80, v80, v81
	v_add_f32_e32 v84, 1.0, v85
	v_rcp_f32_e32 v84, v84
	v_add_f32_e32 v85, 1.0, v90
	v_rcp_f32_e32 v85, v85
	v_mul_f32_e32 v81, v86, v84
	v_mul_f32_e32 v81, v81, v82
	v_mul_f32_e32 v82, v87, v85
	v_mul_f32_e32 v82, v82, v83
	v_cvt_pk_bf16_f32 v81, v81, v82
	v_mov_b32_dpp v83, v76 row_ror:2 row_mask:0xf bank_mask:0xf
	v_mov_b32_dpp v85, v77 row_ror:2 row_mask:0xf bank_mask:0xf
	v_mov_b32_dpp v86, v78 row_ror:2 row_mask:0xf bank_mask:0xf
	v_mov_b32_dpp v90, v79 row_ror:2 row_mask:0xf bank_mask:0xf
	v_mov_b32_dpp v82, v76 row_ror:1 row_mask:0xf bank_mask:0xf
; __device__ __forceinline__ unsigned cvt_pk_bf16(float lo, float hi) { unsigned r; asm volatile("v_cvt_pk_bf16_f32 %0, %1, %2" : "=v"(r) : "v"(lo), "v"(hi)); return r; }
; template <int CTRL> __device__ __forceinline__ float dpp_ror(float v) { return __builtin_bit_cast(float, __builtin_amdgcn_update_dpp(0, __builtin_bit_cast(int, v), CTRL, 0xf, 0xf, false)); }
; __device__ __forceinline__ float silu_f(float g) { return g * __builtin_amdgcn_rcpf(1.f + __builtin_amdgcn_exp2f(-g * LOG2E)); }
;     __device__ __forceinline__ void operator()(const f32x4 (&acc)[2][2][4][2], const pg8::Unit& u, int wr, int wc, int fr, int fq) const {
;     ...
;                 for (int m = 0; m < 4; ++m) {
;                     f32x4 y[2];
; #pragma unroll
;                     for (int bj = 0; bj < 2; ++bj) {
;                         const f32x4 cur = acc[ai][bj][m][n]; f32x4 r1, r2;
; #pragma unroll
;                         for (int j = 0; j < 4; ++j) { r1[j] = dpp_ror<0x121>(cur[j]); r2[j] = dpp_ror<0x122>(cur[j]); }
;                         const f32x4 s1 = (fr >= 1) ? r1 : p1[bj], s2 = (fr >= 2) ? r2 : p2[bj];
;                         y[bj] = bb[bj] + w[bj][0] * s2 + w[bj][1] * s1 + w[bj][2] * cur;
;                         p1[bj] = r1; p2[bj] = r2;
;                         if (m == 0 && fr < 2) *(f32x4*)(hf + (size_t)(wb * 2 + fr) * FFN2 + bj * FFN + f0) = cur;
;                         if (m == 3 && fr >= 14) *(f32x4*)(hl + (size_t)(wb * 2 + fr - 14) * FFN2 + bj * FFN + f0) = cur;
;                     }
;                     u32x2 o; o.x = pg8::cvt_pk_bf16(silu_f(y[0][0]) * y[1][0], silu_f(y[0][1]) * y[1][1]); o.y = pg8::cvt_pk_bf16(silu_f(y[0][2]) * y[1][2], silu_f(y[0][3]) * y[1][3]);
;                     if (n == 0) held[ai][m] = o;
;                     else *(u32x4*)(act + (size_t)(wb * 64 + m * 16 + fr) * FFN + f0 - 4) = (u32x4){held[ai][m].x, held[ai][m].y, o.x, o.y};
	v_mov_b32_dpp v84, v77 row_ror:1 row_mask:0xf bank_mask:0xf
	v_mov_b32_dpp v87, v78 row_ror:1 row_mask:0xf bank_mask:0xf
	v_mov_b32_dpp v91, v79 row_ror:1 row_mask:0xf bank_mask:0xf
	v_cndmask_b32_e64 v101, v206, v85, s[8:9]
	v_cndmask_b32_e64 v100, v204, v83, s[8:9]
	v_cndmask_b32_e64 v103, v210, v90, s[8:9]
	v_cndmask_b32_e64 v102, v208, v86, s[8:9]
	v_cndmask_b32_e64 v95, v91, v209, s[4:5]
	v_cndmask_b32_e64 v94, v87, v207, s[4:5]
	v_cndmask_b32_e64 v99, v84, v205, s[4:5]
	v_cndmask_b32_e64 v98, v82, v203, s[4:5]
	v_pk_fma_f32 v[102:103], v[126:127], v[102:103], v[122:123]
	v_pk_fma_f32 v[100:101], v[124:125], v[100:101], v[120:121]
	v_pk_fma_f32 v[94:95], v[114:115], v[94:95], v[102:103]
	v_pk_fma_f32 v[98:99], v[112:113], v[98:99], v[100:101]
	v_pk_fma_f32 v[100:101], v[78:79], v[118:119], v[94:95]
	v_pk_fma_f32 v[102:103], v[76:77], v[116:117], v[98:99]
	v_mov_b32_dpp v77, v72 row_ror:2 row_mask:0xf bank_mask:0xf
	v_mov_b32_dpp v78, v73 row_ror:1 row_mask:0xf bank_mask:0xf
	v_mov_b32_dpp v79, v73 row_ror:2 row_mask:0xf bank_mask:0xf
	v_mov_b32_dpp v76, v72 row_ror:1 row_mask:0xf bank_mask:0xf
	v_cndmask_b32_e64 v129, v78, v151, s[4:5]
	v_cndmask_b32_e64 v151, v156, v79, s[8:9]
	v_cndmask_b32_e64 v150, v150, v77, s[8:9]
	v_cndmask_b32_e64 v128, v76, v128, s[4:5]
	v_pk_fma_f32 v[150:151], v[144:145], v[150:151], v[132:133]
	v_pk_fma_f32 v[128:129], v[136:137], v[128:129], v[150:151]
	v_mul_f32_e32 v150, 0xbfb8aa3b, v102
	v_mov_b32_dpp v95, v74 row_ror:1 row_mask:0xf bank_mask:0xf
	v_mov_b32_dpp v94, v74 row_ror:2 row_mask:0xf bank_mask:0xf
	v_mov_b32_dpp v98, v75 row_ror:2 row_mask:0xf bank_mask:0xf
	v_exp_f32_e32 v150, v150
	v_mul_f32_e32 v151, 0xbfb8aa3b, v103
	v_mov_b32_dpp v99, v75 row_ror:1 row_mask:0xf bank_mask:0xf
	v_cndmask_b32_e64 v106, v95, v157, s[4:5]
	v_cndmask_b32_e64 v157, v159, v98, s[8:9]
	v_cndmask_b32_e64 v156, v158, v94, s[8:9]
	v_exp_f32_e32 v151, v151
	v_cndmask_b32_e64 v107, v99, v107, s[4:5]
	v_pk_fma_f32 v[156:157], v[146:147], v[156:157], v[134:135]
	v_pk_fma_f32 v[72:73], v[72:73], v[140:141], v[128:129]
	v_pk_fma_f32 v[106:107], v[138:139], v[106:107], v[156:157]
	v_add_u32_e32 v92, s3, v198
	v_pk_fma_f32 v[74:75], v[74:75], v[142:143], v[106:107]
	v_add_f32_e32 v106, 1.0, v150
	v_rcp_f32_e32 v106, v106
	v_add_f32_e32 v107, 1.0, v151
	v_rcp_f32_e32 v107, v107
	v_mad_i64_i32 v[92:93], s[46:47], v92, s71, 0
	v_mul_f32_e32 v102, v102, v106
	v_mul_f32_e32 v72, v102, v72
	v_mul_f32_e32 v102, v103, v107
	v_mul_f32_e32 v103, 0xbfb8aa3b, v100
	v_exp_f32_e32 v103, v103
	v_mul_f32_e32 v106, 0xbfb8aa3b, v101
	v_exp_f32_e32 v106, v106
	v_mul_f32_e32 v73, v102, v73
	v_add_f32_e32 v102, 1.0, v103
	v_rcp_f32_e32 v102, v102
	v_add_f32_e32 v103, 1.0, v106
	v_rcp_f32_e32 v103, v103
	v_cvt_pk_bf16_f32 v72, v72, v73
	v_mul_f32_e32 v73, v100, v102
	v_mul_f32_e32 v73, v73, v74
	v_mul_f32_e32 v74, v101, v103
	v_mul_f32_e32 v74, v74, v75
	v_cvt_pk_bf16_f32 v73, v73, v74
	v_lshl_add_u64 v[128:129], s[28:29], 0, v[92:93]
	v_mov_b32_dpp v74, v64 row_ror:1 row_mask:0xf bank_mask:0xf
	v_mov_b32_dpp v75, v64 row_ror:2 row_mask:0xf bank_mask:0xf
	v_mov_b32_dpp v100, v65 row_ror:1 row_mask:0xf bank_mask:0xf
	v_mov_b32_dpp v101, v65 row_ror:2 row_mask:0xf bank_mask:0xf
	v_mov_b32_dpp v103, v66 row_ror:1 row_mask:0xf bank_mask:0xf
	v_mov_b32_dpp v102, v66 row_ror:2 row_mask:0xf bank_mask:0xf
	v_mov_b32_dpp v107, v67 row_ror:1 row_mask:0xf bank_mask:0xf
	v_mov_b32_dpp v106, v67 row_ror:2 row_mask:0xf bank_mask:0xf
	v_lshl_add_u64 v[150:151], v[176:177], 2, v[128:129]
	s_and_saveexec_b64 s[46:47], s[12:13]
	s_cbranch_execz .LBB0_504
	global_store_dwordx4 v[150:151], v[64:67], off
.LBB0_504:
	s_or_b64 exec, exec, s[46:47]
	v_mov_b32_dpp v92, v68 row_ror:1 row_mask:0xf bank_mask:0xf
	v_mov_b32_dpp v93, v68 row_ror:2 row_mask:0xf bank_mask:0xf
	v_mov_b32_dpp v156, v69 row_ror:1 row_mask:0xf bank_mask:0xf
	v_mov_b32_dpp v157, v69 row_ror:2 row_mask:0xf bank_mask:0xf
	v_mov_b32_dpp v159, v70 row_ror:1 row_mask:0xf bank_mask:0xf
	v_mov_b32_dpp v158, v70 row_ror:2 row_mask:0xf bank_mask:0xf
	v_mov_b32_dpp v204, v71 row_ror:1 row_mask:0xf bank_mask:0xf
	v_mov_b32_dpp v203, v71 row_ror:2 row_mask:0xf bank_mask:0xf
	s_and_saveexec_b64 s[46:47], s[12:13]
	s_cbranch_execz .LBB0_506
	v_add_co_u32_e32 v206, vcc, 0x2000, v150
	s_nop 1
	v_addc_co_u32_e32 v207, vcc, 0, v151, vcc
	global_store_dwordx4 v[206:207], v[68:71], off offset:3072
; __device__ __forceinline__ unsigned cvt_pk_bf16(float lo, float hi) { unsigned r; asm volatile("v_cvt_pk_bf16_f32 %0, %1, %2" : "=v"(r) : "v"(lo), "v"(hi)); return r; }
; __device__ __forceinline__ float silu_f(float g) { return g * __builtin_amdgcn_rcpf(1.f + __builtin_amdgcn_exp2f(-g * LOG2E)); }
;     __device__ __forceinline__ void operator()(const f32x4 (&acc)[2][2][4][2], const pg8::Unit& u, int wr, int wc, int fr, int fq) const {
;     ...
;         for (int n = 0; n < 2; ++n) {
;             const int f0 = u.pn * 128 + wc * 32 + 8 * fq + 4 * n;
;             f32x4 w[2][3], bb[2];
; #pragma unroll
;             for (int bj = 0; bj < 2; ++bj) { const int col = bj * FFN + f0; bb[bj] = *(const f32x4*)(cb + col);
; #pragma unroll
;                 for (int tp = 0; tp < 3; ++tp) w[bj][tp] = *(const f32x4*)(cw + tp * FFN2 + col); }
; #pragma unroll
;             for (int ai = 0; ai < 2; ++ai) {
;                 const int wb = (u.pm * 2 + ai) * 2 + wr;
;                 f32x4 p1[2], p2[2];
;                 p1[0] = p1[1] = p2[0] = p2[1] = (f32x4){0.f, 0.f, 0.f, 0.f};
; #pragma unroll
;                 for (int m = 0; m < 4; ++m) {
;                     f32x4 y[2];
; #pragma unroll
;                     for (int bj = 0; bj < 2; ++bj) {
;                         const f32x4 cur = acc[ai][bj][m][n]; f32x4 r1, r2;
; #pragma unroll
;                         for (int j = 0; j < 4; ++j) { r1[j] = dpp_ror<0x121>(cur[j]); r2[j] = dpp_ror<0x122>(cur[j]); }
;                         const f32x4 s1 = (fr >= 1) ? r1 : p1[bj], s2 = (fr >= 2) ? r2 : p2[bj];
;                         y[bj] = bb[bj] + w[bj][0] * s2 + w[bj][1] * s1 + w[bj][2] * cur;
;                         p1[bj] = r1; p2[bj] = r2;
;                         if (m == 0 && fr < 2) *(f32x4*)(hf + (size_t)(wb * 2 + fr) * FFN2 + bj * FFN + f0) = cur;
;                         if (m == 3 && fr >= 14) *(f32x4*)(hl + (size_t)(wb * 2 + fr - 14) * FFN2 + bj * FFN + f0) = cur;
;                     }
;                     u32x2 o; o.x = pg8::cvt_pk_bf16(silu_f(y[0][0]) * y[1][0], silu_f(y[0][1]) * y[1][1]); o.y = pg8::cvt_pk_bf16(silu_f(y[0][2]) * y[1][2], silu_f(y[0][3]) * y[1][3]);
;                     if (n == 0) held[ai][m] = o;
;                     else *(u32x4*)(act + (size_t)(wb * 64 + m * 16 + fr) * FFN + f0 - 4) = (u32x4){held[ai][m].x, held[ai][m].y, o.x, o.y};
.LBB0_506:
	s_or_b64 exec, exec, s[46:47]
	v_cndmask_b32_e64 v207, v156, v78, s[4:5]
	v_cndmask_b32_e64 v79, v79, v157, s[8:9]
	v_cndmask_b32_e64 v78, v77, v93, s[8:9]
	v_cndmask_b32_e64 v206, v92, v76, s[4:5]
	v_pk_fma_f32 v[78:79], v[144:145], v[78:79], v[132:133]
	v_cndmask_b32_e64 v85, v85, v101, s[8:9]
	v_pk_fma_f32 v[78:79], v[136:137], v[206:207], v[78:79]
	v_cndmask_b32_e64 v77, v98, v203, s[8:9]
	v_pk_fma_f32 v[68:69], v[68:69], v[140:141], v[78:79]
	v_cndmask_b32_e64 v79, v100, v84, s[4:5]
	v_cndmask_b32_e64 v84, v83, v75, s[8:9]
	v_cndmask_b32_e64 v78, v74, v82, s[4:5]
	v_pk_fma_f32 v[82:83], v[124:125], v[84:85], v[120:121]
	v_cndmask_b32_e64 v76, v94, v158, s[8:9]
	v_pk_fma_f32 v[78:79], v[112:113], v[78:79], v[82:83]
	v_cndmask_b32_e64 v205, v204, v99, s[4:5]
	v_pk_fma_f32 v[64:65], v[64:65], v[116:117], v[78:79]
	v_cndmask_b32_e64 v204, v159, v95, s[4:5]
	v_mul_f32_e32 v78, 0xbfb8aa3b, v64
	v_exp_f32_e32 v78, v78
	v_pk_fma_f32 v[76:77], v[146:147], v[76:77], v[134:135]
	v_cndmask_b32_e64 v75, v90, v106, s[8:9]
	v_pk_fma_f32 v[76:77], v[138:139], v[204:205], v[76:77]
	v_cndmask_b32_e64 v74, v86, v102, s[8:9]
	v_pk_fma_f32 v[70:71], v[70:71], v[142:143], v[76:77]
	v_cndmask_b32_e64 v77, v107, v91, s[4:5]
	v_cndmask_b32_e64 v76, v103, v87, s[4:5]
	v_pk_fma_f32 v[74:75], v[126:127], v[74:75], v[122:123]
	v_mul_f32_e32 v79, 0xbfb8aa3b, v65
	v_pk_fma_f32 v[74:75], v[114:115], v[76:77], v[74:75]
	v_add_f32_e32 v76, 1.0, v78
	v_exp_f32_e32 v79, v79
	v_rcp_f32_e32 v76, v76
	v_pk_fma_f32 v[66:67], v[66:67], v[118:119], v[74:75]
	v_add_f32_e32 v77, 1.0, v79
	v_mul_f32_e32 v64, v64, v76
	v_rcp_f32_e32 v77, v77
	v_mul_f32_e32 v64, v64, v68
	v_mul_f32_e32 v68, 0xbfb8aa3b, v66
	v_mul_f32_e32 v74, 0xbfb8aa3b, v67
	v_exp_f32_e32 v68, v68
	v_exp_f32_e32 v74, v74
	v_mul_f32_e32 v65, v65, v77
	v_mul_f32_e32 v65, v65, v69
	v_add_f32_e32 v68, 1.0, v68
	v_add_f32_e32 v69, 1.0, v74
	v_rcp_f32_e32 v68, v68
	v_rcp_f32_e32 v69, v69
	v_cvt_pk_bf16_f32 v64, v64, v65
	v_mul_f32_e32 v65, v66, v68
	v_mul_f32_e32 v66, v67, v69
	v_mul_f32_e32 v65, v65, v70
	v_mul_f32_e32 v66, v66, v71
	v_cvt_pk_bf16_f32 v65, v65, v66
	v_add_co_u32_e32 v66, vcc, s68, v180
	global_load_dwordx4 v[84:87], v[182:183], off offset:16
	s_nop 0
	v_addc_co_u32_e32 v67, vcc, 0, v181, vcc
	v_add_co_u32_e32 v70, vcc, s69, v180
	global_load_dwordx4 v[92:95], v[180:181], off offset:16
	s_nop 0
	global_load_dwordx4 v[66:69], v[66:67], off offset:2064
	v_addc_co_u32_e32 v71, vcc, 0, v181, vcc
	global_load_dwordx4 v[76:79], v[70:71], off offset:16
	global_load_dwordx4 v[118:121], v[184:185], off offset:3088
	global_load_dwordx4 v[122:125], v[186:187], off offset:3088
	global_load_dwordx4 v[114:117], v[188:189], off offset:1040
	global_load_dwordx4 v[100:103], v[190:191], off offset:3088
	v_mov_b32_dpp v98, v56 row_ror:1 row_mask:0xf bank_mask:0xf
	v_mov_b32_dpp v99, v56 row_ror:2 row_mask:0xf bank_mask:0xf
	v_mov_b32_dpp v126, v57 row_ror:1 row_mask:0xf bank_mask:0xf
	v_mov_b32_dpp v127, v57 row_ror:2 row_mask:0xf bank_mask:0xf
	v_mov_b32_dpp v133, v58 row_ror:1 row_mask:0xf bank_mask:0xf
	v_mov_b32_dpp v132, v58 row_ror:2 row_mask:0xf bank_mask:0xf
	v_mov_b32_dpp v135, v59 row_ror:1 row_mask:0xf bank_mask:0xf
	v_mov_b32_dpp v134, v59 row_ror:2 row_mask:0xf bank_mask:0xf
	s_and_saveexec_b64 s[46:47], s[10:11]
	s_cbranch_execz .LBB0_508
	global_store_dwordx4 v[192:193], v[56:59], off offset:16
.LBB0_508:
	s_or_b64 exec, exec, s[46:47]
	v_or_b32_e32 v70, 4, v176
	v_ashrrev_i32_e32 v71, 31, v70
	v_mov_b32_dpp v74, v60 row_ror:1 row_mask:0xf bank_mask:0xf
	v_mov_b32_dpp v75, v60 row_ror:2 row_mask:0xf bank_mask:0xf
	v_mov_b32_dpp v82, v61 row_ror:1 row_mask:0xf bank_mask:0xf
	v_mov_b32_dpp v83, v61 row_ror:2 row_mask:0xf bank_mask:0xf
	v_mov_b32_dpp v91, v62 row_ror:1 row_mask:0xf bank_mask:0xf
	v_mov_b32_dpp v90, v62 row_ror:2 row_mask:0xf bank_mask:0xf
	v_mov_b32_dpp v107, v63 row_ror:1 row_mask:0xf bank_mask:0xf
	v_mov_b32_dpp v106, v63 row_ror:2 row_mask:0xf bank_mask:0xf
	s_and_saveexec_b64 s[46:47], s[10:11]
	s_cbranch_execz .LBB0_510
	v_lshl_add_u64 v[112:113], v[70:71], 2, v[178:179]
	v_add_co_u32_e32 v112, vcc, 0x2000, v112
	s_nop 1
	v_addc_co_u32_e32 v113, vcc, 0, v113, vcc
	global_store_dwordx4 v[112:113], v[60:63], off offset:3072
; __device__ __forceinline__ unsigned cvt_pk_bf16(float lo, float hi) { unsigned r; asm volatile("v_cvt_pk_bf16_f32 %0, %1, %2" : "=v"(r) : "v"(lo), "v"(hi)); return r; }
; template <int CTRL> __device__ __forceinline__ float dpp_ror(float v) { return __builtin_bit_cast(float, __builtin_amdgcn_update_dpp(0, __builtin_bit_cast(int, v), CTRL, 0xf, 0xf, false)); }
; __device__ __forceinline__ float silu_f(float g) { return g * __builtin_amdgcn_rcpf(1.f + __builtin_amdgcn_exp2f(-g * LOG2E)); }
;     __device__ __forceinline__ void operator()(const f32x4 (&acc)[2][2][4][2], const pg8::Unit& u, int wr, int wc, int fr, int fq) const {
;     ...
;                 for (int m = 0; m < 4; ++m) {
;                     f32x4 y[2];
; #pragma unroll
;                     for (int bj = 0; bj < 2; ++bj) {
;                         const f32x4 cur = acc[ai][bj][m][n]; f32x4 r1, r2;
; #pragma unroll
;                         for (int j = 0; j < 4; ++j) { r1[j] = dpp_ror<0x121>(cur[j]); r2[j] = dpp_ror<0x122>(cur[j]); }
;                         const f32x4 s1 = (fr >= 1) ? r1 : p1[bj], s2 = (fr >= 2) ? r2 : p2[bj];
;                         y[bj] = bb[bj] + w[bj][0] * s2 + w[bj][1] * s1 + w[bj][2] * cur;
;                         p1[bj] = r1; p2[bj] = r2;
;                         if (m == 0 && fr < 2) *(f32x4*)(hf + (size_t)(wb * 2 + fr) * FFN2 + bj * FFN + f0) = cur;
;                         if (m == 3 && fr >= 14) *(f32x4*)(hl + (size_t)(wb * 2 + fr - 14) * FFN2 + bj * FFN + f0) = cur;
;                     }
;                     u32x2 o; o.x = pg8::cvt_pk_bf16(silu_f(y[0][0]) * y[1][0], silu_f(y[0][1]) * y[1][1]); o.y = pg8::cvt_pk_bf16(silu_f(y[0][2]) * y[1][2], silu_f(y[0][3]) * y[1][3]);
;                     if (n == 0) held[ai][m] = o;
;                     else *(u32x4*)(act + (size_t)(wb * 64 + m * 16 + fr) * FFN + f0 - 4) = (u32x4){held[ai][m].x, held[ai][m].y, o.x, o.y};
.LBB0_510:
	s_or_b64 exec, exec, s[46:47]
	v_cndmask_b32_e64 v139, 0, v83, s[8:9]
	v_cndmask_b32_e64 v138, 0, v75, s[8:9]
	v_cndmask_b32_e64 v137, v82, 0, s[4:5]
	v_cndmask_b32_e64 v136, v74, 0, s[4:5]
	s_waitcnt vmcnt(2)
	v_pk_fma_f32 v[138:139], v[122:123], v[138:139], v[118:119]
	v_cndmask_b32_e64 v141, 0, v106, s[8:9]
	s_waitcnt vmcnt(1)
	v_pk_fma_f32 v[136:137], v[114:115], v[136:137], v[138:139]
	v_cndmask_b32_e64 v139, 0, v127, s[8:9]
	v_cndmask_b32_e64 v138, 0, v99, s[8:9]
	s_waitcnt vmcnt(0)
	v_pk_fma_f32 v[60:61], v[60:61], v[100:101], v[136:137]
	v_cndmask_b32_e64 v137, v126, 0, s[4:5]
	v_cndmask_b32_e64 v136, v98, 0, s[4:5]
	v_pk_fma_f32 v[138:139], v[92:93], v[138:139], v[84:85]
	v_cndmask_b32_e64 v140, 0, v90, s[8:9]
	v_pk_fma_f32 v[136:137], v[66:67], v[136:137], v[138:139]
	v_cndmask_b32_e64 v113, v107, 0, s[4:5]
	v_pk_fma_f32 v[56:57], v[56:57], v[76:77], v[136:137]
	v_cndmask_b32_e64 v112, v91, 0, s[4:5]
	v_mul_f32_e32 v136, 0xbfb8aa3b, v56
	v_pk_fma_f32 v[140:141], v[124:125], v[140:141], v[120:121]
	v_exp_f32_e32 v138, v136
	v_pk_fma_f32 v[112:113], v[116:117], v[112:113], v[140:141]
	v_cndmask_b32_e64 v141, 0, v134, s[8:9]
	v_cndmask_b32_e64 v140, 0, v132, s[8:9]
	v_pk_fma_f32 v[62:63], v[62:63], v[102:103], v[112:113]
	v_cndmask_b32_e64 v113, v135, 0, s[4:5]
	v_cndmask_b32_e64 v112, v133, 0, s[4:5]
	v_pk_fma_f32 v[140:141], v[94:95], v[140:141], v[86:87]
	v_mul_f32_e32 v136, 0xbfb8aa3b, v57
	v_pk_fma_f32 v[112:113], v[68:69], v[112:113], v[140:141]
	v_exp_f32_e32 v139, v136
	v_pk_fma_f32 v[136:137], v[58:59], v[78:79], v[112:113]
	v_add_f32_e32 v58, 1.0, v138
	v_rcp_f32_e32 v59, v58
	v_add_f32_e32 v58, 1.0, v139
	v_rcp_f32_e32 v112, v58
	v_lshl_or_b32 v58, s39, 6, v196
	v_mul_f32_e32 v56, v56, v59
	v_mul_f32_e32 v56, v56, v60
	v_mul_f32_e32 v59, 0xbfb8aa3b, v136
	v_mul_f32_e32 v60, 0xbfb8aa3b, v137
	v_exp_f32_e32 v59, v59
	v_exp_f32_e32 v60, v60
	v_mul_f32_e32 v57, v57, v112
	v_mul_f32_e32 v57, v57, v61
	v_add_f32_e32 v59, 1.0, v59
	v_add_f32_e32 v60, 1.0, v60
	v_rcp_f32_e32 v59, v59
	v_rcp_f32_e32 v60, v60
	v_cvt_pk_bf16_f32 v112, v56, v57
	v_mul_f32_e32 v56, v136, v59
	v_mul_f32_e32 v57, v137, v60
	v_mul_f32_e32 v56, v56, v62
	v_mul_f32_e32 v57, v57, v63
	v_mov_b64_e32 v[136:137], s[24:25]
	v_cvt_pk_bf16_f32 v113, v56, v57
	v_mad_i64_i32 v[60:61], s[46:47], v58, s77, v[136:137]
	v_lshlrev_b64 v[56:57], 1, v[176:177]
	v_lshl_add_u64 v[60:61], v[60:61], 0, v[56:57]
	global_store_dwordx4 v[60:61], v[110:113], off
	v_mov_b32_dpp v59, v52 row_ror:1 row_mask:0xf bank_mask:0xf
	s_nop 0
	v_mov_b32_dpp v112, v52 row_ror:2 row_mask:0xf bank_mask:0xf
	v_mov_b32_dpp v140, v54 row_ror:2 row_mask:0xf bank_mask:0xf
	v_mov_b32_dpp v142, v55 row_ror:2 row_mask:0xf bank_mask:0xf
	v_mov_b32_dpp v138, v53 row_ror:2 row_mask:0xf bank_mask:0xf
	v_mov_b32_dpp v139, v54 row_ror:1 row_mask:0xf bank_mask:0xf
	v_mov_b32_dpp v141, v55 row_ror:1 row_mask:0xf bank_mask:0xf
	v_cndmask_b32_e64 v62, v59, v98, s[4:5]
	v_cndmask_b32_e64 v110, v99, v112, s[8:9]
	v_cndmask_b32_e64 v99, v134, v142, s[8:9]
	v_cndmask_b32_e64 v98, v132, v140, s[8:9]
	v_mov_b32_dpp v113, v53 row_ror:1 row_mask:0xf bank_mask:0xf
	v_cndmask_b32_e64 v61, v141, v135, s[4:5]
	v_cndmask_b32_e64 v60, v139, v133, s[4:5]
	v_cndmask_b32_e64 v111, v127, v138, s[8:9]
	v_pk_fma_f32 v[98:99], v[94:95], v[98:99], v[86:87]
	v_cndmask_b32_e64 v63, v113, v126, s[4:5]
	v_pk_fma_f32 v[110:111], v[92:93], v[110:111], v[84:85]
	v_pk_fma_f32 v[60:61], v[68:69], v[60:61], v[98:99]
	v_pk_fma_f32 v[62:63], v[66:67], v[62:63], v[110:111]
	v_mov_b32_dpp v98, v48 row_ror:1 row_mask:0xf bank_mask:0xf
	v_mov_b32_dpp v126, v48 row_ror:2 row_mask:0xf bank_mask:0xf
	v_mov_b32_dpp v99, v49 row_ror:1 row_mask:0xf bank_mask:0xf
	v_mov_b32_dpp v133, v50 row_ror:2 row_mask:0xf bank_mask:0xf
	v_mov_b32_dpp v135, v51 row_ror:2 row_mask:0xf bank_mask:0xf
	v_pk_fma_f32 v[52:53], v[52:53], v[76:77], v[62:63]
	v_mov_b32_dpp v132, v50 row_ror:1 row_mask:0xf bank_mask:0xf
	v_mov_b32_dpp v134, v51 row_ror:1 row_mask:0xf bank_mask:0xf
	v_cndmask_b32_e64 v63, v99, v82, s[4:5]
	v_cndmask_b32_e64 v62, v98, v74, s[4:5]
	v_cndmask_b32_e64 v82, v75, v126, s[8:9]
	v_cndmask_b32_e64 v75, v106, v135, s[8:9]
	v_cndmask_b32_e64 v74, v90, v133, s[8:9]
	v_pk_fma_f32 v[54:55], v[54:55], v[78:79], v[60:61]
	v_cndmask_b32_e64 v61, v134, v107, s[4:5]
	v_cndmask_b32_e64 v60, v132, v91, s[4:5]
	v_pk_fma_f32 v[74:75], v[124:125], v[74:75], v[120:121]
	v_pk_fma_f32 v[60:61], v[116:117], v[60:61], v[74:75]
	v_mul_f32_e32 v74, 0xbfb8aa3b, v52
	v_exp_f32_e32 v74, v74
	v_mul_f32_e32 v75, 0xbfb8aa3b, v53
	v_exp_f32_e32 v75, v75
	v_pk_fma_f32 v[50:51], v[50:51], v[102:103], v[60:61]
	v_add_f32_e32 v60, 1.0, v74
	v_mov_b32_dpp v127, v49 row_ror:2 row_mask:0xf bank_mask:0xf
	v_rcp_f32_e32 v60, v60
	v_add_f32_e32 v61, 1.0, v75
	v_cndmask_b32_e64 v83, v83, v127, s[8:9]
	v_rcp_f32_e32 v61, v61
	v_pk_fma_f32 v[82:83], v[122:123], v[82:83], v[118:119]
	v_mul_f32_e32 v52, v52, v60
	v_pk_fma_f32 v[62:63], v[114:115], v[62:63], v[82:83]
	v_mul_f32_e32 v60, 0xbfb8aa3b, v55
	v_pk_fma_f32 v[48:49], v[48:49], v[100:101], v[62:63]
	v_exp_f32_e32 v60, v60
	v_mul_f32_e32 v48, v52, v48
	v_mul_f32_e32 v52, v53, v61
	v_mul_f32_e32 v53, 0xbfb8aa3b, v54
	v_exp_f32_e32 v53, v53
	v_mul_f32_e32 v49, v52, v49
	v_cvt_pk_bf16_f32 v110, v48, v49
	v_add_f32_e32 v52, 1.0, v53
	v_rcp_f32_e32 v52, v52
	v_add_f32_e32 v53, 1.0, v60
	v_rcp_f32_e32 v53, v53
	v_mul_f32_e32 v48, v54, v52
	v_mul_f32_e32 v48, v48, v50
	v_mul_f32_e32 v49, v55, v53
	v_mul_f32_e32 v49, v49, v51
	v_cvt_pk_bf16_f32 v111, v48, v49
	v_or_b32_e32 v48, 16, v58
	v_mad_i64_i32 v[48:49], s[46:47], v48, s77, v[136:137]
; __device__ __forceinline__ unsigned cvt_pk_bf16(float lo, float hi) { unsigned r; asm volatile("v_cvt_pk_bf16_f32 %0, %1, %2" : "=v"(r) : "v"(lo), "v"(hi)); return r; }
; template <int CTRL> __device__ __forceinline__ float dpp_ror(float v) { return __builtin_bit_cast(float, __builtin_amdgcn_update_dpp(0, __builtin_bit_cast(int, v), CTRL, 0xf, 0xf, false)); }
; __device__ __forceinline__ float silu_f(float g) { return g * __builtin_amdgcn_rcpf(1.f + __builtin_amdgcn_exp2f(-g * LOG2E)); }
;     __device__ __forceinline__ void operator()(const f32x4 (&acc)[2][2][4][2], const pg8::Unit& u, int wr, int wc, int fr, int fq) const {
;     ...
;                 for (int m = 0; m < 4; ++m) {
;                     f32x4 y[2];
; #pragma unroll
;                     for (int bj = 0; bj < 2; ++bj) {
;                         const f32x4 cur = acc[ai][bj][m][n]; f32x4 r1, r2;
; #pragma unroll
;                         for (int j = 0; j < 4; ++j) { r1[j] = dpp_ror<0x121>(cur[j]); r2[j] = dpp_ror<0x122>(cur[j]); }
;                         const f32x4 s1 = (fr >= 1) ? r1 : p1[bj], s2 = (fr >= 2) ? r2 : p2[bj];
;                         y[bj] = bb[bj] + w[bj][0] * s2 + w[bj][1] * s1 + w[bj][2] * cur;
;                         p1[bj] = r1; p2[bj] = r2;
;                         if (m == 0 && fr < 2) *(f32x4*)(hf + (size_t)(wb * 2 + fr) * FFN2 + bj * FFN + f0) = cur;
;                         if (m == 3 && fr >= 14) *(f32x4*)(hl + (size_t)(wb * 2 + fr - 14) * FFN2 + bj * FFN + f0) = cur;
;                     }
;                     u32x2 o; o.x = pg8::cvt_pk_bf16(silu_f(y[0][0]) * y[1][0], silu_f(y[0][1]) * y[1][1]); o.y = pg8::cvt_pk_bf16(silu_f(y[0][2]) * y[1][2], silu_f(y[0][3]) * y[1][3]);
;                     if (n == 0) held[ai][m] = o;
;                     else *(u32x4*)(act + (size_t)(wb * 64 + m * 16 + fr) * FFN + f0 - 4) = (u32x4){held[ai][m].x, held[ai][m].y, o.x, o.y};
	v_lshl_add_u64 v[48:49], v[48:49], 0, v[56:57]
	global_store_dwordx4 v[48:49], v[108:111], off
	v_mov_b32_dpp v49, v44 row_ror:2 row_mask:0xf bank_mask:0xf
	v_mov_b32_dpp v51, v45 row_ror:2 row_mask:0xf bank_mask:0xf
	v_mov_b32_dpp v52, v46 row_ror:2 row_mask:0xf bank_mask:0xf
	v_mov_b32_dpp v54, v47 row_ror:2 row_mask:0xf bank_mask:0xf
	v_mov_b32_dpp v48, v44 row_ror:1 row_mask:0xf bank_mask:0xf
	v_mov_b32_dpp v50, v45 row_ror:1 row_mask:0xf bank_mask:0xf
	v_mov_b32_dpp v53, v46 row_ror:1 row_mask:0xf bank_mask:0xf
	v_mov_b32_dpp v55, v47 row_ror:1 row_mask:0xf bank_mask:0xf
	v_cndmask_b32_e64 v75, v138, v51, s[8:9]
	v_cndmask_b32_e64 v74, v112, v49, s[8:9]
	v_cndmask_b32_e64 v83, v142, v54, s[8:9]
	v_cndmask_b32_e64 v82, v140, v52, s[8:9]
	v_cndmask_b32_e64 v61, v55, v141, s[4:5]
	v_cndmask_b32_e64 v60, v53, v139, s[4:5]
	v_cndmask_b32_e64 v63, v50, v113, s[4:5]
	v_cndmask_b32_e64 v62, v48, v59, s[4:5]
	v_pk_fma_f32 v[82:83], v[94:95], v[82:83], v[86:87]
	v_pk_fma_f32 v[74:75], v[92:93], v[74:75], v[84:85]
	v_pk_fma_f32 v[60:61], v[68:69], v[60:61], v[82:83]
	v_pk_fma_f32 v[62:63], v[66:67], v[62:63], v[74:75]
	v_pk_fma_f32 v[74:75], v[46:47], v[78:79], v[60:61]
	v_pk_fma_f32 v[82:83], v[44:45], v[76:77], v[62:63]
	v_mov_b32_dpp v45, v40 row_ror:2 row_mask:0xf bank_mask:0xf
	v_mov_b32_dpp v47, v41 row_ror:2 row_mask:0xf bank_mask:0xf
	v_mov_b32_dpp v44, v40 row_ror:1 row_mask:0xf bank_mask:0xf
	v_mov_b32_dpp v46, v41 row_ror:1 row_mask:0xf bank_mask:0xf
	v_cndmask_b32_e64 v107, v127, v47, s[8:9]
	v_cndmask_b32_e64 v106, v126, v45, s[8:9]
	v_cndmask_b32_e64 v99, v46, v99, s[4:5]
	v_cndmask_b32_e64 v98, v44, v98, s[4:5]
	v_pk_fma_f32 v[106:107], v[122:123], v[106:107], v[118:119]
	v_mul_f32_e32 v63, 0xbfb8aa3b, v82
	v_pk_fma_f32 v[98:99], v[114:115], v[98:99], v[106:107]
	v_exp_f32_e32 v63, v63
	v_mul_f32_e32 v106, 0xbfb8aa3b, v83
	v_mov_b32_dpp v59, v42 row_ror:2 row_mask:0xf bank_mask:0xf
	v_mov_b32_dpp v61, v43 row_ror:2 row_mask:0xf bank_mask:0xf
	v_exp_f32_e32 v106, v106
	v_mov_b32_dpp v60, v42 row_ror:1 row_mask:0xf bank_mask:0xf
	v_mov_b32_dpp v62, v43 row_ror:1 row_mask:0xf bank_mask:0xf
	v_cndmask_b32_e64 v109, v135, v61, s[8:9]
	v_cndmask_b32_e64 v108, v133, v59, s[8:9]
	v_cndmask_b32_e64 v91, v62, v134, s[4:5]
	v_cndmask_b32_e64 v90, v60, v132, s[4:5]
	v_pk_fma_f32 v[108:109], v[124:125], v[108:109], v[120:121]
	v_add_f32_e32 v63, 1.0, v63
	v_pk_fma_f32 v[90:91], v[116:117], v[90:91], v[108:109]
	v_rcp_f32_e32 v63, v63
	v_pk_fma_f32 v[42:43], v[42:43], v[102:103], v[90:91]
	v_add_f32_e32 v90, 1.0, v106
	v_rcp_f32_e32 v90, v90
	v_pk_fma_f32 v[40:41], v[40:41], v[100:101], v[98:99]
	v_mul_f32_e32 v63, v82, v63
	v_mul_f32_e32 v82, 0xbfb8aa3b, v74
	v_mul_f32_e32 v40, v63, v40
	v_mul_f32_e32 v63, v83, v90
	v_exp_f32_e32 v82, v82
	v_mul_f32_e32 v83, 0xbfb8aa3b, v75
	v_exp_f32_e32 v83, v83
	v_mul_f32_e32 v41, v63, v41
	v_add_f32_e32 v63, 1.0, v82
	v_rcp_f32_e32 v63, v63
	v_add_f32_e32 v82, 1.0, v83
	v_rcp_f32_e32 v82, v82
	v_cvt_pk_bf16_f32 v106, v40, v41
	v_mul_f32_e32 v40, v74, v63
	v_mul_f32_e32 v40, v40, v42
	v_mul_f32_e32 v41, v75, v82
	v_mul_f32_e32 v41, v41, v43
	v_cvt_pk_bf16_f32 v107, v40, v41
	v_or_b32_e32 v40, 32, v58
	v_mad_i64_i32 v[40:41], s[46:47], v40, s77, v[136:137]
	v_lshl_add_u64 v[40:41], v[40:41], 0, v[56:57]
	global_store_dwordx4 v[40:41], v[104:107], off
	v_mov_b32_dpp v40, v32 row_ror:1 row_mask:0xf bank_mask:0xf
	v_mov_b32_dpp v41, v32 row_ror:2 row_mask:0xf bank_mask:0xf
	v_mov_b32_dpp v42, v33 row_ror:1 row_mask:0xf bank_mask:0xf
	v_mov_b32_dpp v43, v33 row_ror:2 row_mask:0xf bank_mask:0xf
	v_mov_b32_dpp v74, v34 row_ror:1 row_mask:0xf bank_mask:0xf
	v_mov_b32_dpp v63, v34 row_ror:2 row_mask:0xf bank_mask:0xf
	v_mov_b32_dpp v82, v35 row_ror:1 row_mask:0xf bank_mask:0xf
	v_mov_b32_dpp v75, v35 row_ror:2 row_mask:0xf bank_mask:0xf
	s_and_saveexec_b64 s[46:47], s[12:13]
	s_cbranch_execz .LBB0_512
	global_store_dwordx4 v[154:155], v[32:35], off offset:16
.LBB0_512:
	s_or_b64 exec, exec, s[46:47]
	v_mov_b32_dpp v83, v36 row_ror:1 row_mask:0xf bank_mask:0xf
	v_mov_b32_dpp v90, v36 row_ror:2 row_mask:0xf bank_mask:0xf
	v_mov_b32_dpp v91, v37 row_ror:1 row_mask:0xf bank_mask:0xf
	v_mov_b32_dpp v98, v37 row_ror:2 row_mask:0xf bank_mask:0xf
	v_mov_b32_dpp v104, v38 row_ror:1 row_mask:0xf bank_mask:0xf
	v_mov_b32_dpp v99, v38 row_ror:2 row_mask:0xf bank_mask:0xf
	v_mov_b32_dpp v106, v39 row_ror:1 row_mask:0xf bank_mask:0xf
	v_mov_b32_dpp v105, v39 row_ror:2 row_mask:0xf bank_mask:0xf
	s_and_saveexec_b64 s[46:47], s[12:13]
	s_cbranch_execz .LBB0_514
	v_lshl_add_u64 v[108:109], v[70:71], 2, v[148:149]
	v_add_co_u32_e32 v108, vcc, 0x2000, v108
	s_nop 1
	v_addc_co_u32_e32 v109, vcc, 0, v109, vcc
	global_store_dwordx4 v[108:109], v[36:39], off offset:3072
; __device__ __forceinline__ unsigned cvt_pk_bf16(float lo, float hi) { unsigned r; asm volatile("v_cvt_pk_bf16_f32 %0, %1, %2" : "=v"(r) : "v"(lo), "v"(hi)); return r; }
; template <int CTRL> __device__ __forceinline__ float dpp_ror(float v) { return __builtin_bit_cast(float, __builtin_amdgcn_update_dpp(0, __builtin_bit_cast(int, v), CTRL, 0xf, 0xf, false)); }
; __device__ __forceinline__ float silu_f(float g) { return g * __builtin_amdgcn_rcpf(1.f + __builtin_amdgcn_exp2f(-g * LOG2E)); }
;     __device__ __forceinline__ void operator()(const f32x4 (&acc)[2][2][4][2], const pg8::Unit& u, int wr, int wc, int fr, int fq) const {
;     ...
;                 for (int m = 0; m < 4; ++m) {
;                     f32x4 y[2];
; #pragma unroll
;                     for (int bj = 0; bj < 2; ++bj) {
;                         const f32x4 cur = acc[ai][bj][m][n]; f32x4 r1, r2;
; #pragma unroll
;                         for (int j = 0; j < 4; ++j) { r1[j] = dpp_ror<0x121>(cur[j]); r2[j] = dpp_ror<0x122>(cur[j]); }
;                         const f32x4 s1 = (fr >= 1) ? r1 : p1[bj], s2 = (fr >= 2) ? r2 : p2[bj];
;                         y[bj] = bb[bj] + w[bj][0] * s2 + w[bj][1] * s1 + w[bj][2] * cur;
;                         p1[bj] = r1; p2[bj] = r2;
;                         if (m == 0 && fr < 2) *(f32x4*)(hf + (size_t)(wb * 2 + fr) * FFN2 + bj * FFN + f0) = cur;
;                         if (m == 3 && fr >= 14) *(f32x4*)(hl + (size_t)(wb * 2 + fr - 14) * FFN2 + bj * FFN + f0) = cur;
;                     }
;                     u32x2 o; o.x = pg8::cvt_pk_bf16(silu_f(y[0][0]) * y[1][0], silu_f(y[0][1]) * y[1][1]); o.y = pg8::cvt_pk_bf16(silu_f(y[0][2]) * y[1][2], silu_f(y[0][3]) * y[1][3]);
;                     if (n == 0) held[ai][m] = o;
;                     else *(u32x4*)(act + (size_t)(wb * 64 + m * 16 + fr) * FFN + f0 - 4) = (u32x4){held[ai][m].x, held[ai][m].y, o.x, o.y};
.LBB0_514:
	s_or_b64 exec, exec, s[46:47]
	v_cndmask_b32_e64 v109, v91, v46, s[4:5]
	v_cndmask_b32_e64 v47, v47, v98, s[8:9]
	v_cndmask_b32_e64 v46, v45, v90, s[8:9]
	v_cndmask_b32_e64 v108, v83, v44, s[4:5]
	v_pk_fma_f32 v[46:47], v[122:123], v[46:47], v[118:119]
	v_cndmask_b32_e64 v43, v51, v43, s[8:9]
	v_pk_fma_f32 v[46:47], v[114:115], v[108:109], v[46:47]
	v_cndmask_b32_e64 v45, v61, v105, s[8:9]
	v_pk_fma_f32 v[36:37], v[36:37], v[100:101], v[46:47]
	v_cndmask_b32_e64 v47, v42, v50, s[4:5]
	v_cndmask_b32_e64 v42, v49, v41, s[8:9]
	v_cndmask_b32_e64 v46, v40, v48, s[4:5]
	v_pk_fma_f32 v[42:43], v[92:93], v[42:43], v[84:85]
	v_cndmask_b32_e64 v44, v59, v99, s[8:9]
	v_pk_fma_f32 v[42:43], v[66:67], v[46:47], v[42:43]
	v_cndmask_b32_e64 v107, v106, v62, s[4:5]
	v_pk_fma_f32 v[32:33], v[32:33], v[76:77], v[42:43]
	v_cndmask_b32_e64 v106, v104, v60, s[4:5]
	v_mul_f32_e32 v42, 0xbfb8aa3b, v32
	v_exp_f32_e32 v42, v42
	v_mul_f32_e32 v43, 0xbfb8aa3b, v33
	v_pk_fma_f32 v[44:45], v[124:125], v[44:45], v[120:121]
	v_exp_f32_e32 v43, v43
	v_add_f32_e32 v42, 1.0, v42
	v_rcp_f32_e32 v42, v42
	v_pk_fma_f32 v[44:45], v[116:117], v[106:107], v[44:45]
	v_cndmask_b32_e64 v41, v54, v75, s[8:9]
	v_cndmask_b32_e64 v40, v52, v63, s[8:9]
	v_pk_fma_f32 v[38:39], v[38:39], v[102:103], v[44:45]
	v_cndmask_b32_e64 v45, v82, v55, s[4:5]
	v_cndmask_b32_e64 v44, v74, v53, s[4:5]
	v_pk_fma_f32 v[40:41], v[94:95], v[40:41], v[86:87]
	v_add_f32_e32 v43, 1.0, v43
	v_pk_fma_f32 v[40:41], v[68:69], v[44:45], v[40:41]
	v_mul_f32_e32 v32, v32, v42
	v_pk_fma_f32 v[34:35], v[34:35], v[78:79], v[40:41]
	v_rcp_f32_e32 v43, v43
	v_mul_f32_e32 v32, v32, v36
	v_mul_f32_e32 v36, 0xbfb8aa3b, v34
	v_mul_f32_e32 v40, 0xbfb8aa3b, v35
	v_exp_f32_e32 v36, v36
	v_exp_f32_e32 v40, v40
	v_mul_f32_e32 v33, v33, v43
	v_mul_f32_e32 v33, v33, v37
	v_add_f32_e32 v36, 1.0, v36
	v_add_f32_e32 v37, 1.0, v40
	v_rcp_f32_e32 v36, v36
	v_rcp_f32_e32 v37, v37
	v_cvt_pk_bf16_f32 v98, v32, v33
	v_mul_f32_e32 v32, v34, v36
	v_mul_f32_e32 v33, v35, v37
	v_mul_f32_e32 v32, v32, v38
	v_mul_f32_e32 v33, v33, v39
	v_cvt_pk_bf16_f32 v99, v32, v33
	v_or_b32_e32 v34, 48, v58
	v_mov_b64_e32 v[32:33], s[24:25]
	v_mad_i64_i32 v[32:33], s[46:47], v34, s77, v[32:33]
	v_lshl_add_u64 v[32:33], v[176:177], 1, v[32:33]
	v_mov_b32_dpp v39, v24 row_ror:1 row_mask:0xf bank_mask:0xf
	v_mov_b32_dpp v40, v24 row_ror:2 row_mask:0xf bank_mask:0xf
	v_mov_b32_dpp v42, v25 row_ror:1 row_mask:0xf bank_mask:0xf
	v_mov_b32_dpp v43, v25 row_ror:2 row_mask:0xf bank_mask:0xf
	v_mov_b32_dpp v45, v26 row_ror:1 row_mask:0xf bank_mask:0xf
	v_mov_b32_dpp v44, v26 row_ror:2 row_mask:0xf bank_mask:0xf
	v_mov_b32_dpp v47, v27 row_ror:1 row_mask:0xf bank_mask:0xf
	v_mov_b32_dpp v46, v27 row_ror:2 row_mask:0xf bank_mask:0xf
	global_store_dwordx4 v[32:33], v[96:99], off
	s_and_saveexec_b64 s[46:47], s[10:11]
	s_cbranch_execz .LBB0_516
	global_store_dwordx4 v[152:153], v[24:27], off offset:16
.LBB0_516:
	s_or_b64 exec, exec, s[46:47]
	v_mov_b32_dpp v32, v28 row_ror:1 row_mask:0xf bank_mask:0xf
	v_mov_b32_dpp v33, v28 row_ror:2 row_mask:0xf bank_mask:0xf
	v_mov_b32_dpp v34, v29 row_ror:1 row_mask:0xf bank_mask:0xf
	v_mov_b32_dpp v35, v29 row_ror:2 row_mask:0xf bank_mask:0xf
	v_mov_b32_dpp v37, v30 row_ror:1 row_mask:0xf bank_mask:0xf
	v_mov_b32_dpp v36, v30 row_ror:2 row_mask:0xf bank_mask:0xf
	v_mov_b32_dpp v41, v31 row_ror:1 row_mask:0xf bank_mask:0xf
	v_mov_b32_dpp v38, v31 row_ror:2 row_mask:0xf bank_mask:0xf
	s_and_saveexec_b64 s[46:47], s[10:11]
	s_cbranch_execz .LBB0_518
	v_lshl_add_u64 v[48:49], v[70:71], 2, v[130:131]
	v_add_co_u32_e32 v48, vcc, 0x2000, v48
	s_nop 1
	v_addc_co_u32_e32 v49, vcc, 0, v49, vcc
	global_store_dwordx4 v[48:49], v[28:31], off offset:3072
.LBB0_518:
	s_or_b64 exec, exec, s[46:47]
	v_cndmask_b32_e64 v53, 0, v35, s[8:9]
	v_cndmask_b32_e64 v52, 0, v33, s[8:9]
	v_cndmask_b32_e64 v51, v34, 0, s[4:5]
	v_cndmask_b32_e64 v50, v32, 0, s[4:5]
	v_pk_fma_f32 v[52:53], v[122:123], v[52:53], v[118:119]
	v_cndmask_b32_e64 v55, 0, v38, s[8:9]
	v_pk_fma_f32 v[50:51], v[114:115], v[50:51], v[52:53]
	v_cndmask_b32_e64 v53, 0, v43, s[8:9]
	v_cndmask_b32_e64 v52, 0, v40, s[8:9]
	v_pk_fma_f32 v[28:29], v[28:29], v[100:101], v[50:51]
	v_cndmask_b32_e64 v51, v42, 0, s[4:5]
	v_cndmask_b32_e64 v50, v39, 0, s[4:5]
	v_pk_fma_f32 v[52:53], v[92:93], v[52:53], v[84:85]
	v_cndmask_b32_e64 v54, 0, v36, s[8:9]
	v_pk_fma_f32 v[50:51], v[66:67], v[50:51], v[52:53]
	v_cndmask_b32_e64 v49, v41, 0, s[4:5]
	v_pk_fma_f32 v[50:51], v[24:25], v[76:77], v[50:51]
	v_cndmask_b32_e64 v48, v37, 0, s[4:5]
	v_mul_f32_e32 v24, 0xbfb8aa3b, v50
	v_exp_f32_e32 v24, v24
	v_pk_fma_f32 v[54:55], v[124:125], v[54:55], v[120:121]
	v_mul_f32_e32 v25, 0xbfb8aa3b, v51
	v_pk_fma_f32 v[48:49], v[116:117], v[48:49], v[54:55]
	v_cndmask_b32_e64 v55, 0, v46, s[8:9]
	v_cndmask_b32_e64 v54, 0, v44, s[8:9]
	v_pk_fma_f32 v[30:31], v[30:31], v[102:103], v[48:49]
	v_cndmask_b32_e64 v49, v47, 0, s[4:5]
	v_cndmask_b32_e64 v48, v45, 0, s[4:5]
	v_pk_fma_f32 v[54:55], v[94:95], v[54:55], v[86:87]
	v_add_f32_e32 v24, 1.0, v24
	v_pk_fma_f32 v[48:49], v[68:69], v[48:49], v[54:55]
	v_exp_f32_e32 v25, v25
	v_pk_fma_f32 v[26:27], v[26:27], v[78:79], v[48:49]
	v_rcp_f32_e32 v48, v24
	v_mul_f32_e32 v49, 0xbfb8aa3b, v27
	v_add_f32_e32 v24, 1.0, v25
	v_rcp_f32_e32 v25, v24
	v_mul_f32_e32 v48, v50, v48
	v_mul_f32_e32 v28, v48, v28
	v_mul_f32_e32 v48, 0xbfb8aa3b, v26
	v_exp_f32_e32 v48, v48
	v_exp_f32_e32 v49, v49
	v_mul_f32_e32 v25, v51, v25
	v_mul_f32_e32 v25, v25, v29
	v_add_f32_e32 v29, 1.0, v48
	v_add_f32_e32 v48, 1.0, v49
	v_rcp_f32_e32 v29, v29
	v_rcp_f32_e32 v48, v48
	v_cvt_pk_bf16_f32 v90, v28, v25
; __device__ __forceinline__ unsigned cvt_pk_bf16(float lo, float hi) { unsigned r; asm volatile("v_cvt_pk_bf16_f32 %0, %1, %2" : "=v"(r) : "v"(lo), "v"(hi)); return r; }
; template <int CTRL> __device__ __forceinline__ float dpp_ror(float v) { return __builtin_bit_cast(float, __builtin_amdgcn_update_dpp(0, __builtin_bit_cast(int, v), CTRL, 0xf, 0xf, false)); }
; __device__ __forceinline__ float silu_f(float g) { return g * __builtin_amdgcn_rcpf(1.f + __builtin_amdgcn_exp2f(-g * LOG2E)); }
;     __device__ __forceinline__ void operator()(const f32x4 (&acc)[2][2][4][2], const pg8::Unit& u, int wr, int wc, int fr, int fq) const {
;     ...
;                 for (int m = 0; m < 4; ++m) {
;                     f32x4 y[2];
; #pragma unroll
;                     for (int bj = 0; bj < 2; ++bj) {
;                         const f32x4 cur = acc[ai][bj][m][n]; f32x4 r1, r2;
; #pragma unroll
;                         for (int j = 0; j < 4; ++j) { r1[j] = dpp_ror<0x121>(cur[j]); r2[j] = dpp_ror<0x122>(cur[j]); }
;                         const f32x4 s1 = (fr >= 1) ? r1 : p1[bj], s2 = (fr >= 2) ? r2 : p2[bj];
;                         y[bj] = bb[bj] + w[bj][0] * s2 + w[bj][1] * s1 + w[bj][2] * cur;
;                         p1[bj] = r1; p2[bj] = r2;
;                         if (m == 0 && fr < 2) *(f32x4*)(hf + (size_t)(wb * 2 + fr) * FFN2 + bj * FFN + f0) = cur;
;                         if (m == 3 && fr >= 14) *(f32x4*)(hl + (size_t)(wb * 2 + fr - 14) * FFN2 + bj * FFN + f0) = cur;
;                     }
;                     u32x2 o; o.x = pg8::cvt_pk_bf16(silu_f(y[0][0]) * y[1][0], silu_f(y[0][1]) * y[1][1]); o.y = pg8::cvt_pk_bf16(silu_f(y[0][2]) * y[1][2], silu_f(y[0][3]) * y[1][3]);
;                     if (n == 0) held[ai][m] = o;
;                     else *(u32x4*)(act + (size_t)(wb * 64 + m * 16 + fr) * FFN + f0 - 4) = (u32x4){held[ai][m].x, held[ai][m].y, o.x, o.y};
	v_lshl_or_b32 v24, s37, 6, v196
	v_mul_f32_e32 v25, v26, v29
	v_mul_f32_e32 v26, v27, v48
	v_mul_f32_e32 v25, v25, v30
	v_mul_f32_e32 v26, v26, v31
	v_mov_b64_e32 v[30:31], s[24:25]
	v_cvt_pk_bf16_f32 v91, v25, v26
	v_mad_i64_i32 v[26:27], s[46:47], v24, s77, v[30:31]
	v_lshl_add_u64 v[26:27], v[26:27], 0, v[56:57]
	v_mov_b32_dpp v48, v20 row_ror:2 row_mask:0xf bank_mask:0xf
	v_mov_b32_dpp v49, v21 row_ror:1 row_mask:0xf bank_mask:0xf
	v_mov_b32_dpp v50, v21 row_ror:2 row_mask:0xf bank_mask:0xf
	v_mov_b32_dpp v51, v22 row_ror:1 row_mask:0xf bank_mask:0xf
	v_mov_b32_dpp v52, v22 row_ror:2 row_mask:0xf bank_mask:0xf
	v_mov_b32_dpp v54, v23 row_ror:2 row_mask:0xf bank_mask:0xf
	global_store_dwordx4 v[26:27], v[88:91], off
	v_mov_b32_dpp v25, v20 row_ror:1 row_mask:0xf bank_mask:0xf
	v_mov_b32_dpp v53, v23 row_ror:1 row_mask:0xf bank_mask:0xf
	v_cndmask_b32_e64 v26, v51, v45, s[4:5]
	v_cndmask_b32_e64 v29, v49, v42, s[4:5]
	v_cndmask_b32_e64 v43, v43, v50, s[8:9]
	v_cndmask_b32_e64 v42, v40, v48, s[8:9]
	v_cndmask_b32_e64 v45, v46, v54, s[8:9]
	v_cndmask_b32_e64 v44, v44, v52, s[8:9]
	v_cndmask_b32_e64 v27, v53, v47, s[4:5]
	v_cndmask_b32_e64 v28, v25, v39, s[4:5]
	v_pk_fma_f32 v[44:45], v[94:95], v[44:45], v[86:87]
	v_pk_fma_f32 v[42:43], v[92:93], v[42:43], v[84:85]
	v_pk_fma_f32 v[26:27], v[68:69], v[26:27], v[44:45]
	v_pk_fma_f32 v[28:29], v[66:67], v[28:29], v[42:43]
	v_mov_b32_dpp v40, v16 row_ror:1 row_mask:0xf bank_mask:0xf
	v_mov_b32_dpp v42, v16 row_ror:2 row_mask:0xf bank_mask:0xf
	v_mov_b32_dpp v39, v17 row_ror:1 row_mask:0xf bank_mask:0xf
	v_mov_b32_dpp v45, v18 row_ror:2 row_mask:0xf bank_mask:0xf
	v_mov_b32_dpp v47, v19 row_ror:2 row_mask:0xf bank_mask:0xf
	v_pk_fma_f32 v[20:21], v[20:21], v[76:77], v[28:29]
	v_mov_b32_dpp v44, v18 row_ror:1 row_mask:0xf bank_mask:0xf
	v_mov_b32_dpp v46, v19 row_ror:1 row_mask:0xf bank_mask:0xf
	v_cndmask_b32_e64 v29, v39, v34, s[4:5]
	v_cndmask_b32_e64 v28, v40, v32, s[4:5]
	v_cndmask_b32_e64 v34, v33, v42, s[8:9]
	v_cndmask_b32_e64 v33, v38, v47, s[8:9]
	v_cndmask_b32_e64 v32, v36, v45, s[8:9]
	v_pk_fma_f32 v[22:23], v[22:23], v[78:79], v[26:27]
	v_cndmask_b32_e64 v27, v46, v41, s[4:5]
	v_cndmask_b32_e64 v26, v44, v37, s[4:5]
	v_pk_fma_f32 v[32:33], v[124:125], v[32:33], v[120:121]
	v_pk_fma_f32 v[26:27], v[116:117], v[26:27], v[32:33]
	v_mul_f32_e32 v32, 0xbfb8aa3b, v20
	v_exp_f32_e32 v32, v32
	v_mul_f32_e32 v33, 0xbfb8aa3b, v21
	v_exp_f32_e32 v33, v33
	v_pk_fma_f32 v[18:19], v[18:19], v[102:103], v[26:27]
	v_add_f32_e32 v26, 1.0, v32
	v_mov_b32_dpp v43, v17 row_ror:2 row_mask:0xf bank_mask:0xf
	v_rcp_f32_e32 v26, v26
	v_add_f32_e32 v27, 1.0, v33
	v_cndmask_b32_e64 v35, v35, v43, s[8:9]
	v_rcp_f32_e32 v27, v27
	v_pk_fma_f32 v[34:35], v[122:123], v[34:35], v[118:119]
	v_mul_f32_e32 v20, v20, v26
	v_pk_fma_f32 v[28:29], v[114:115], v[28:29], v[34:35]
	v_mul_f32_e32 v26, 0xbfb8aa3b, v23
	v_pk_fma_f32 v[16:17], v[16:17], v[100:101], v[28:29]
	v_exp_f32_e32 v26, v26
	v_mul_f32_e32 v16, v20, v16
	v_mul_f32_e32 v20, v21, v27
	v_mul_f32_e32 v21, 0xbfb8aa3b, v22
	v_exp_f32_e32 v21, v21
	v_mul_f32_e32 v17, v20, v17
	v_cvt_pk_bf16_f32 v82, v16, v17
	v_add_f32_e32 v20, 1.0, v21
	v_rcp_f32_e32 v20, v20
	v_add_f32_e32 v21, 1.0, v26
	v_rcp_f32_e32 v21, v21
	v_mul_f32_e32 v16, v22, v20
	v_mul_f32_e32 v16, v16, v18
	v_mul_f32_e32 v17, v23, v21
	v_mul_f32_e32 v17, v17, v19
	v_cvt_pk_bf16_f32 v83, v16, v17
	v_or_b32_e32 v16, 16, v24
	v_mad_i64_i32 v[16:17], s[46:47], v16, s77, v[30:31]
	v_lshl_add_u64 v[16:17], v[16:17], 0, v[56:57]
	global_store_dwordx4 v[16:17], v[80:83], off
	v_mov_b32_dpp v20, v12 row_ror:2 row_mask:0xf bank_mask:0xf
	v_mov_b32_dpp v21, v13 row_ror:2 row_mask:0xf bank_mask:0xf
	v_mov_b32_dpp v22, v14 row_ror:2 row_mask:0xf bank_mask:0xf
	v_mov_b32_dpp v23, v15 row_ror:2 row_mask:0xf bank_mask:0xf
	v_mov_b32_dpp v16, v12 row_ror:1 row_mask:0xf bank_mask:0xf
	v_mov_b32_dpp v17, v13 row_ror:1 row_mask:0xf bank_mask:0xf
	v_mov_b32_dpp v18, v14 row_ror:1 row_mask:0xf bank_mask:0xf
	v_mov_b32_dpp v19, v15 row_ror:1 row_mask:0xf bank_mask:0xf
; __device__ __forceinline__ unsigned cvt_pk_bf16(float lo, float hi) { unsigned r; asm volatile("v_cvt_pk_bf16_f32 %0, %1, %2" : "=v"(r) : "v"(lo), "v"(hi)); return r; }
; template <int CTRL> __device__ __forceinline__ float dpp_ror(float v) { return __builtin_bit_cast(float, __builtin_amdgcn_update_dpp(0, __builtin_bit_cast(int, v), CTRL, 0xf, 0xf, false)); }
; __device__ __forceinline__ float silu_f(float g) { return g * __builtin_amdgcn_rcpf(1.f + __builtin_amdgcn_exp2f(-g * LOG2E)); }
;     __device__ __forceinline__ void operator()(const f32x4 (&acc)[2][2][4][2], const pg8::Unit& u, int wr, int wc, int fr, int fq) const {
;     ...
;                 for (int m = 0; m < 4; ++m) {
;                     f32x4 y[2];
; #pragma unroll
;                     for (int bj = 0; bj < 2; ++bj) {
;                         const f32x4 cur = acc[ai][bj][m][n]; f32x4 r1, r2;
; #pragma unroll
;                         for (int j = 0; j < 4; ++j) { r1[j] = dpp_ror<0x121>(cur[j]); r2[j] = dpp_ror<0x122>(cur[j]); }
;                         const f32x4 s1 = (fr >= 1) ? r1 : p1[bj], s2 = (fr >= 2) ? r2 : p2[bj];
;                         y[bj] = bb[bj] + w[bj][0] * s2 + w[bj][1] * s1 + w[bj][2] * cur;
;                         p1[bj] = r1; p2[bj] = r2;
;                         if (m == 0 && fr < 2) *(f32x4*)(hf + (size_t)(wb * 2 + fr) * FFN2 + bj * FFN + f0) = cur;
;                         if (m == 3 && fr >= 14) *(f32x4*)(hl + (size_t)(wb * 2 + fr - 14) * FFN2 + bj * FFN + f0) = cur;
;                     }
;                     u32x2 o; o.x = pg8::cvt_pk_bf16(silu_f(y[0][0]) * y[1][0], silu_f(y[0][1]) * y[1][1]); o.y = pg8::cvt_pk_bf16(silu_f(y[0][2]) * y[1][2], silu_f(y[0][3]) * y[1][3]);
;                     if (n == 0) held[ai][m] = o;
;                     else *(u32x4*)(act + (size_t)(wb * 64 + m * 16 + fr) * FFN + f0 - 4) = (u32x4){held[ai][m].x, held[ai][m].y, o.x, o.y};
	v_cndmask_b32_e64 v33, v50, v21, s[8:9]
	v_cndmask_b32_e64 v32, v48, v20, s[8:9]
	v_cndmask_b32_e64 v35, v54, v23, s[8:9]
	v_cndmask_b32_e64 v34, v52, v22, s[8:9]
	v_cndmask_b32_e64 v27, v19, v53, s[4:5]
	v_cndmask_b32_e64 v26, v18, v51, s[4:5]
	v_cndmask_b32_e64 v29, v17, v49, s[4:5]
	v_cndmask_b32_e64 v28, v16, v25, s[4:5]
	v_pk_fma_f32 v[34:35], v[94:95], v[34:35], v[86:87]
	v_pk_fma_f32 v[32:33], v[92:93], v[32:33], v[84:85]
	v_pk_fma_f32 v[26:27], v[68:69], v[26:27], v[34:35]
	v_pk_fma_f32 v[28:29], v[66:67], v[28:29], v[32:33]
	v_pk_fma_f32 v[32:33], v[14:15], v[78:79], v[26:27]
	v_pk_fma_f32 v[34:35], v[12:13], v[76:77], v[28:29]
	v_mov_b32_dpp v12, v8 row_ror:1 row_mask:0xf bank_mask:0xf
	v_mov_b32_dpp v25, v8 row_ror:2 row_mask:0xf bank_mask:0xf
	v_mov_b32_dpp v26, v9 row_ror:2 row_mask:0xf bank_mask:0xf
	v_cndmask_b32_e64 v38, v12, v40, s[4:5]
	v_mov_b32_dpp v13, v9 row_ror:1 row_mask:0xf bank_mask:0xf
	v_cndmask_b32_e64 v41, v43, v26, s[8:9]
	v_cndmask_b32_e64 v40, v42, v25, s[8:9]
	v_cndmask_b32_e64 v39, v13, v39, s[4:5]
	v_pk_fma_f32 v[40:41], v[122:123], v[40:41], v[118:119]
	v_mul_f32_e32 v29, 0xbfb8aa3b, v34
	v_pk_fma_f32 v[38:39], v[114:115], v[38:39], v[40:41]
	v_exp_f32_e32 v29, v29
	v_mul_f32_e32 v40, 0xbfb8aa3b, v35
	v_mov_b32_dpp v27, v10 row_ror:2 row_mask:0xf bank_mask:0xf
	v_mov_b32_dpp v28, v11 row_ror:2 row_mask:0xf bank_mask:0xf
	v_exp_f32_e32 v40, v40
	v_mov_b32_dpp v14, v10 row_ror:1 row_mask:0xf bank_mask:0xf
	v_mov_b32_dpp v15, v11 row_ror:1 row_mask:0xf bank_mask:0xf
	v_cndmask_b32_e64 v43, v47, v28, s[8:9]
	v_cndmask_b32_e64 v42, v45, v27, s[8:9]
	v_cndmask_b32_e64 v37, v15, v46, s[4:5]
	v_cndmask_b32_e64 v36, v14, v44, s[4:5]
	v_pk_fma_f32 v[42:43], v[124:125], v[42:43], v[120:121]
	v_add_f32_e32 v29, 1.0, v29
	v_pk_fma_f32 v[36:37], v[116:117], v[36:37], v[42:43]
	v_rcp_f32_e32 v29, v29
	v_pk_fma_f32 v[10:11], v[10:11], v[102:103], v[36:37]
	v_add_f32_e32 v36, 1.0, v40
	v_rcp_f32_e32 v36, v36
	v_pk_fma_f32 v[8:9], v[8:9], v[100:101], v[38:39]
	v_mul_f32_e32 v29, v34, v29
	v_mul_f32_e32 v34, 0xbfb8aa3b, v32
	v_mul_f32_e32 v8, v29, v8
	v_mul_f32_e32 v29, v35, v36
	v_exp_f32_e32 v34, v34
	v_mul_f32_e32 v35, 0xbfb8aa3b, v33
	v_exp_f32_e32 v35, v35
	v_mul_f32_e32 v9, v29, v9
	v_add_f32_e32 v29, 1.0, v34
	v_rcp_f32_e32 v29, v29
	v_add_f32_e32 v34, 1.0, v35
	v_rcp_f32_e32 v34, v34
	v_cvt_pk_bf16_f32 v74, v8, v9
	v_mul_f32_e32 v8, v32, v29
	v_mul_f32_e32 v8, v8, v10
	v_mul_f32_e32 v9, v33, v34
	v_mul_f32_e32 v9, v9, v11
	v_cvt_pk_bf16_f32 v75, v8, v9
	v_or_b32_e32 v8, 32, v24
	v_mad_i64_i32 v[8:9], s[46:47], v8, s77, v[30:31]
	v_lshl_add_u64 v[8:9], v[8:9], 0, v[56:57]
	global_store_dwordx4 v[8:9], v[72:75], off
	v_mov_b32_dpp v8, v0 row_ror:1 row_mask:0xf bank_mask:0xf
	v_mov_b32_dpp v29, v0 row_ror:2 row_mask:0xf bank_mask:0xf
	v_mov_b32_dpp v9, v1 row_ror:1 row_mask:0xf bank_mask:0xf
	v_mov_b32_dpp v30, v1 row_ror:2 row_mask:0xf bank_mask:0xf
	v_mov_b32_dpp v10, v2 row_ror:1 row_mask:0xf bank_mask:0xf
	v_mov_b32_dpp v31, v2 row_ror:2 row_mask:0xf bank_mask:0xf
	v_mov_b32_dpp v11, v3 row_ror:1 row_mask:0xf bank_mask:0xf
	v_mov_b32_dpp v32, v3 row_ror:2 row_mask:0xf bank_mask:0xf
	s_and_saveexec_b64 s[46:47], s[12:13]
	s_cbranch_execz .LBB0_520
	global_store_dwordx4 v[150:151], v[0:3], off offset:16
.LBB0_520:
	s_or_b64 exec, exec, s[46:47]
	v_mov_b32_dpp v33, v4 row_ror:1 row_mask:0xf bank_mask:0xf
	v_mov_b32_dpp v37, v4 row_ror:2 row_mask:0xf bank_mask:0xf
	v_mov_b32_dpp v34, v5 row_ror:1 row_mask:0xf bank_mask:0xf
	v_mov_b32_dpp v38, v5 row_ror:2 row_mask:0xf bank_mask:0xf
	v_mov_b32_dpp v35, v6 row_ror:1 row_mask:0xf bank_mask:0xf
	v_mov_b32_dpp v39, v6 row_ror:2 row_mask:0xf bank_mask:0xf
	v_mov_b32_dpp v36, v7 row_ror:1 row_mask:0xf bank_mask:0xf
	v_mov_b32_dpp v40, v7 row_ror:2 row_mask:0xf bank_mask:0xf
	s_and_saveexec_b64 s[46:47], s[12:13]
	s_cbranch_execz .LBB0_522
	v_lshl_add_u64 v[42:43], v[70:71], 2, v[128:129]
	v_add_co_u32_e32 v42, vcc, 0x2000, v42
	s_nop 1
	v_addc_co_u32_e32 v43, vcc, 0, v43, vcc
	global_store_dwordx4 v[42:43], v[4:7], off offset:3072

; __device__ __forceinline__ unsigned cvt_pk_bf16(float lo, float hi) { unsigned r; asm volatile("v_cvt_pk_bf16_f32 %0, %1, %2" : "=v"(r) : "v"(lo), "v"(hi)); return r; }
; __device__ __forceinline__ float silu_f(float g) { return g * __builtin_amdgcn_rcpf(1.f + __builtin_amdgcn_exp2f(-g * LOG2E)); }
;     __device__ __forceinline__ void operator()(const f32x4 (&acc)[2][2][4][2], const pg8::Unit& u, int wr, int wc, int fr, int fq) const {
;     ...
;         for (int n = 0; n < 2; ++n) {
;             const int f0 = u.pn * 128 + wc * 32 + 8 * fq + 4 * n;
;             f32x4 w[2][3], bb[2];
; #pragma unroll
;             for (int bj = 0; bj < 2; ++bj) { const int col = bj * FFN + f0; bb[bj] = *(const f32x4*)(cb + col);
; #pragma unroll
;                 for (int tp = 0; tp < 3; ++tp) w[bj][tp] = *(const f32x4*)(cw + tp * FFN2 + col); }
; #pragma unroll
;             for (int ai = 0; ai < 2; ++ai) {
;                 const int wb = (u.pm * 2 + ai) * 2 + wr;
;                 f32x4 p1[2], p2[2];
;                 p1[0] = p1[1] = p2[0] = p2[1] = (f32x4){0.f, 0.f, 0.f, 0.f};
; #pragma unroll
;                 for (int m = 0; m < 4; ++m) {
;                     f32x4 y[2];
; #pragma unroll
;                     for (int bj = 0; bj < 2; ++bj) {
;                         const f32x4 cur = acc[ai][bj][m][n]; f32x4 r1, r2;
; #pragma unroll
;                         for (int j = 0; j < 4; ++j) { r1[j] = dpp_ror<0x121>(cur[j]); r2[j] = dpp_ror<0x122>(cur[j]); }
;                         const f32x4 s1 = (fr >= 1) ? r1 : p1[bj], s2 = (fr >= 2) ? r2 : p2[bj];
;                         y[bj] = bb[bj] + w[bj][0] * s2 + w[bj][1] * s1 + w[bj][2] * cur;
;                         p1[bj] = r1; p2[bj] = r2;
;                         if (m == 0 && fr < 2) *(f32x4*)(hf + (size_t)(wb * 2 + fr) * FFN2 + bj * FFN + f0) = cur;
;                         if (m == 3 && fr >= 14) *(f32x4*)(hl + (size_t)(wb * 2 + fr - 14) * FFN2 + bj * FFN + f0) = cur;
;                     }
;                     u32x2 o; o.x = pg8::cvt_pk_bf16(silu_f(y[0][0]) * y[1][0], silu_f(y[0][1]) * y[1][1]); o.y = pg8::cvt_pk_bf16(silu_f(y[0][2]) * y[1][2], silu_f(y[0][3]) * y[1][3]);
;                     if (n == 0) held[ai][m] = o;
;                     else *(u32x4*)(act + (size_t)(wb * 64 + m * 16 + fr) * FFN + f0 - 4) = (u32x4){held[ai][m].x, held[ai][m].y, o.x, o.y};
.LBB0_1342:
	v_lshl_or_b32 v176, s46, 7, v193
	v_ashrrev_i32_e32 v177, 31, v176
	v_lshlrev_b64 v[112:113], 2, v[176:177]
	v_lshl_add_u64 v[140:141], s[24:25], 0, v[112:113]
	v_lshl_add_u64 v[132:133], s[26:27], 0, v[112:113]
	v_add_co_u32_e32 v112, vcc, 0x5000, v140
	global_load_dwordx4 v[120:123], v[132:133], off
	s_nop 0
	v_addc_co_u32_e32 v113, vcc, 0, v141, vcc
	v_add_co_u32_e32 v116, vcc, 0xb000, v140
	global_load_dwordx4 v[124:127], v[140:141], off
	s_nop 0
	global_load_dwordx4 v[112:115], v[112:113], off offset:2048
	v_addc_co_u32_e32 v117, vcc, 0, v141, vcc
	v_add_co_u32_e32 v180, vcc, s55, v132
	global_load_dwordx4 v[116:119], v[116:117], off
	s_nop 0
	v_addc_co_u32_e32 v181, vcc, 0, v133, vcc
	v_add_co_u32_e32 v182, vcc, s55, v140
	global_load_dwordx4 v[132:135], v[180:181], off offset:3072
	s_nop 0
	v_addc_co_u32_e32 v183, vcc, 0, v141, vcc
	v_add_co_u32_e32 v184, vcc, s59, v140
	s_lshl_b32 s37, s42, 2
	s_nop 0
	v_addc_co_u32_e32 v185, vcc, 0, v141, vcc
	v_add_co_u32_e32 v186, vcc, s68, v140
	global_load_dwordx4 v[144:147], v[182:183], off offset:3072
	global_load_dwordx4 v[136:139], v[184:185], off offset:1024
	v_addc_co_u32_e32 v187, vcc, 0, v141, vcc
	global_load_dwordx4 v[140:143], v[186:187], off offset:3072
	s_add_i32 s37, s37, s5
	s_lshl_b32 s3, s37, 1
	v_add_u32_e32 v178, s3, v190
	v_mad_i64_i32 v[178:179], s[42:43], v178, s69, 0
	v_lshl_add_u64 v[178:179], s[20:21], 0, v[178:179]
	v_mov_b32_dpp v205, v108 row_ror:1 row_mask:0xf bank_mask:0xf
	v_mov_b32_dpp v206, v108 row_ror:2 row_mask:0xf bank_mask:0xf
	v_mov_b32_dpp v208, v109 row_ror:1 row_mask:0xf bank_mask:0xf
	v_mov_b32_dpp v209, v109 row_ror:2 row_mask:0xf bank_mask:0xf
	v_mov_b32_dpp v211, v110 row_ror:1 row_mask:0xf bank_mask:0xf
	v_mov_b32_dpp v210, v110 row_ror:2 row_mask:0xf bank_mask:0xf
	v_mov_b32_dpp v213, v111 row_ror:1 row_mask:0xf bank_mask:0xf
	v_mov_b32_dpp v212, v111 row_ror:2 row_mask:0xf bank_mask:0xf
	v_lshl_add_u64 v[188:189], v[176:177], 2, v[178:179]
	s_and_saveexec_b64 s[42:43], s[10:11]
	s_cbranch_execz .LBB0_1344
	global_store_dwordx4 v[188:189], v[108:111], off
.LBB0_1344:
	s_or_b64 exec, exec, s[42:43]
	v_mov_b32_dpp v198, v156 row_ror:1 row_mask:0xf bank_mask:0xf
	v_mov_b32_dpp v199, v156 row_ror:2 row_mask:0xf bank_mask:0xf
	v_mov_b32_dpp v200, v157 row_ror:1 row_mask:0xf bank_mask:0xf
	v_mov_b32_dpp v201, v157 row_ror:2 row_mask:0xf bank_mask:0xf
	v_mov_b32_dpp v203, v158 row_ror:1 row_mask:0xf bank_mask:0xf
	v_mov_b32_dpp v202, v158 row_ror:2 row_mask:0xf bank_mask:0xf
	v_mov_b32_dpp v207, v159 row_ror:1 row_mask:0xf bank_mask:0xf
	v_mov_b32_dpp v204, v159 row_ror:2 row_mask:0xf bank_mask:0xf
	s_and_saveexec_b64 s[42:43], s[10:11]
	s_cbranch_execz .LBB0_1346
	v_add_co_u32_e32 v214, vcc, 0x2000, v188
	s_nop 1
	v_addc_co_u32_e32 v215, vcc, 0, v189, vcc
	global_store_dwordx4 v[214:215], v[156:159], off offset:3072
.LBB0_1346:
	s_or_b64 exec, exec, s[42:43]
	v_cndmask_b32_e64 v221, 0, v204, s[8:9]
	v_cndmask_b32_e64 v220, 0, v202, s[8:9]
	v_cndmask_b32_e64 v215, v207, 0, s[6:7]
	v_cndmask_b32_e64 v214, v203, 0, s[6:7]
	v_cndmask_b32_e64 v219, 0, v201, s[8:9]
	v_cndmask_b32_e64 v218, 0, v199, s[8:9]
	s_waitcnt vmcnt(0)
	v_pk_fma_f32 v[220:221], v[146:147], v[220:221], v[134:135]
	v_cndmask_b32_e64 v217, v200, 0, s[6:7]
	v_cndmask_b32_e64 v216, v198, 0, s[6:7]
	v_pk_fma_f32 v[218:219], v[144:145], v[218:219], v[132:133]
	v_pk_fma_f32 v[214:215], v[138:139], v[214:215], v[220:221]
	v_cndmask_b32_e64 v221, 0, v209, s[8:9]
	v_cndmask_b32_e64 v220, 0, v206, s[8:9]
	v_pk_fma_f32 v[216:217], v[136:137], v[216:217], v[218:219]
	v_cndmask_b32_e64 v219, v208, 0, s[6:7]
	v_cndmask_b32_e64 v218, v205, 0, s[6:7]
	v_pk_fma_f32 v[220:221], v[124:125], v[220:221], v[120:121]
	v_cndmask_b32_e64 v223, 0, v212, s[8:9]
	v_pk_fma_f32 v[218:219], v[112:113], v[218:219], v[220:221]
	v_cndmask_b32_e64 v222, 0, v210, s[8:9]
	v_pk_fma_f32 v[108:109], v[108:109], v[116:117], v[218:219]
	v_pk_fma_f32 v[158:159], v[158:159], v[142:143], v[214:215]
	v_mul_f32_e32 v218, 0xbfb8aa3b, v108
	v_exp_f32_e32 v218, v218
	v_pk_fma_f32 v[214:215], v[156:157], v[140:141], v[216:217]
	v_cndmask_b32_e64 v217, v213, 0, s[6:7]
	v_cndmask_b32_e64 v216, v211, 0, s[6:7]
	v_pk_fma_f32 v[222:223], v[126:127], v[222:223], v[122:123]
	v_mul_f32_e32 v219, 0xbfb8aa3b, v109
	v_pk_fma_f32 v[216:217], v[114:115], v[216:217], v[222:223]
	v_exp_f32_e32 v219, v219
	v_pk_fma_f32 v[216:217], v[110:111], v[118:119], v[216:217]
	v_add_f32_e32 v218, 1.0, v218
	v_mul_f32_e32 v110, 0xbfb8aa3b, v216
	v_rcp_f32_e32 v218, v218
	v_exp_f32_e32 v110, v110
	v_mul_f32_e32 v111, 0xbfb8aa3b, v217
	v_exp_f32_e32 v111, v111
	v_add_f32_e32 v219, 1.0, v219
	v_rcp_f32_e32 v219, v219
	v_mul_f32_e32 v108, v108, v218
	v_add_f32_e32 v110, 1.0, v110
	v_mul_f32_e32 v108, v108, v214
	v_rcp_f32_e32 v214, v110
	v_add_f32_e32 v110, 1.0, v111
	v_rcp_f32_e32 v111, v110
	v_mul_f32_e32 v109, v109, v219
	v_mul_f32_e32 v109, v109, v215
	v_cvt_pk_bf16_f32 v110, v108, v109
	v_mul_f32_e32 v108, v216, v214
	v_mul_f32_e32 v109, v217, v111
	v_mov_b32_dpp v215, v152 row_ror:2 row_mask:0xf bank_mask:0xf
	v_mov_b32_dpp v216, v153 row_ror:1 row_mask:0xf bank_mask:0xf
	v_mov_b32_dpp v217, v153 row_ror:2 row_mask:0xf bank_mask:0xf
	v_mul_f32_e32 v108, v108, v158
	v_mul_f32_e32 v109, v109, v159
	v_mov_b32_dpp v214, v152 row_ror:1 row_mask:0xf bank_mask:0xf
	v_mov_b32_dpp v218, v154 row_ror:1 row_mask:0xf bank_mask:0xf
	v_mov_b32_dpp v219, v154 row_ror:2 row_mask:0xf bank_mask:0xf
	v_mov_b32_dpp v221, v155 row_ror:2 row_mask:0xf bank_mask:0xf
	v_cndmask_b32_e64 v159, v216, v208, s[6:7]
	v_cndmask_b32_e64 v209, v209, v217, s[8:9]
; __device__ __forceinline__ unsigned cvt_pk_bf16(float lo, float hi) { unsigned r; asm volatile("v_cvt_pk_bf16_f32 %0, %1, %2" : "=v"(r) : "v"(lo), "v"(hi)); return r; }
; template <int CTRL> __device__ __forceinline__ float dpp_ror(float v) { return __builtin_bit_cast(float, __builtin_amdgcn_update_dpp(0, __builtin_bit_cast(int, v), CTRL, 0xf, 0xf, false)); }
; __device__ __forceinline__ float silu_f(float g) { return g * __builtin_amdgcn_rcpf(1.f + __builtin_amdgcn_exp2f(-g * LOG2E)); }
;     __device__ __forceinline__ void operator()(const f32x4 (&acc)[2][2][4][2], const pg8::Unit& u, int wr, int wc, int fr, int fq) const {
;     ...
;                 for (int m = 0; m < 4; ++m) {
;                     f32x4 y[2];
; #pragma unroll
;                     for (int bj = 0; bj < 2; ++bj) {
;                         const f32x4 cur = acc[ai][bj][m][n]; f32x4 r1, r2;
; #pragma unroll
;                         for (int j = 0; j < 4; ++j) { r1[j] = dpp_ror<0x121>(cur[j]); r2[j] = dpp_ror<0x122>(cur[j]); }
;                         const f32x4 s1 = (fr >= 1) ? r1 : p1[bj], s2 = (fr >= 2) ? r2 : p2[bj];
;                         y[bj] = bb[bj] + w[bj][0] * s2 + w[bj][1] * s1 + w[bj][2] * cur;
;                         p1[bj] = r1; p2[bj] = r2;
;                         if (m == 0 && fr < 2) *(f32x4*)(hf + (size_t)(wb * 2 + fr) * FFN2 + bj * FFN + f0) = cur;
;                         if (m == 3 && fr >= 14) *(f32x4*)(hl + (size_t)(wb * 2 + fr - 14) * FFN2 + bj * FFN + f0) = cur;
;                     }
;                     u32x2 o; o.x = pg8::cvt_pk_bf16(silu_f(y[0][0]) * y[1][0], silu_f(y[0][1]) * y[1][1]); o.y = pg8::cvt_pk_bf16(silu_f(y[0][2]) * y[1][2], silu_f(y[0][3]) * y[1][3]);
;                     if (n == 0) held[ai][m] = o;
;                     else *(u32x4*)(act + (size_t)(wb * 64 + m * 16 + fr) * FFN + f0 - 4) = (u32x4){held[ai][m].x, held[ai][m].y, o.x, o.y};
	v_cndmask_b32_e64 v208, v206, v215, s[8:9]
	v_cvt_pk_bf16_f32 v111, v108, v109
	v_mov_b32_dpp v220, v155 row_ror:1 row_mask:0xf bank_mask:0xf
	v_cndmask_b32_e64 v108, v218, v211, s[6:7]
	v_cndmask_b32_e64 v158, v214, v205, s[6:7]
	v_cndmask_b32_e64 v211, v212, v221, s[8:9]
	v_cndmask_b32_e64 v210, v210, v219, s[8:9]
	v_pk_fma_f32 v[208:209], v[124:125], v[208:209], v[120:121]
	v_cndmask_b32_e64 v109, v220, v213, s[6:7]
	v_pk_fma_f32 v[210:211], v[126:127], v[210:211], v[122:123]
	v_pk_fma_f32 v[158:159], v[112:113], v[158:159], v[208:209]
	v_pk_fma_f32 v[108:109], v[114:115], v[108:109], v[210:211]
	v_mov_b32_dpp v206, v148 row_ror:1 row_mask:0xf bank_mask:0xf
	v_mov_b32_dpp v208, v148 row_ror:2 row_mask:0xf bank_mask:0xf
	v_mov_b32_dpp v209, v149 row_ror:1 row_mask:0xf bank_mask:0xf
	v_mov_b32_dpp v212, v150 row_ror:2 row_mask:0xf bank_mask:0xf
	v_mov_b32_dpp v213, v151 row_ror:2 row_mask:0xf bank_mask:0xf
	v_pk_fma_f32 v[154:155], v[154:155], v[118:119], v[108:109]
	v_pk_fma_f32 v[108:109], v[152:153], v[116:117], v[158:159]
	v_mov_b32_dpp v211, v150 row_ror:1 row_mask:0xf bank_mask:0xf
	v_mov_b32_dpp v205, v151 row_ror:1 row_mask:0xf bank_mask:0xf
	v_cndmask_b32_e64 v159, v209, v200, s[6:7]
	v_cndmask_b32_e64 v158, v206, v198, s[6:7]
	v_cndmask_b32_e64 v200, v199, v208, s[8:9]
	v_cndmask_b32_e64 v199, v204, v213, s[8:9]
	v_cndmask_b32_e64 v198, v202, v212, s[8:9]
	v_cndmask_b32_e64 v153, v205, v207, s[6:7]
	v_cndmask_b32_e64 v152, v211, v203, s[6:7]
	v_pk_fma_f32 v[198:199], v[146:147], v[198:199], v[134:135]
	v_pk_fma_f32 v[152:153], v[138:139], v[152:153], v[198:199]
	v_mul_f32_e32 v198, 0xbfb8aa3b, v108
	v_exp_f32_e32 v198, v198
	v_mul_f32_e32 v199, 0xbfb8aa3b, v109
	v_pk_fma_f32 v[150:151], v[150:151], v[142:143], v[152:153]
	v_mov_b32_dpp v210, v149 row_ror:2 row_mask:0xf bank_mask:0xf
	v_add_f32_e32 v152, 1.0, v198
	v_exp_f32_e32 v199, v199
	v_rcp_f32_e32 v152, v152
	v_cndmask_b32_e64 v201, v201, v210, s[8:9]
	v_pk_fma_f32 v[200:201], v[144:145], v[200:201], v[132:133]
	v_add_f32_e32 v153, 1.0, v199
	v_pk_fma_f32 v[158:159], v[136:137], v[158:159], v[200:201]
	v_mul_f32_e32 v108, v108, v152
	v_pk_fma_f32 v[148:149], v[148:149], v[140:141], v[158:159]
	v_rcp_f32_e32 v153, v153
	v_mul_f32_e32 v108, v108, v148
	v_mul_f32_e32 v148, 0xbfb8aa3b, v154
	v_mul_f32_e32 v152, 0xbfb8aa3b, v155
	v_exp_f32_e32 v148, v148
	v_exp_f32_e32 v152, v152
	v_mul_f32_e32 v109, v109, v153
	v_mul_f32_e32 v109, v109, v149
	v_add_f32_e32 v148, 1.0, v148
	v_add_f32_e32 v149, 1.0, v152
	v_rcp_f32_e32 v148, v148
	v_rcp_f32_e32 v149, v149
	v_cvt_pk_bf16_f32 v108, v108, v109
	v_mul_f32_e32 v109, v154, v148
	v_mul_f32_e32 v148, v155, v149
	v_mul_f32_e32 v148, v148, v151
	v_mul_f32_e32 v109, v109, v150
	v_mov_b32_dpp v151, v128 row_ror:2 row_mask:0xf bank_mask:0xf
	v_mov_b32_dpp v153, v129 row_ror:2 row_mask:0xf bank_mask:0xf
	v_mov_b32_dpp v158, v130 row_ror:2 row_mask:0xf bank_mask:0xf
	v_mov_b32_dpp v198, v131 row_ror:2 row_mask:0xf bank_mask:0xf
	v_mov_b32_dpp v150, v128 row_ror:1 row_mask:0xf bank_mask:0xf
	v_mov_b32_dpp v152, v129 row_ror:1 row_mask:0xf bank_mask:0xf
	v_mov_b32_dpp v159, v130 row_ror:1 row_mask:0xf bank_mask:0xf
	v_mov_b32_dpp v199, v131 row_ror:1 row_mask:0xf bank_mask:0xf
	v_cndmask_b32_e64 v201, v217, v153, s[8:9]
	v_cndmask_b32_e64 v200, v215, v151, s[8:9]
	v_cndmask_b32_e64 v203, v221, v198, s[8:9]
	v_cndmask_b32_e64 v202, v219, v158, s[8:9]
	v_cvt_pk_bf16_f32 v109, v109, v148
	v_cndmask_b32_e64 v149, v199, v220, s[6:7]
	v_cndmask_b32_e64 v148, v159, v218, s[6:7]
	v_cndmask_b32_e64 v155, v152, v216, s[6:7]
	v_cndmask_b32_e64 v154, v150, v214, s[6:7]
	v_pk_fma_f32 v[202:203], v[126:127], v[202:203], v[122:123]
	v_pk_fma_f32 v[200:201], v[124:125], v[200:201], v[120:121]
	v_pk_fma_f32 v[148:149], v[114:115], v[148:149], v[202:203]
	v_pk_fma_f32 v[154:155], v[112:113], v[154:155], v[200:201]
	v_pk_fma_f32 v[148:149], v[130:131], v[118:119], v[148:149]
	v_pk_fma_f32 v[154:155], v[128:129], v[116:117], v[154:155]
	v_mov_b32_dpp v129, v104 row_ror:2 row_mask:0xf bank_mask:0xf
	v_mov_b32_dpp v130, v105 row_ror:1 row_mask:0xf bank_mask:0xf
	v_mov_b32_dpp v131, v105 row_ror:2 row_mask:0xf bank_mask:0xf
	v_mov_b32_dpp v128, v104 row_ror:1 row_mask:0xf bank_mask:0xf
	v_cndmask_b32_e64 v207, v130, v209, s[6:7]
	v_cndmask_b32_e64 v209, v210, v131, s[8:9]
	v_cndmask_b32_e64 v208, v208, v129, s[8:9]
	v_cndmask_b32_e64 v206, v128, v206, s[6:7]
	v_pk_fma_f32 v[208:209], v[144:145], v[208:209], v[132:133]
	v_pk_fma_f32 v[206:207], v[136:137], v[206:207], v[208:209]
	v_mul_f32_e32 v208, 0xbfb8aa3b, v154
	v_mov_b32_dpp v201, v106 row_ror:1 row_mask:0xf bank_mask:0xf
	v_mov_b32_dpp v200, v106 row_ror:2 row_mask:0xf bank_mask:0xf
	v_mov_b32_dpp v202, v107 row_ror:2 row_mask:0xf bank_mask:0xf
	v_exp_f32_e32 v208, v208
	v_mul_f32_e32 v209, 0xbfb8aa3b, v155
	v_mov_b32_dpp v203, v107 row_ror:1 row_mask:0xf bank_mask:0xf
	v_cndmask_b32_e64 v204, v201, v211, s[6:7]
	v_cndmask_b32_e64 v211, v213, v202, s[8:9]
	v_cndmask_b32_e64 v210, v212, v200, s[8:9]
	v_exp_f32_e32 v209, v209
	v_cndmask_b32_e64 v205, v203, v205, s[6:7]
	v_pk_fma_f32 v[210:211], v[146:147], v[210:211], v[134:135]
	v_pk_fma_f32 v[104:105], v[104:105], v[140:141], v[206:207]
	v_pk_fma_f32 v[204:205], v[138:139], v[204:205], v[210:211]
	v_add_u32_e32 v156, s3, v192
	v_pk_fma_f32 v[106:107], v[106:107], v[142:143], v[204:205]
	v_add_f32_e32 v204, 1.0, v208
	v_rcp_f32_e32 v204, v204
	v_add_f32_e32 v205, 1.0, v209
	v_rcp_f32_e32 v205, v205
	v_mad_i64_i32 v[156:157], s[42:43], v156, s69, 0
	v_mul_f32_e32 v154, v154, v204
	v_mul_f32_e32 v104, v154, v104
	v_mul_f32_e32 v154, v155, v205
	v_mul_f32_e32 v155, 0xbfb8aa3b, v148
	v_exp_f32_e32 v155, v155
	v_mul_f32_e32 v204, 0xbfb8aa3b, v149
	v_exp_f32_e32 v204, v204
	v_mul_f32_e32 v105, v154, v105
	v_add_f32_e32 v154, 1.0, v155
	v_rcp_f32_e32 v154, v154
	v_add_f32_e32 v155, 1.0, v204
	v_rcp_f32_e32 v155, v155
	v_cvt_pk_bf16_f32 v104, v104, v105
	v_mul_f32_e32 v105, v148, v154
	v_mul_f32_e32 v105, v105, v106
	v_mul_f32_e32 v106, v149, v155
	v_mul_f32_e32 v106, v106, v107
	v_cvt_pk_bf16_f32 v105, v105, v106
	v_lshl_add_u64 v[148:149], s[22:23], 0, v[156:157]
	v_mov_b32_dpp v106, v96 row_ror:1 row_mask:0xf bank_mask:0xf
	v_mov_b32_dpp v107, v96 row_ror:2 row_mask:0xf bank_mask:0xf
	v_mov_b32_dpp v204, v97 row_ror:1 row_mask:0xf bank_mask:0xf
	v_mov_b32_dpp v205, v97 row_ror:2 row_mask:0xf bank_mask:0xf
	v_mov_b32_dpp v207, v98 row_ror:1 row_mask:0xf bank_mask:0xf
	v_mov_b32_dpp v206, v98 row_ror:2 row_mask:0xf bank_mask:0xf
	v_mov_b32_dpp v209, v99 row_ror:1 row_mask:0xf bank_mask:0xf
	v_mov_b32_dpp v208, v99 row_ror:2 row_mask:0xf bank_mask:0xf
	v_lshl_add_u64 v[154:155], v[176:177], 2, v[148:149]
	s_and_saveexec_b64 s[42:43], s[12:13]
	s_cbranch_execz .LBB0_1348
	global_store_dwordx4 v[154:155], v[96:99], off
; __device__ __forceinline__ unsigned cvt_pk_bf16(float lo, float hi) { unsigned r; asm volatile("v_cvt_pk_bf16_f32 %0, %1, %2" : "=v"(r) : "v"(lo), "v"(hi)); return r; }
; template <int CTRL> __device__ __forceinline__ float dpp_ror(float v) { return __builtin_bit_cast(float, __builtin_amdgcn_update_dpp(0, __builtin_bit_cast(int, v), CTRL, 0xf, 0xf, false)); }
; __device__ __forceinline__ float silu_f(float g) { return g * __builtin_amdgcn_rcpf(1.f + __builtin_amdgcn_exp2f(-g * LOG2E)); }
;     __device__ __forceinline__ void operator()(const f32x4 (&acc)[2][2][4][2], const pg8::Unit& u, int wr, int wc, int fr, int fq) const {
;     ...
;                 for (int m = 0; m < 4; ++m) {
;                     f32x4 y[2];
; #pragma unroll
;                     for (int bj = 0; bj < 2; ++bj) {
;                         const f32x4 cur = acc[ai][bj][m][n]; f32x4 r1, r2;
; #pragma unroll
;                         for (int j = 0; j < 4; ++j) { r1[j] = dpp_ror<0x121>(cur[j]); r2[j] = dpp_ror<0x122>(cur[j]); }
;                         const f32x4 s1 = (fr >= 1) ? r1 : p1[bj], s2 = (fr >= 2) ? r2 : p2[bj];
;                         y[bj] = bb[bj] + w[bj][0] * s2 + w[bj][1] * s1 + w[bj][2] * cur;
;                         p1[bj] = r1; p2[bj] = r2;
;                         if (m == 0 && fr < 2) *(f32x4*)(hf + (size_t)(wb * 2 + fr) * FFN2 + bj * FFN + f0) = cur;
;                         if (m == 3 && fr >= 14) *(f32x4*)(hl + (size_t)(wb * 2 + fr - 14) * FFN2 + bj * FFN + f0) = cur;
;                     }
;                     u32x2 o; o.x = pg8::cvt_pk_bf16(silu_f(y[0][0]) * y[1][0], silu_f(y[0][1]) * y[1][1]); o.y = pg8::cvt_pk_bf16(silu_f(y[0][2]) * y[1][2], silu_f(y[0][3]) * y[1][3]);
;                     if (n == 0) held[ai][m] = o;
;                     else *(u32x4*)(act + (size_t)(wb * 64 + m * 16 + fr) * FFN + f0 - 4) = (u32x4){held[ai][m].x, held[ai][m].y, o.x, o.y};
.LBB0_1348:
	s_or_b64 exec, exec, s[42:43]
	v_mov_b32_dpp v156, v100 row_ror:1 row_mask:0xf bank_mask:0xf
	v_mov_b32_dpp v157, v100 row_ror:2 row_mask:0xf bank_mask:0xf
	v_mov_b32_dpp v210, v101 row_ror:1 row_mask:0xf bank_mask:0xf
	v_mov_b32_dpp v211, v101 row_ror:2 row_mask:0xf bank_mask:0xf
	v_mov_b32_dpp v213, v102 row_ror:1 row_mask:0xf bank_mask:0xf
	v_mov_b32_dpp v212, v102 row_ror:2 row_mask:0xf bank_mask:0xf
	v_mov_b32_dpp v215, v103 row_ror:1 row_mask:0xf bank_mask:0xf
	v_mov_b32_dpp v214, v103 row_ror:2 row_mask:0xf bank_mask:0xf
	s_and_saveexec_b64 s[42:43], s[12:13]
	s_cbranch_execz .LBB0_1350
	v_add_co_u32_e32 v216, vcc, 0x2000, v154
	s_nop 1
	v_addc_co_u32_e32 v217, vcc, 0, v155, vcc
	global_store_dwordx4 v[216:217], v[100:103], off offset:3072
.LBB0_1350:
	s_or_b64 exec, exec, s[42:43]
	v_cndmask_b32_e64 v219, v210, v130, s[6:7]
	v_cndmask_b32_e64 v131, v131, v211, s[8:9]
	v_cndmask_b32_e64 v130, v129, v157, s[8:9]
	v_cndmask_b32_e64 v218, v156, v128, s[6:7]
	v_pk_fma_f32 v[130:131], v[144:145], v[130:131], v[132:133]
	v_cndmask_b32_e64 v153, v153, v205, s[8:9]
	v_pk_fma_f32 v[130:131], v[136:137], v[218:219], v[130:131]
	v_cndmask_b32_e64 v129, v202, v214, s[8:9]
	v_pk_fma_f32 v[100:101], v[100:101], v[140:141], v[130:131]
	v_cndmask_b32_e64 v131, v204, v152, s[6:7]
	v_cndmask_b32_e64 v152, v151, v107, s[8:9]
	v_cndmask_b32_e64 v130, v106, v150, s[6:7]
	v_pk_fma_f32 v[150:151], v[124:125], v[152:153], v[120:121]
	v_cndmask_b32_e64 v128, v200, v212, s[8:9]
	v_pk_fma_f32 v[130:131], v[112:113], v[130:131], v[150:151]
	v_cndmask_b32_e64 v217, v215, v203, s[6:7]
	v_pk_fma_f32 v[96:97], v[96:97], v[116:117], v[130:131]
	v_cndmask_b32_e64 v216, v213, v201, s[6:7]
	v_mul_f32_e32 v130, 0xbfb8aa3b, v96
	v_exp_f32_e32 v130, v130
	v_pk_fma_f32 v[128:129], v[146:147], v[128:129], v[134:135]
	v_cndmask_b32_e64 v107, v198, v208, s[8:9]
	v_pk_fma_f32 v[128:129], v[138:139], v[216:217], v[128:129]
	v_cndmask_b32_e64 v106, v158, v206, s[8:9]
	v_pk_fma_f32 v[102:103], v[102:103], v[142:143], v[128:129]
	v_cndmask_b32_e64 v129, v209, v199, s[6:7]
	v_cndmask_b32_e64 v128, v207, v159, s[6:7]
	v_pk_fma_f32 v[106:107], v[126:127], v[106:107], v[122:123]
	v_mul_f32_e32 v131, 0xbfb8aa3b, v97
	v_pk_fma_f32 v[106:107], v[114:115], v[128:129], v[106:107]
	v_add_f32_e32 v128, 1.0, v130
	v_exp_f32_e32 v131, v131
	v_rcp_f32_e32 v128, v128
	v_pk_fma_f32 v[98:99], v[98:99], v[118:119], v[106:107]
	s_add_i32 s35, s37, 2
	v_add_f32_e32 v129, 1.0, v131
	v_mul_f32_e32 v96, v96, v128
	v_rcp_f32_e32 v129, v129
	v_mul_f32_e32 v96, v96, v100
	v_mul_f32_e32 v100, 0xbfb8aa3b, v98
	v_mul_f32_e32 v106, 0xbfb8aa3b, v99
	v_exp_f32_e32 v100, v100
	v_exp_f32_e32 v106, v106
	v_mul_f32_e32 v97, v97, v129
	v_mul_f32_e32 v97, v97, v101
	v_add_f32_e32 v100, 1.0, v100
	v_add_f32_e32 v101, 1.0, v106
	v_rcp_f32_e32 v100, v100
	v_rcp_f32_e32 v101, v101
	v_cvt_pk_bf16_f32 v96, v96, v97
	s_lshl_b32 s3, s35, 1
	v_mul_f32_e32 v97, v98, v100
	v_mul_f32_e32 v98, v99, v101
	v_mul_f32_e32 v97, v97, v102
	v_mul_f32_e32 v98, v98, v103
	v_cvt_pk_bf16_f32 v97, v97, v98
	v_add_u32_e32 v98, s3, v190
	v_mad_i64_i32 v[98:99], s[42:43], v98, s69, 0
	v_lshl_add_u64 v[130:131], s[20:21], 0, v[98:99]
	v_mov_b32_dpp v107, v88 row_ror:1 row_mask:0xf bank_mask:0xf
	v_mov_b32_dpp v128, v88 row_ror:2 row_mask:0xf bank_mask:0xf
	v_mov_b32_dpp v150, v89 row_ror:1 row_mask:0xf bank_mask:0xf
	v_mov_b32_dpp v151, v89 row_ror:2 row_mask:0xf bank_mask:0xf
	v_mov_b32_dpp v157, v90 row_ror:1 row_mask:0xf bank_mask:0xf
	v_mov_b32_dpp v156, v90 row_ror:2 row_mask:0xf bank_mask:0xf
	v_mov_b32_dpp v159, v91 row_ror:1 row_mask:0xf bank_mask:0xf
	v_mov_b32_dpp v158, v91 row_ror:2 row_mask:0xf bank_mask:0xf
	v_lshl_add_u64 v[152:153], v[176:177], 2, v[130:131]
	s_and_saveexec_b64 s[42:43], s[10:11]
	s_cbranch_execz .LBB0_1352
	global_store_dwordx4 v[152:153], v[88:91], off
.LBB0_1352:
	s_or_b64 exec, exec, s[42:43]
	v_mov_b32_dpp v98, v92 row_ror:1 row_mask:0xf bank_mask:0xf
	v_mov_b32_dpp v99, v92 row_ror:2 row_mask:0xf bank_mask:0xf
	v_mov_b32_dpp v100, v93 row_ror:1 row_mask:0xf bank_mask:0xf
	v_mov_b32_dpp v101, v93 row_ror:2 row_mask:0xf bank_mask:0xf
	v_mov_b32_dpp v103, v94 row_ror:1 row_mask:0xf bank_mask:0xf
	v_mov_b32_dpp v102, v94 row_ror:2 row_mask:0xf bank_mask:0xf
	v_mov_b32_dpp v129, v95 row_ror:1 row_mask:0xf bank_mask:0xf
	v_mov_b32_dpp v106, v95 row_ror:2 row_mask:0xf bank_mask:0xf
	s_and_saveexec_b64 s[42:43], s[10:11]
	s_cbranch_execz .LBB0_1354
	v_add_co_u32_e32 v198, vcc, 0x2000, v152
	s_nop 1
	v_addc_co_u32_e32 v199, vcc, 0, v153, vcc
	global_store_dwordx4 v[198:199], v[92:95], off offset:3072
; __device__ __forceinline__ unsigned cvt_pk_bf16(float lo, float hi) { unsigned r; asm volatile("v_cvt_pk_bf16_f32 %0, %1, %2" : "=v"(r) : "v"(lo), "v"(hi)); return r; }
; template <int CTRL> __device__ __forceinline__ float dpp_ror(float v) { return __builtin_bit_cast(float, __builtin_amdgcn_update_dpp(0, __builtin_bit_cast(int, v), CTRL, 0xf, 0xf, false)); }
; __device__ __forceinline__ float silu_f(float g) { return g * __builtin_amdgcn_rcpf(1.f + __builtin_amdgcn_exp2f(-g * LOG2E)); }
;     __device__ __forceinline__ void operator()(const f32x4 (&acc)[2][2][4][2], const pg8::Unit& u, int wr, int wc, int fr, int fq) const {
;     ...
;                 for (int m = 0; m < 4; ++m) {
;                     f32x4 y[2];
; #pragma unroll
;                     for (int bj = 0; bj < 2; ++bj) {
;                         const f32x4 cur = acc[ai][bj][m][n]; f32x4 r1, r2;
; #pragma unroll
;                         for (int j = 0; j < 4; ++j) { r1[j] = dpp_ror<0x121>(cur[j]); r2[j] = dpp_ror<0x122>(cur[j]); }
;                         const f32x4 s1 = (fr >= 1) ? r1 : p1[bj], s2 = (fr >= 2) ? r2 : p2[bj];
;                         y[bj] = bb[bj] + w[bj][0] * s2 + w[bj][1] * s1 + w[bj][2] * cur;
;                         p1[bj] = r1; p2[bj] = r2;
;                         if (m == 0 && fr < 2) *(f32x4*)(hf + (size_t)(wb * 2 + fr) * FFN2 + bj * FFN + f0) = cur;
;                         if (m == 3 && fr >= 14) *(f32x4*)(hl + (size_t)(wb * 2 + fr - 14) * FFN2 + bj * FFN + f0) = cur;
;                     }
;                     u32x2 o; o.x = pg8::cvt_pk_bf16(silu_f(y[0][0]) * y[1][0], silu_f(y[0][1]) * y[1][1]); o.y = pg8::cvt_pk_bf16(silu_f(y[0][2]) * y[1][2], silu_f(y[0][3]) * y[1][3]);
;                     if (n == 0) held[ai][m] = o;
;                     else *(u32x4*)(act + (size_t)(wb * 64 + m * 16 + fr) * FFN + f0 - 4) = (u32x4){held[ai][m].x, held[ai][m].y, o.x, o.y};
.LBB0_1354:
	s_or_b64 exec, exec, s[42:43]
	v_cndmask_b32_e64 v205, 0, v106, s[8:9]
	v_cndmask_b32_e64 v204, 0, v102, s[8:9]
	v_cndmask_b32_e64 v199, v129, 0, s[6:7]
	v_cndmask_b32_e64 v198, v103, 0, s[6:7]
	v_cndmask_b32_e64 v203, 0, v101, s[8:9]
	v_cndmask_b32_e64 v202, 0, v99, s[8:9]
	v_pk_fma_f32 v[204:205], v[146:147], v[204:205], v[134:135]
	v_cndmask_b32_e64 v201, v100, 0, s[6:7]
	v_cndmask_b32_e64 v200, v98, 0, s[6:7]
	v_pk_fma_f32 v[202:203], v[144:145], v[202:203], v[132:133]
	v_pk_fma_f32 v[198:199], v[138:139], v[198:199], v[204:205]
	v_cndmask_b32_e64 v205, 0, v151, s[8:9]
	v_cndmask_b32_e64 v204, 0, v128, s[8:9]
	v_pk_fma_f32 v[200:201], v[136:137], v[200:201], v[202:203]
	v_cndmask_b32_e64 v203, v150, 0, s[6:7]
	v_cndmask_b32_e64 v202, v107, 0, s[6:7]
	v_pk_fma_f32 v[204:205], v[124:125], v[204:205], v[120:121]
	v_cndmask_b32_e64 v207, 0, v158, s[8:9]
	v_pk_fma_f32 v[202:203], v[112:113], v[202:203], v[204:205]
	v_cndmask_b32_e64 v206, 0, v156, s[8:9]
	v_pk_fma_f32 v[88:89], v[88:89], v[116:117], v[202:203]
	v_pk_fma_f32 v[94:95], v[94:95], v[142:143], v[198:199]
	v_mul_f32_e32 v202, 0xbfb8aa3b, v88
	v_exp_f32_e32 v202, v202
	v_mul_f32_e32 v203, 0xbfb8aa3b, v89
	v_exp_f32_e32 v203, v203
	v_pk_fma_f32 v[198:199], v[92:93], v[140:141], v[200:201]
	v_add_f32_e32 v202, 1.0, v202
	v_rcp_f32_e32 v202, v202
	v_cndmask_b32_e64 v201, v159, 0, s[6:7]
	v_cndmask_b32_e64 v200, v157, 0, s[6:7]
	v_pk_fma_f32 v[206:207], v[126:127], v[206:207], v[122:123]
	v_add_f32_e32 v203, 1.0, v203
	v_pk_fma_f32 v[200:201], v[114:115], v[200:201], v[206:207]
	v_mul_f32_e32 v88, v88, v202
	v_pk_fma_f32 v[90:91], v[90:91], v[118:119], v[200:201]
	v_rcp_f32_e32 v203, v203
	v_mul_f32_e32 v88, v88, v198
	v_mul_f32_e32 v198, 0xbfb8aa3b, v90
	v_mul_f32_e32 v200, 0xbfb8aa3b, v91
	v_exp_f32_e32 v198, v198
	v_exp_f32_e32 v200, v200
	v_mul_f32_e32 v89, v89, v203
	v_mul_f32_e32 v89, v89, v199
	v_add_f32_e32 v198, 1.0, v198
	v_add_f32_e32 v199, 1.0, v200
	v_rcp_f32_e32 v198, v198
	v_rcp_f32_e32 v199, v199
	v_cvt_pk_bf16_f32 v88, v88, v89
	v_mul_f32_e32 v89, v90, v198
	v_mul_f32_e32 v90, v91, v199
	v_mov_b32_dpp v199, v84 row_ror:2 row_mask:0xf bank_mask:0xf
	v_mov_b32_dpp v200, v85 row_ror:1 row_mask:0xf bank_mask:0xf
	v_mov_b32_dpp v201, v85 row_ror:2 row_mask:0xf bank_mask:0xf
	v_mul_f32_e32 v89, v89, v94
	v_mul_f32_e32 v90, v90, v95
	v_mov_b32_dpp v198, v84 row_ror:1 row_mask:0xf bank_mask:0xf
	v_mov_b32_dpp v202, v86 row_ror:1 row_mask:0xf bank_mask:0xf
	v_mov_b32_dpp v203, v86 row_ror:2 row_mask:0xf bank_mask:0xf
	v_mov_b32_dpp v205, v87 row_ror:2 row_mask:0xf bank_mask:0xf
	v_cndmask_b32_e64 v95, v200, v150, s[6:7]
	v_cndmask_b32_e64 v151, v151, v201, s[8:9]
	v_cndmask_b32_e64 v150, v128, v199, s[8:9]
	v_cvt_pk_bf16_f32 v89, v89, v90
	v_mov_b32_dpp v204, v87 row_ror:1 row_mask:0xf bank_mask:0xf
	v_cndmask_b32_e64 v90, v202, v157, s[6:7]
	v_cndmask_b32_e64 v94, v198, v107, s[6:7]
	v_cndmask_b32_e64 v157, v158, v205, s[8:9]
	v_cndmask_b32_e64 v156, v156, v203, s[8:9]
	v_pk_fma_f32 v[150:151], v[124:125], v[150:151], v[120:121]
	v_cndmask_b32_e64 v91, v204, v159, s[6:7]
	v_pk_fma_f32 v[156:157], v[126:127], v[156:157], v[122:123]
	v_pk_fma_f32 v[94:95], v[112:113], v[94:95], v[150:151]
	v_pk_fma_f32 v[90:91], v[114:115], v[90:91], v[156:157]
	v_mov_b32_dpp v128, v80 row_ror:1 row_mask:0xf bank_mask:0xf
	v_mov_b32_dpp v150, v80 row_ror:2 row_mask:0xf bank_mask:0xf
	v_mov_b32_dpp v151, v81 row_ror:1 row_mask:0xf bank_mask:0xf
	v_mov_b32_dpp v158, v82 row_ror:2 row_mask:0xf bank_mask:0xf
	v_mov_b32_dpp v159, v83 row_ror:2 row_mask:0xf bank_mask:0xf
	v_pk_fma_f32 v[84:85], v[84:85], v[116:117], v[94:95]
	v_mov_b32_dpp v157, v82 row_ror:1 row_mask:0xf bank_mask:0xf
	v_mov_b32_dpp v107, v83 row_ror:1 row_mask:0xf bank_mask:0xf
	v_cndmask_b32_e64 v95, v151, v100, s[6:7]
	v_cndmask_b32_e64 v94, v128, v98, s[6:7]
	v_cndmask_b32_e64 v100, v99, v150, s[8:9]
	v_cndmask_b32_e64 v99, v106, v159, s[8:9]
	v_cndmask_b32_e64 v98, v102, v158, s[8:9]
	v_pk_fma_f32 v[86:87], v[86:87], v[118:119], v[90:91]
	v_cndmask_b32_e64 v91, v107, v129, s[6:7]
	v_cndmask_b32_e64 v90, v157, v103, s[6:7]
	v_pk_fma_f32 v[98:99], v[146:147], v[98:99], v[134:135]
	v_pk_fma_f32 v[90:91], v[138:139], v[90:91], v[98:99]
	v_mul_f32_e32 v98, 0xbfb8aa3b, v84
	v_exp_f32_e32 v98, v98
	v_mul_f32_e32 v99, 0xbfb8aa3b, v85
	v_exp_f32_e32 v99, v99
	v_pk_fma_f32 v[82:83], v[82:83], v[142:143], v[90:91]
	v_add_f32_e32 v90, 1.0, v98
	v_mov_b32_dpp v156, v81 row_ror:2 row_mask:0xf bank_mask:0xf
	v_rcp_f32_e32 v90, v90
	v_add_f32_e32 v91, 1.0, v99
	v_cndmask_b32_e64 v101, v101, v156, s[8:9]
	v_rcp_f32_e32 v91, v91
	v_pk_fma_f32 v[100:101], v[144:145], v[100:101], v[132:133]
	v_mul_f32_e32 v84, v84, v90
	v_pk_fma_f32 v[94:95], v[136:137], v[94:95], v[100:101]
	v_mul_f32_e32 v90, 0xbfb8aa3b, v87
	v_pk_fma_f32 v[80:81], v[80:81], v[140:141], v[94:95]
	v_exp_f32_e32 v90, v90
	v_mul_f32_e32 v80, v84, v80
	v_mul_f32_e32 v84, v85, v91
	v_mul_f32_e32 v85, 0xbfb8aa3b, v86
	v_exp_f32_e32 v85, v85
	v_mul_f32_e32 v81, v84, v81
	v_cvt_pk_bf16_f32 v80, v80, v81
	v_add_f32_e32 v84, 1.0, v85
	v_rcp_f32_e32 v84, v84
	v_add_f32_e32 v85, 1.0, v90
	v_rcp_f32_e32 v85, v85
	v_mul_f32_e32 v81, v86, v84
	v_mul_f32_e32 v81, v81, v82
	v_mul_f32_e32 v82, v87, v85
	v_mul_f32_e32 v82, v82, v83
	v_cvt_pk_bf16_f32 v81, v81, v82
	v_mov_b32_dpp v83, v76 row_ror:2 row_mask:0xf bank_mask:0xf
	v_mov_b32_dpp v85, v77 row_ror:2 row_mask:0xf bank_mask:0xf
	v_mov_b32_dpp v86, v78 row_ror:2 row_mask:0xf bank_mask:0xf
	v_mov_b32_dpp v90, v79 row_ror:2 row_mask:0xf bank_mask:0xf
	v_mov_b32_dpp v82, v76 row_ror:1 row_mask:0xf bank_mask:0xf
; __device__ __forceinline__ unsigned cvt_pk_bf16(float lo, float hi) { unsigned r; asm volatile("v_cvt_pk_bf16_f32 %0, %1, %2" : "=v"(r) : "v"(lo), "v"(hi)); return r; }
; template <int CTRL> __device__ __forceinline__ float dpp_ror(float v) { return __builtin_bit_cast(float, __builtin_amdgcn_update_dpp(0, __builtin_bit_cast(int, v), CTRL, 0xf, 0xf, false)); }
; __device__ __forceinline__ float silu_f(float g) { return g * __builtin_amdgcn_rcpf(1.f + __builtin_amdgcn_exp2f(-g * LOG2E)); }
;     __device__ __forceinline__ void operator()(const f32x4 (&acc)[2][2][4][2], const pg8::Unit& u, int wr, int wc, int fr, int fq) const {
;     ...
;                 for (int m = 0; m < 4; ++m) {
;                     f32x4 y[2];
; #pragma unroll
;                     for (int bj = 0; bj < 2; ++bj) {
;                         const f32x4 cur = acc[ai][bj][m][n]; f32x4 r1, r2;
; #pragma unroll
;                         for (int j = 0; j < 4; ++j) { r1[j] = dpp_ror<0x121>(cur[j]); r2[j] = dpp_ror<0x122>(cur[j]); }
;                         const f32x4 s1 = (fr >= 1) ? r1 : p1[bj], s2 = (fr >= 2) ? r2 : p2[bj];
;                         y[bj] = bb[bj] + w[bj][0] * s2 + w[bj][1] * s1 + w[bj][2] * cur;
;                         p1[bj] = r1; p2[bj] = r2;
;                         if (m == 0 && fr < 2) *(f32x4*)(hf + (size_t)(wb * 2 + fr) * FFN2 + bj * FFN + f0) = cur;
;                         if (m == 3 && fr >= 14) *(f32x4*)(hl + (size_t)(wb * 2 + fr - 14) * FFN2 + bj * FFN + f0) = cur;
;                     }
;                     u32x2 o; o.x = pg8::cvt_pk_bf16(silu_f(y[0][0]) * y[1][0], silu_f(y[0][1]) * y[1][1]); o.y = pg8::cvt_pk_bf16(silu_f(y[0][2]) * y[1][2], silu_f(y[0][3]) * y[1][3]);
;                     if (n == 0) held[ai][m] = o;
;                     else *(u32x4*)(act + (size_t)(wb * 64 + m * 16 + fr) * FFN + f0 - 4) = (u32x4){held[ai][m].x, held[ai][m].y, o.x, o.y};
	v_mov_b32_dpp v84, v77 row_ror:1 row_mask:0xf bank_mask:0xf
	v_mov_b32_dpp v87, v78 row_ror:1 row_mask:0xf bank_mask:0xf
	v_mov_b32_dpp v91, v79 row_ror:1 row_mask:0xf bank_mask:0xf
	v_cndmask_b32_e64 v101, v201, v85, s[8:9]
	v_cndmask_b32_e64 v100, v199, v83, s[8:9]
	v_cndmask_b32_e64 v103, v205, v90, s[8:9]
	v_cndmask_b32_e64 v102, v203, v86, s[8:9]
	v_cndmask_b32_e64 v95, v91, v204, s[6:7]
	v_cndmask_b32_e64 v94, v87, v202, s[6:7]
	v_cndmask_b32_e64 v99, v84, v200, s[6:7]
	v_cndmask_b32_e64 v98, v82, v198, s[6:7]
	v_pk_fma_f32 v[102:103], v[126:127], v[102:103], v[122:123]
	v_pk_fma_f32 v[100:101], v[124:125], v[100:101], v[120:121]
	v_pk_fma_f32 v[94:95], v[114:115], v[94:95], v[102:103]
	v_pk_fma_f32 v[98:99], v[112:113], v[98:99], v[100:101]
	v_pk_fma_f32 v[100:101], v[78:79], v[118:119], v[94:95]
	v_pk_fma_f32 v[102:103], v[76:77], v[116:117], v[98:99]
	v_mov_b32_dpp v77, v72 row_ror:2 row_mask:0xf bank_mask:0xf
	v_mov_b32_dpp v78, v73 row_ror:1 row_mask:0xf bank_mask:0xf
	v_mov_b32_dpp v79, v73 row_ror:2 row_mask:0xf bank_mask:0xf
	v_mov_b32_dpp v76, v72 row_ror:1 row_mask:0xf bank_mask:0xf
	v_cndmask_b32_e64 v129, v78, v151, s[6:7]
	v_cndmask_b32_e64 v151, v156, v79, s[8:9]
	v_cndmask_b32_e64 v150, v150, v77, s[8:9]
	v_cndmask_b32_e64 v128, v76, v128, s[6:7]
	v_pk_fma_f32 v[150:151], v[144:145], v[150:151], v[132:133]
	v_pk_fma_f32 v[128:129], v[136:137], v[128:129], v[150:151]
	v_mul_f32_e32 v150, 0xbfb8aa3b, v102
	v_mov_b32_dpp v95, v74 row_ror:1 row_mask:0xf bank_mask:0xf
	v_mov_b32_dpp v94, v74 row_ror:2 row_mask:0xf bank_mask:0xf
	v_mov_b32_dpp v98, v75 row_ror:2 row_mask:0xf bank_mask:0xf
	v_exp_f32_e32 v150, v150
	v_mul_f32_e32 v151, 0xbfb8aa3b, v103
	v_mov_b32_dpp v99, v75 row_ror:1 row_mask:0xf bank_mask:0xf
	v_cndmask_b32_e64 v106, v95, v157, s[6:7]
	v_cndmask_b32_e64 v157, v159, v98, s[8:9]
	v_cndmask_b32_e64 v156, v158, v94, s[8:9]
	v_exp_f32_e32 v151, v151
	v_cndmask_b32_e64 v107, v99, v107, s[6:7]
	v_pk_fma_f32 v[156:157], v[146:147], v[156:157], v[134:135]
	v_pk_fma_f32 v[72:73], v[72:73], v[140:141], v[128:129]
	v_pk_fma_f32 v[106:107], v[138:139], v[106:107], v[156:157]
	v_add_u32_e32 v92, s3, v192
	v_pk_fma_f32 v[74:75], v[74:75], v[142:143], v[106:107]
	v_add_f32_e32 v106, 1.0, v150
	v_rcp_f32_e32 v106, v106
	v_add_f32_e32 v107, 1.0, v151
	v_rcp_f32_e32 v107, v107
	v_mad_i64_i32 v[92:93], s[42:43], v92, s69, 0
	v_mul_f32_e32 v102, v102, v106
	v_mul_f32_e32 v72, v102, v72
	v_mul_f32_e32 v102, v103, v107
	v_mul_f32_e32 v103, 0xbfb8aa3b, v100
	v_exp_f32_e32 v103, v103
	v_mul_f32_e32 v106, 0xbfb8aa3b, v101
	v_exp_f32_e32 v106, v106
	v_mul_f32_e32 v73, v102, v73
	v_add_f32_e32 v102, 1.0, v103
	v_rcp_f32_e32 v102, v102
	v_add_f32_e32 v103, 1.0, v106
	v_rcp_f32_e32 v103, v103
	v_cvt_pk_bf16_f32 v72, v72, v73
	v_mul_f32_e32 v73, v100, v102
	v_mul_f32_e32 v73, v73, v74
	v_mul_f32_e32 v74, v101, v103
	v_mul_f32_e32 v74, v74, v75
	v_cvt_pk_bf16_f32 v73, v73, v74
	v_lshl_add_u64 v[128:129], s[22:23], 0, v[92:93]
	v_mov_b32_dpp v74, v64 row_ror:1 row_mask:0xf bank_mask:0xf
	v_mov_b32_dpp v75, v64 row_ror:2 row_mask:0xf bank_mask:0xf
	v_mov_b32_dpp v100, v65 row_ror:1 row_mask:0xf bank_mask:0xf
	v_mov_b32_dpp v101, v65 row_ror:2 row_mask:0xf bank_mask:0xf
	v_mov_b32_dpp v103, v66 row_ror:1 row_mask:0xf bank_mask:0xf
	v_mov_b32_dpp v102, v66 row_ror:2 row_mask:0xf bank_mask:0xf
	v_mov_b32_dpp v107, v67 row_ror:1 row_mask:0xf bank_mask:0xf
	v_mov_b32_dpp v106, v67 row_ror:2 row_mask:0xf bank_mask:0xf
	v_lshl_add_u64 v[150:151], v[176:177], 2, v[128:129]
	s_and_saveexec_b64 s[42:43], s[12:13]
	s_cbranch_execz .LBB0_1356
	global_store_dwordx4 v[150:151], v[64:67], off
.LBB0_1356:
	s_or_b64 exec, exec, s[42:43]
	v_mov_b32_dpp v92, v68 row_ror:1 row_mask:0xf bank_mask:0xf
	v_mov_b32_dpp v93, v68 row_ror:2 row_mask:0xf bank_mask:0xf
	v_mov_b32_dpp v156, v69 row_ror:1 row_mask:0xf bank_mask:0xf
	v_mov_b32_dpp v157, v69 row_ror:2 row_mask:0xf bank_mask:0xf
	v_mov_b32_dpp v159, v70 row_ror:1 row_mask:0xf bank_mask:0xf
	v_mov_b32_dpp v158, v70 row_ror:2 row_mask:0xf bank_mask:0xf
	v_mov_b32_dpp v199, v71 row_ror:1 row_mask:0xf bank_mask:0xf
	v_mov_b32_dpp v198, v71 row_ror:2 row_mask:0xf bank_mask:0xf
	s_and_saveexec_b64 s[42:43], s[12:13]
	s_cbranch_execz .LBB0_1358
	v_add_co_u32_e32 v200, vcc, 0x2000, v150
	s_nop 1
	v_addc_co_u32_e32 v201, vcc, 0, v151, vcc
	global_store_dwordx4 v[200:201], v[68:71], off offset:3072
; __device__ __forceinline__ unsigned cvt_pk_bf16(float lo, float hi) { unsigned r; asm volatile("v_cvt_pk_bf16_f32 %0, %1, %2" : "=v"(r) : "v"(lo), "v"(hi)); return r; }
; __device__ __forceinline__ float silu_f(float g) { return g * __builtin_amdgcn_rcpf(1.f + __builtin_amdgcn_exp2f(-g * LOG2E)); }
;     __device__ __forceinline__ void operator()(const f32x4 (&acc)[2][2][4][2], const pg8::Unit& u, int wr, int wc, int fr, int fq) const {
;     ...
;         for (int n = 0; n < 2; ++n) {
;             const int f0 = u.pn * 128 + wc * 32 + 8 * fq + 4 * n;
;             f32x4 w[2][3], bb[2];
; #pragma unroll
;             for (int bj = 0; bj < 2; ++bj) { const int col = bj * FFN + f0; bb[bj] = *(const f32x4*)(cb + col);
; #pragma unroll
;                 for (int tp = 0; tp < 3; ++tp) w[bj][tp] = *(const f32x4*)(cw + tp * FFN2 + col); }
; #pragma unroll
;             for (int ai = 0; ai < 2; ++ai) {
;                 const int wb = (u.pm * 2 + ai) * 2 + wr;
;                 f32x4 p1[2], p2[2];
;                 p1[0] = p1[1] = p2[0] = p2[1] = (f32x4){0.f, 0.f, 0.f, 0.f};
; #pragma unroll
;                 for (int m = 0; m < 4; ++m) {
;                     f32x4 y[2];
; #pragma unroll
;                     for (int bj = 0; bj < 2; ++bj) {
;                         const f32x4 cur = acc[ai][bj][m][n]; f32x4 r1, r2;
; #pragma unroll
;                         for (int j = 0; j < 4; ++j) { r1[j] = dpp_ror<0x121>(cur[j]); r2[j] = dpp_ror<0x122>(cur[j]); }
;                         const f32x4 s1 = (fr >= 1) ? r1 : p1[bj], s2 = (fr >= 2) ? r2 : p2[bj];
;                         y[bj] = bb[bj] + w[bj][0] * s2 + w[bj][1] * s1 + w[bj][2] * cur;
;                         p1[bj] = r1; p2[bj] = r2;
;                         if (m == 0 && fr < 2) *(f32x4*)(hf + (size_t)(wb * 2 + fr) * FFN2 + bj * FFN + f0) = cur;
;                         if (m == 3 && fr >= 14) *(f32x4*)(hl + (size_t)(wb * 2 + fr - 14) * FFN2 + bj * FFN + f0) = cur;
;                     }
;                     u32x2 o; o.x = pg8::cvt_pk_bf16(silu_f(y[0][0]) * y[1][0], silu_f(y[0][1]) * y[1][1]); o.y = pg8::cvt_pk_bf16(silu_f(y[0][2]) * y[1][2], silu_f(y[0][3]) * y[1][3]);
;                     if (n == 0) held[ai][m] = o;
;                     else *(u32x4*)(act + (size_t)(wb * 64 + m * 16 + fr) * FFN + f0 - 4) = (u32x4){held[ai][m].x, held[ai][m].y, o.x, o.y};
.LBB0_1358:
	s_or_b64 exec, exec, s[42:43]
	v_cndmask_b32_e64 v203, v156, v78, s[6:7]
	v_cndmask_b32_e64 v79, v79, v157, s[8:9]
	v_cndmask_b32_e64 v78, v77, v93, s[8:9]
	v_cndmask_b32_e64 v202, v92, v76, s[6:7]
	v_pk_fma_f32 v[78:79], v[144:145], v[78:79], v[132:133]
	v_cndmask_b32_e64 v85, v85, v101, s[8:9]
	v_pk_fma_f32 v[78:79], v[136:137], v[202:203], v[78:79]
	v_cndmask_b32_e64 v77, v98, v198, s[8:9]
	v_pk_fma_f32 v[68:69], v[68:69], v[140:141], v[78:79]
	v_cndmask_b32_e64 v79, v100, v84, s[6:7]
	v_cndmask_b32_e64 v84, v83, v75, s[8:9]
	v_cndmask_b32_e64 v78, v74, v82, s[6:7]
	v_pk_fma_f32 v[82:83], v[124:125], v[84:85], v[120:121]
	v_cndmask_b32_e64 v76, v94, v158, s[8:9]
	v_pk_fma_f32 v[78:79], v[112:113], v[78:79], v[82:83]
	v_cndmask_b32_e64 v201, v199, v99, s[6:7]
	v_pk_fma_f32 v[64:65], v[64:65], v[116:117], v[78:79]
	v_cndmask_b32_e64 v200, v159, v95, s[6:7]
	v_mul_f32_e32 v78, 0xbfb8aa3b, v64
	v_exp_f32_e32 v78, v78
	v_pk_fma_f32 v[76:77], v[146:147], v[76:77], v[134:135]
	v_cndmask_b32_e64 v75, v90, v106, s[8:9]
	v_pk_fma_f32 v[76:77], v[138:139], v[200:201], v[76:77]
	v_cndmask_b32_e64 v74, v86, v102, s[8:9]
	v_pk_fma_f32 v[70:71], v[70:71], v[142:143], v[76:77]
	v_cndmask_b32_e64 v77, v107, v91, s[6:7]
	v_cndmask_b32_e64 v76, v103, v87, s[6:7]
	v_pk_fma_f32 v[74:75], v[126:127], v[74:75], v[122:123]
	v_mul_f32_e32 v79, 0xbfb8aa3b, v65
	v_pk_fma_f32 v[74:75], v[114:115], v[76:77], v[74:75]
	v_add_f32_e32 v76, 1.0, v78
	v_rcp_f32_e32 v76, v76
	v_exp_f32_e32 v79, v79
	v_pk_fma_f32 v[66:67], v[66:67], v[118:119], v[74:75]
	v_mul_f32_e32 v64, v64, v76
	v_add_f32_e32 v77, 1.0, v79
	v_mul_f32_e32 v64, v64, v68
	v_mul_f32_e32 v68, 0xbfb8aa3b, v66
	v_rcp_f32_e32 v77, v77
	v_exp_f32_e32 v68, v68
	v_mul_f32_e32 v74, 0xbfb8aa3b, v67
	v_exp_f32_e32 v74, v74
	v_mul_f32_e32 v65, v65, v77
	v_add_f32_e32 v68, 1.0, v68
	v_mul_f32_e32 v65, v65, v69
	v_rcp_f32_e32 v68, v68
	v_add_f32_e32 v69, 1.0, v74
	v_rcp_f32_e32 v69, v69
	v_cvt_pk_bf16_f32 v64, v64, v65
	v_mul_f32_e32 v65, v66, v68
	v_mul_f32_e32 v65, v65, v70
	v_mul_f32_e32 v66, v67, v69
	v_or_b32_e32 v70, 4, v176
	v_mul_f32_e32 v66, v66, v71
	v_ashrrev_i32_e32 v71, 31, v70
	v_cvt_pk_bf16_f32 v65, v65, v66
	v_lshlrev_b64 v[66:67], 2, v[70:71]
	v_lshl_add_u64 v[74:75], s[24:25], 0, v[66:67]
	v_lshl_add_u64 v[68:69], s[26:27], 0, v[66:67]
	v_add_co_u32_e32 v66, vcc, s66, v74
	global_load_dwordx4 v[84:87], v[68:69], off
	s_nop 0
	v_addc_co_u32_e32 v67, vcc, 0, v75, vcc
	global_load_dwordx4 v[92:95], v[74:75], off
	s_nop 0
	global_load_dwordx4 v[66:69], v[66:67], off offset:2048
	v_add_co_u32_e32 v74, vcc, s67, v74
	s_nop 0
	s_nop 0
	v_addc_co_u32_e32 v75, vcc, 0, v75, vcc
	global_load_dwordx4 v[76:79], v[74:75], off
	global_load_dwordx4 v[118:121], v[180:181], off offset:3088
	global_load_dwordx4 v[122:125], v[182:183], off offset:3088
	global_load_dwordx4 v[114:117], v[184:185], off offset:1040
	global_load_dwordx4 v[100:103], v[186:187], off offset:3088
	v_mov_b32_dpp v99, v56 row_ror:1 row_mask:0xf bank_mask:0xf
	v_mov_b32_dpp v106, v56 row_ror:2 row_mask:0xf bank_mask:0xf
	v_mov_b32_dpp v126, v57 row_ror:1 row_mask:0xf bank_mask:0xf
	v_mov_b32_dpp v127, v57 row_ror:2 row_mask:0xf bank_mask:0xf
	v_mov_b32_dpp v133, v58 row_ror:1 row_mask:0xf bank_mask:0xf
	v_mov_b32_dpp v132, v58 row_ror:2 row_mask:0xf bank_mask:0xf
	v_mov_b32_dpp v135, v59 row_ror:1 row_mask:0xf bank_mask:0xf
	v_mov_b32_dpp v134, v59 row_ror:2 row_mask:0xf bank_mask:0xf
	s_and_saveexec_b64 s[42:43], s[10:11]
	s_cbranch_execz .LBB0_1360
	global_store_dwordx4 v[188:189], v[56:59], off offset:16
.LBB0_1360:
	s_or_b64 exec, exec, s[42:43]
	v_mov_b32_dpp v74, v60 row_ror:1 row_mask:0xf bank_mask:0xf
	v_mov_b32_dpp v75, v60 row_ror:2 row_mask:0xf bank_mask:0xf
	v_mov_b32_dpp v82, v61 row_ror:1 row_mask:0xf bank_mask:0xf
	v_mov_b32_dpp v83, v61 row_ror:2 row_mask:0xf bank_mask:0xf
	v_mov_b32_dpp v91, v62 row_ror:1 row_mask:0xf bank_mask:0xf
	v_mov_b32_dpp v90, v62 row_ror:2 row_mask:0xf bank_mask:0xf
	v_mov_b32_dpp v107, v63 row_ror:1 row_mask:0xf bank_mask:0xf
	v_mov_b32_dpp v98, v63 row_ror:2 row_mask:0xf bank_mask:0xf
	s_and_saveexec_b64 s[42:43], s[10:11]
	s_cbranch_execz .LBB0_1362
	v_lshl_add_u64 v[112:113], v[70:71], 2, v[178:179]
	v_add_co_u32_e32 v112, vcc, 0x2000, v112
	s_nop 1
	v_addc_co_u32_e32 v113, vcc, 0, v113, vcc
	global_store_dwordx4 v[112:113], v[60:63], off offset:3072
; __device__ __forceinline__ unsigned cvt_pk_bf16(float lo, float hi) { unsigned r; asm volatile("v_cvt_pk_bf16_f32 %0, %1, %2" : "=v"(r) : "v"(lo), "v"(hi)); return r; }
; template <int CTRL> __device__ __forceinline__ float dpp_ror(float v) { return __builtin_bit_cast(float, __builtin_amdgcn_update_dpp(0, __builtin_bit_cast(int, v), CTRL, 0xf, 0xf, false)); }
; __device__ __forceinline__ float silu_f(float g) { return g * __builtin_amdgcn_rcpf(1.f + __builtin_amdgcn_exp2f(-g * LOG2E)); }
;     __device__ __forceinline__ void operator()(const f32x4 (&acc)[2][2][4][2], const pg8::Unit& u, int wr, int wc, int fr, int fq) const {
;     ...
;                 for (int m = 0; m < 4; ++m) {
;                     f32x4 y[2];
; #pragma unroll
;                     for (int bj = 0; bj < 2; ++bj) {
;                         const f32x4 cur = acc[ai][bj][m][n]; f32x4 r1, r2;
; #pragma unroll
;                         for (int j = 0; j < 4; ++j) { r1[j] = dpp_ror<0x121>(cur[j]); r2[j] = dpp_ror<0x122>(cur[j]); }
;                         const f32x4 s1 = (fr >= 1) ? r1 : p1[bj], s2 = (fr >= 2) ? r2 : p2[bj];
;                         y[bj] = bb[bj] + w[bj][0] * s2 + w[bj][1] * s1 + w[bj][2] * cur;
;                         p1[bj] = r1; p2[bj] = r2;
;                         if (m == 0 && fr < 2) *(f32x4*)(hf + (size_t)(wb * 2 + fr) * FFN2 + bj * FFN + f0) = cur;
;                         if (m == 3 && fr >= 14) *(f32x4*)(hl + (size_t)(wb * 2 + fr - 14) * FFN2 + bj * FFN + f0) = cur;
;                     }
;                     u32x2 o; o.x = pg8::cvt_pk_bf16(silu_f(y[0][0]) * y[1][0], silu_f(y[0][1]) * y[1][1]); o.y = pg8::cvt_pk_bf16(silu_f(y[0][2]) * y[1][2], silu_f(y[0][3]) * y[1][3]);
;                     if (n == 0) held[ai][m] = o;
;                     else *(u32x4*)(act + (size_t)(wb * 64 + m * 16 + fr) * FFN + f0 - 4) = (u32x4){held[ai][m].x, held[ai][m].y, o.x, o.y};
.LBB0_1362:
	s_or_b64 exec, exec, s[42:43]
	v_cndmask_b32_e64 v139, 0, v83, s[8:9]
	v_cndmask_b32_e64 v138, 0, v75, s[8:9]
	v_cndmask_b32_e64 v137, v82, 0, s[6:7]
	v_cndmask_b32_e64 v136, v74, 0, s[6:7]
	s_waitcnt vmcnt(2)
	v_pk_fma_f32 v[138:139], v[122:123], v[138:139], v[118:119]
	v_cndmask_b32_e64 v141, 0, v98, s[8:9]
	s_waitcnt vmcnt(1)
	v_pk_fma_f32 v[136:137], v[114:115], v[136:137], v[138:139]
	v_cndmask_b32_e64 v139, 0, v127, s[8:9]
	v_cndmask_b32_e64 v138, 0, v106, s[8:9]
	s_waitcnt vmcnt(0)
	v_pk_fma_f32 v[60:61], v[60:61], v[100:101], v[136:137]
	v_cndmask_b32_e64 v137, v126, 0, s[6:7]
	v_cndmask_b32_e64 v136, v99, 0, s[6:7]
	v_pk_fma_f32 v[138:139], v[92:93], v[138:139], v[84:85]
	v_cndmask_b32_e64 v140, 0, v90, s[8:9]
	v_pk_fma_f32 v[136:137], v[66:67], v[136:137], v[138:139]
	v_cndmask_b32_e64 v113, v107, 0, s[6:7]
	v_pk_fma_f32 v[56:57], v[56:57], v[76:77], v[136:137]
	v_cndmask_b32_e64 v112, v91, 0, s[6:7]
	v_mul_f32_e32 v136, 0xbfb8aa3b, v56
	v_pk_fma_f32 v[140:141], v[124:125], v[140:141], v[120:121]
	v_exp_f32_e32 v138, v136
	v_pk_fma_f32 v[112:113], v[116:117], v[112:113], v[140:141]
	v_cndmask_b32_e64 v141, 0, v134, s[8:9]
	v_cndmask_b32_e64 v140, 0, v132, s[8:9]
	v_pk_fma_f32 v[62:63], v[62:63], v[102:103], v[112:113]
	v_cndmask_b32_e64 v113, v135, 0, s[6:7]
	v_cndmask_b32_e64 v112, v133, 0, s[6:7]
	v_pk_fma_f32 v[140:141], v[94:95], v[140:141], v[86:87]
	v_mul_f32_e32 v136, 0xbfb8aa3b, v57
	v_pk_fma_f32 v[112:113], v[68:69], v[112:113], v[140:141]
	v_exp_f32_e32 v139, v136
	v_pk_fma_f32 v[136:137], v[58:59], v[78:79], v[112:113]
	v_add_f32_e32 v58, 1.0, v138
	v_rcp_f32_e32 v59, v58
	v_add_f32_e32 v58, 1.0, v139
	v_rcp_f32_e32 v112, v58
	v_lshl_or_b32 v58, s37, 6, v190
	v_mul_f32_e32 v56, v56, v59
	v_mul_f32_e32 v56, v56, v60
	v_mul_f32_e32 v59, 0xbfb8aa3b, v136
	v_mul_f32_e32 v60, 0xbfb8aa3b, v137
	v_exp_f32_e32 v59, v59
	v_exp_f32_e32 v60, v60
	v_mul_f32_e32 v57, v57, v112
	v_mul_f32_e32 v57, v57, v61
	v_add_f32_e32 v59, 1.0, v59
	v_add_f32_e32 v60, 1.0, v60
	v_rcp_f32_e32 v59, v59
	v_rcp_f32_e32 v60, v60
	v_cvt_pk_bf16_f32 v112, v56, v57
	v_mul_f32_e32 v56, v136, v59
	v_mul_f32_e32 v57, v137, v60
	v_mul_f32_e32 v56, v56, v62
	v_mul_f32_e32 v57, v57, v63
	v_mov_b64_e32 v[136:137], s[18:19]
	v_cvt_pk_bf16_f32 v113, v56, v57
	v_mad_i64_i32 v[60:61], s[42:43], v58, s70, v[136:137]
	v_lshlrev_b64 v[56:57], 1, v[176:177]
	v_lshl_add_u64 v[60:61], v[60:61], 0, v[56:57]
	v_mov_b32_dpp v142, v54 row_ror:2 row_mask:0xf bank_mask:0xf
	v_mov_b32_dpp v144, v55 row_ror:2 row_mask:0xf bank_mask:0xf
	global_store_dwordx4 v[60:61], v[110:113], off
	v_mov_b32_dpp v138, v52 row_ror:2 row_mask:0xf bank_mask:0xf
	v_mov_b32_dpp v140, v53 row_ror:2 row_mask:0xf bank_mask:0xf
	v_mov_b32_dpp v141, v54 row_ror:1 row_mask:0xf bank_mask:0xf
	v_mov_b32_dpp v143, v55 row_ror:1 row_mask:0xf bank_mask:0xf
	v_cndmask_b32_e64 v113, v134, v144, s[8:9]
	v_cndmask_b32_e64 v112, v132, v142, s[8:9]
	v_mov_b32_dpp v59, v52 row_ror:1 row_mask:0xf bank_mask:0xf
	v_mov_b32_dpp v139, v53 row_ror:1 row_mask:0xf bank_mask:0xf
	v_cndmask_b32_e64 v61, v143, v135, s[6:7]
	v_cndmask_b32_e64 v60, v141, v133, s[6:7]
	v_cndmask_b32_e64 v111, v127, v140, s[8:9]
	v_cndmask_b32_e64 v110, v106, v138, s[8:9]
	v_pk_fma_f32 v[112:113], v[94:95], v[112:113], v[86:87]
	v_cndmask_b32_e64 v63, v139, v126, s[6:7]
	v_cndmask_b32_e64 v62, v59, v99, s[6:7]
	v_pk_fma_f32 v[110:111], v[92:93], v[110:111], v[84:85]
	v_pk_fma_f32 v[60:61], v[68:69], v[60:61], v[112:113]
	v_pk_fma_f32 v[62:63], v[66:67], v[62:63], v[110:111]
	v_mov_b32_dpp v106, v48 row_ror:1 row_mask:0xf bank_mask:0xf
	v_mov_b32_dpp v112, v48 row_ror:2 row_mask:0xf bank_mask:0xf
	v_mov_b32_dpp v99, v49 row_ror:1 row_mask:0xf bank_mask:0xf
	v_mov_b32_dpp v127, v50 row_ror:2 row_mask:0xf bank_mask:0xf
	v_mov_b32_dpp v133, v51 row_ror:2 row_mask:0xf bank_mask:0xf
	v_pk_fma_f32 v[52:53], v[52:53], v[76:77], v[62:63]
	v_mov_b32_dpp v126, v50 row_ror:1 row_mask:0xf bank_mask:0xf
	v_mov_b32_dpp v132, v51 row_ror:1 row_mask:0xf bank_mask:0xf
	v_cndmask_b32_e64 v63, v99, v82, s[6:7]
	v_cndmask_b32_e64 v62, v106, v74, s[6:7]
	v_cndmask_b32_e64 v82, v75, v112, s[8:9]
	v_cndmask_b32_e64 v75, v98, v133, s[8:9]
	v_cndmask_b32_e64 v74, v90, v127, s[8:9]
	v_pk_fma_f32 v[54:55], v[54:55], v[78:79], v[60:61]
	v_cndmask_b32_e64 v61, v132, v107, s[6:7]
	v_cndmask_b32_e64 v60, v126, v91, s[6:7]
	v_pk_fma_f32 v[74:75], v[124:125], v[74:75], v[120:121]
	v_pk_fma_f32 v[60:61], v[116:117], v[60:61], v[74:75]
	v_mul_f32_e32 v74, 0xbfb8aa3b, v52
	v_exp_f32_e32 v74, v74
	v_mul_f32_e32 v75, 0xbfb8aa3b, v53
	v_exp_f32_e32 v75, v75
	v_pk_fma_f32 v[50:51], v[50:51], v[102:103], v[60:61]
	v_add_f32_e32 v60, 1.0, v74
	v_mov_b32_dpp v113, v49 row_ror:2 row_mask:0xf bank_mask:0xf
	v_rcp_f32_e32 v60, v60
	v_add_f32_e32 v61, 1.0, v75
	v_cndmask_b32_e64 v83, v83, v113, s[8:9]
	v_rcp_f32_e32 v61, v61
	v_pk_fma_f32 v[82:83], v[122:123], v[82:83], v[118:119]
	v_mul_f32_e32 v52, v52, v60
	v_pk_fma_f32 v[62:63], v[114:115], v[62:63], v[82:83]
	v_mul_f32_e32 v60, 0xbfb8aa3b, v55
	v_pk_fma_f32 v[48:49], v[48:49], v[100:101], v[62:63]
	v_exp_f32_e32 v60, v60
	v_mul_f32_e32 v48, v52, v48
	v_mul_f32_e32 v52, v53, v61
	v_mul_f32_e32 v53, 0xbfb8aa3b, v54
	v_exp_f32_e32 v53, v53
	v_mul_f32_e32 v49, v52, v49
	v_cvt_pk_bf16_f32 v110, v48, v49
	v_add_f32_e32 v52, 1.0, v53
	v_rcp_f32_e32 v52, v52
	v_add_f32_e32 v53, 1.0, v60
	v_rcp_f32_e32 v53, v53
	v_mul_f32_e32 v48, v54, v52
	v_mul_f32_e32 v48, v48, v50
	v_mul_f32_e32 v49, v55, v53
	v_mul_f32_e32 v49, v49, v51
	v_cvt_pk_bf16_f32 v111, v48, v49
	v_or_b32_e32 v48, 16, v58
	v_mad_i64_i32 v[48:49], s[42:43], v48, s70, v[136:137]
; __device__ __forceinline__ unsigned cvt_pk_bf16(float lo, float hi) { unsigned r; asm volatile("v_cvt_pk_bf16_f32 %0, %1, %2" : "=v"(r) : "v"(lo), "v"(hi)); return r; }
; template <int CTRL> __device__ __forceinline__ float dpp_ror(float v) { return __builtin_bit_cast(float, __builtin_amdgcn_update_dpp(0, __builtin_bit_cast(int, v), CTRL, 0xf, 0xf, false)); }
; __device__ __forceinline__ float silu_f(float g) { return g * __builtin_amdgcn_rcpf(1.f + __builtin_amdgcn_exp2f(-g * LOG2E)); }
;     __device__ __forceinline__ void operator()(const f32x4 (&acc)[2][2][4][2], const pg8::Unit& u, int wr, int wc, int fr, int fq) const {
;     ...
;                 for (int m = 0; m < 4; ++m) {
;                     f32x4 y[2];
; #pragma unroll
;                     for (int bj = 0; bj < 2; ++bj) {
;                         const f32x4 cur = acc[ai][bj][m][n]; f32x4 r1, r2;
; #pragma unroll
;                         for (int j = 0; j < 4; ++j) { r1[j] = dpp_ror<0x121>(cur[j]); r2[j] = dpp_ror<0x122>(cur[j]); }
;                         const f32x4 s1 = (fr >= 1) ? r1 : p1[bj], s2 = (fr >= 2) ? r2 : p2[bj];
;                         y[bj] = bb[bj] + w[bj][0] * s2 + w[bj][1] * s1 + w[bj][2] * cur;
;                         p1[bj] = r1; p2[bj] = r2;
;                         if (m == 0 && fr < 2) *(f32x4*)(hf + (size_t)(wb * 2 + fr) * FFN2 + bj * FFN + f0) = cur;
;                         if (m == 3 && fr >= 14) *(f32x4*)(hl + (size_t)(wb * 2 + fr - 14) * FFN2 + bj * FFN + f0) = cur;
;                     }
;                     u32x2 o; o.x = pg8::cvt_pk_bf16(silu_f(y[0][0]) * y[1][0], silu_f(y[0][1]) * y[1][1]); o.y = pg8::cvt_pk_bf16(silu_f(y[0][2]) * y[1][2], silu_f(y[0][3]) * y[1][3]);
;                     if (n == 0) held[ai][m] = o;
;                     else *(u32x4*)(act + (size_t)(wb * 64 + m * 16 + fr) * FFN + f0 - 4) = (u32x4){held[ai][m].x, held[ai][m].y, o.x, o.y};
	v_lshl_add_u64 v[48:49], v[48:49], 0, v[56:57]
	global_store_dwordx4 v[48:49], v[108:111], off
	v_mov_b32_dpp v49, v44 row_ror:2 row_mask:0xf bank_mask:0xf
	v_mov_b32_dpp v51, v45 row_ror:2 row_mask:0xf bank_mask:0xf
	v_mov_b32_dpp v52, v46 row_ror:2 row_mask:0xf bank_mask:0xf
	v_mov_b32_dpp v54, v47 row_ror:2 row_mask:0xf bank_mask:0xf
	v_mov_b32_dpp v48, v44 row_ror:1 row_mask:0xf bank_mask:0xf
	v_mov_b32_dpp v50, v45 row_ror:1 row_mask:0xf bank_mask:0xf
	v_mov_b32_dpp v53, v46 row_ror:1 row_mask:0xf bank_mask:0xf
	v_mov_b32_dpp v55, v47 row_ror:1 row_mask:0xf bank_mask:0xf
	v_cndmask_b32_e64 v75, v140, v51, s[8:9]
	v_cndmask_b32_e64 v74, v138, v49, s[8:9]
	v_cndmask_b32_e64 v83, v144, v54, s[8:9]
	v_cndmask_b32_e64 v82, v142, v52, s[8:9]
	v_cndmask_b32_e64 v61, v55, v143, s[6:7]
	v_cndmask_b32_e64 v60, v53, v141, s[6:7]
	v_cndmask_b32_e64 v63, v50, v139, s[6:7]
	v_cndmask_b32_e64 v62, v48, v59, s[6:7]
	v_pk_fma_f32 v[82:83], v[94:95], v[82:83], v[86:87]
	v_pk_fma_f32 v[74:75], v[92:93], v[74:75], v[84:85]
	v_pk_fma_f32 v[60:61], v[68:69], v[60:61], v[82:83]
	v_pk_fma_f32 v[62:63], v[66:67], v[62:63], v[74:75]
	v_pk_fma_f32 v[74:75], v[46:47], v[78:79], v[60:61]
	v_pk_fma_f32 v[82:83], v[44:45], v[76:77], v[62:63]
	v_mov_b32_dpp v44, v40 row_ror:1 row_mask:0xf bank_mask:0xf
	v_mov_b32_dpp v45, v40 row_ror:2 row_mask:0xf bank_mask:0xf
	v_mov_b32_dpp v47, v41 row_ror:2 row_mask:0xf bank_mask:0xf
	v_cndmask_b32_e64 v98, v44, v106, s[6:7]
	v_mov_b32_dpp v46, v41 row_ror:1 row_mask:0xf bank_mask:0xf
	v_cndmask_b32_e64 v107, v113, v47, s[8:9]
	v_cndmask_b32_e64 v106, v112, v45, s[8:9]
	v_cndmask_b32_e64 v99, v46, v99, s[6:7]
	v_pk_fma_f32 v[106:107], v[122:123], v[106:107], v[118:119]
	v_mul_f32_e32 v63, 0xbfb8aa3b, v82
	v_pk_fma_f32 v[98:99], v[114:115], v[98:99], v[106:107]
	v_exp_f32_e32 v63, v63
	v_mul_f32_e32 v106, 0xbfb8aa3b, v83
	v_mov_b32_dpp v59, v42 row_ror:2 row_mask:0xf bank_mask:0xf
	v_mov_b32_dpp v61, v43 row_ror:2 row_mask:0xf bank_mask:0xf
	v_exp_f32_e32 v106, v106
	v_mov_b32_dpp v60, v42 row_ror:1 row_mask:0xf bank_mask:0xf
	v_mov_b32_dpp v62, v43 row_ror:1 row_mask:0xf bank_mask:0xf
	v_cndmask_b32_e64 v109, v133, v61, s[8:9]
	v_cndmask_b32_e64 v108, v127, v59, s[8:9]
	v_cndmask_b32_e64 v91, v62, v132, s[6:7]
	v_cndmask_b32_e64 v90, v60, v126, s[6:7]
	v_pk_fma_f32 v[108:109], v[124:125], v[108:109], v[120:121]
	v_add_f32_e32 v63, 1.0, v63
	v_pk_fma_f32 v[90:91], v[116:117], v[90:91], v[108:109]
	v_rcp_f32_e32 v63, v63
	v_pk_fma_f32 v[42:43], v[42:43], v[102:103], v[90:91]
	v_add_f32_e32 v90, 1.0, v106
	v_rcp_f32_e32 v90, v90
	v_pk_fma_f32 v[40:41], v[40:41], v[100:101], v[98:99]
	v_mul_f32_e32 v63, v82, v63
	v_mul_f32_e32 v82, 0xbfb8aa3b, v74
	v_mul_f32_e32 v40, v63, v40
	v_mul_f32_e32 v63, v83, v90
	v_exp_f32_e32 v82, v82
	v_mul_f32_e32 v83, 0xbfb8aa3b, v75
	v_exp_f32_e32 v83, v83
	v_mul_f32_e32 v41, v63, v41
	v_add_f32_e32 v63, 1.0, v82
	v_rcp_f32_e32 v63, v63
	v_add_f32_e32 v82, 1.0, v83
	v_rcp_f32_e32 v82, v82
	v_cvt_pk_bf16_f32 v106, v40, v41
	v_mul_f32_e32 v40, v74, v63
	v_mul_f32_e32 v40, v40, v42
	v_mul_f32_e32 v41, v75, v82
	v_mul_f32_e32 v41, v41, v43
	v_cvt_pk_bf16_f32 v107, v40, v41
	v_or_b32_e32 v40, 32, v58
	v_mad_i64_i32 v[40:41], s[42:43], v40, s70, v[136:137]
	v_lshl_add_u64 v[40:41], v[40:41], 0, v[56:57]
	global_store_dwordx4 v[40:41], v[104:107], off
	v_mov_b32_dpp v40, v32 row_ror:1 row_mask:0xf bank_mask:0xf
	v_mov_b32_dpp v41, v32 row_ror:2 row_mask:0xf bank_mask:0xf
	v_mov_b32_dpp v42, v33 row_ror:1 row_mask:0xf bank_mask:0xf
	v_mov_b32_dpp v43, v33 row_ror:2 row_mask:0xf bank_mask:0xf
	v_mov_b32_dpp v74, v34 row_ror:1 row_mask:0xf bank_mask:0xf
	v_mov_b32_dpp v63, v34 row_ror:2 row_mask:0xf bank_mask:0xf
	v_mov_b32_dpp v82, v35 row_ror:1 row_mask:0xf bank_mask:0xf
	v_mov_b32_dpp v75, v35 row_ror:2 row_mask:0xf bank_mask:0xf
	s_and_saveexec_b64 s[42:43], s[12:13]
	s_cbranch_execz .LBB0_1364
	global_store_dwordx4 v[154:155], v[32:35], off offset:16
.LBB0_1364:
	s_or_b64 exec, exec, s[42:43]
	v_mov_b32_dpp v83, v36 row_ror:1 row_mask:0xf bank_mask:0xf
	v_mov_b32_dpp v90, v36 row_ror:2 row_mask:0xf bank_mask:0xf
	v_mov_b32_dpp v91, v37 row_ror:1 row_mask:0xf bank_mask:0xf
	v_mov_b32_dpp v98, v37 row_ror:2 row_mask:0xf bank_mask:0xf
	v_mov_b32_dpp v104, v38 row_ror:1 row_mask:0xf bank_mask:0xf
	v_mov_b32_dpp v99, v38 row_ror:2 row_mask:0xf bank_mask:0xf
	v_mov_b32_dpp v106, v39 row_ror:1 row_mask:0xf bank_mask:0xf
	v_mov_b32_dpp v105, v39 row_ror:2 row_mask:0xf bank_mask:0xf
	s_and_saveexec_b64 s[42:43], s[12:13]
	s_cbranch_execz .LBB0_1366
	v_lshl_add_u64 v[108:109], v[70:71], 2, v[148:149]
	v_add_co_u32_e32 v108, vcc, 0x2000, v108
	s_nop 1
	v_addc_co_u32_e32 v109, vcc, 0, v109, vcc
	global_store_dwordx4 v[108:109], v[36:39], off offset:3072
; __device__ __forceinline__ unsigned cvt_pk_bf16(float lo, float hi) { unsigned r; asm volatile("v_cvt_pk_bf16_f32 %0, %1, %2" : "=v"(r) : "v"(lo), "v"(hi)); return r; }
; template <int CTRL> __device__ __forceinline__ float dpp_ror(float v) { return __builtin_bit_cast(float, __builtin_amdgcn_update_dpp(0, __builtin_bit_cast(int, v), CTRL, 0xf, 0xf, false)); }
; __device__ __forceinline__ float silu_f(float g) { return g * __builtin_amdgcn_rcpf(1.f + __builtin_amdgcn_exp2f(-g * LOG2E)); }
;     __device__ __forceinline__ void operator()(const f32x4 (&acc)[2][2][4][2], const pg8::Unit& u, int wr, int wc, int fr, int fq) const {
;     ...
;                 for (int m = 0; m < 4; ++m) {
;                     f32x4 y[2];
; #pragma unroll
;                     for (int bj = 0; bj < 2; ++bj) {
;                         const f32x4 cur = acc[ai][bj][m][n]; f32x4 r1, r2;
; #pragma unroll
;                         for (int j = 0; j < 4; ++j) { r1[j] = dpp_ror<0x121>(cur[j]); r2[j] = dpp_ror<0x122>(cur[j]); }
;                         const f32x4 s1 = (fr >= 1) ? r1 : p1[bj], s2 = (fr >= 2) ? r2 : p2[bj];
;                         y[bj] = bb[bj] + w[bj][0] * s2 + w[bj][1] * s1 + w[bj][2] * cur;
;                         p1[bj] = r1; p2[bj] = r2;
;                         if (m == 0 && fr < 2) *(f32x4*)(hf + (size_t)(wb * 2 + fr) * FFN2 + bj * FFN + f0) = cur;
;                         if (m == 3 && fr >= 14) *(f32x4*)(hl + (size_t)(wb * 2 + fr - 14) * FFN2 + bj * FFN + f0) = cur;
;                     }
;                     u32x2 o; o.x = pg8::cvt_pk_bf16(silu_f(y[0][0]) * y[1][0], silu_f(y[0][1]) * y[1][1]); o.y = pg8::cvt_pk_bf16(silu_f(y[0][2]) * y[1][2], silu_f(y[0][3]) * y[1][3]);
;                     if (n == 0) held[ai][m] = o;
;                     else *(u32x4*)(act + (size_t)(wb * 64 + m * 16 + fr) * FFN + f0 - 4) = (u32x4){held[ai][m].x, held[ai][m].y, o.x, o.y};
.LBB0_1366:
	s_or_b64 exec, exec, s[42:43]
	v_cndmask_b32_e64 v109, v91, v46, s[6:7]
	v_cndmask_b32_e64 v47, v47, v98, s[8:9]
	v_cndmask_b32_e64 v46, v45, v90, s[8:9]
	v_cndmask_b32_e64 v108, v83, v44, s[6:7]
	v_pk_fma_f32 v[46:47], v[122:123], v[46:47], v[118:119]
	v_cndmask_b32_e64 v43, v51, v43, s[8:9]
	v_pk_fma_f32 v[46:47], v[114:115], v[108:109], v[46:47]
	v_cndmask_b32_e64 v45, v61, v105, s[8:9]
	v_pk_fma_f32 v[36:37], v[36:37], v[100:101], v[46:47]
	v_cndmask_b32_e64 v47, v42, v50, s[6:7]
	v_cndmask_b32_e64 v42, v49, v41, s[8:9]
	v_cndmask_b32_e64 v46, v40, v48, s[6:7]
	v_pk_fma_f32 v[42:43], v[92:93], v[42:43], v[84:85]
	v_cndmask_b32_e64 v44, v59, v99, s[8:9]
	v_pk_fma_f32 v[42:43], v[66:67], v[46:47], v[42:43]
	v_cndmask_b32_e64 v107, v106, v62, s[6:7]
	v_pk_fma_f32 v[32:33], v[32:33], v[76:77], v[42:43]
	v_cndmask_b32_e64 v106, v104, v60, s[6:7]
	v_mul_f32_e32 v42, 0xbfb8aa3b, v32
	v_exp_f32_e32 v42, v42
	v_mul_f32_e32 v43, 0xbfb8aa3b, v33
	v_pk_fma_f32 v[44:45], v[124:125], v[44:45], v[120:121]
	v_exp_f32_e32 v43, v43
	v_add_f32_e32 v42, 1.0, v42
	v_rcp_f32_e32 v42, v42
	v_pk_fma_f32 v[44:45], v[116:117], v[106:107], v[44:45]
	v_cndmask_b32_e64 v41, v54, v75, s[8:9]
	v_cndmask_b32_e64 v40, v52, v63, s[8:9]
	v_pk_fma_f32 v[38:39], v[38:39], v[102:103], v[44:45]
	v_cndmask_b32_e64 v45, v82, v55, s[6:7]
	v_cndmask_b32_e64 v44, v74, v53, s[6:7]
	v_pk_fma_f32 v[40:41], v[94:95], v[40:41], v[86:87]
	v_add_f32_e32 v43, 1.0, v43
	v_pk_fma_f32 v[40:41], v[68:69], v[44:45], v[40:41]
	v_mul_f32_e32 v32, v32, v42
	v_pk_fma_f32 v[34:35], v[34:35], v[78:79], v[40:41]
	v_rcp_f32_e32 v43, v43
	v_mul_f32_e32 v32, v32, v36
	v_mul_f32_e32 v36, 0xbfb8aa3b, v34
	v_mul_f32_e32 v40, 0xbfb8aa3b, v35
	v_exp_f32_e32 v36, v36
	v_exp_f32_e32 v40, v40
	v_mul_f32_e32 v33, v33, v43
	v_mul_f32_e32 v33, v33, v37
	v_add_f32_e32 v36, 1.0, v36
	v_add_f32_e32 v37, 1.0, v40
	v_rcp_f32_e32 v36, v36
	v_rcp_f32_e32 v37, v37
	v_cvt_pk_bf16_f32 v98, v32, v33
	v_mul_f32_e32 v32, v34, v36
	v_mul_f32_e32 v33, v35, v37
	v_mul_f32_e32 v32, v32, v38
	v_mul_f32_e32 v33, v33, v39
	v_cvt_pk_bf16_f32 v99, v32, v33
	v_or_b32_e32 v34, 48, v58
	v_mov_b64_e32 v[32:33], s[18:19]
	v_mad_i64_i32 v[32:33], s[42:43], v34, s70, v[32:33]
	v_lshl_add_u64 v[32:33], v[176:177], 1, v[32:33]
	v_mov_b32_dpp v39, v24 row_ror:1 row_mask:0xf bank_mask:0xf
	v_mov_b32_dpp v40, v24 row_ror:2 row_mask:0xf bank_mask:0xf
	v_mov_b32_dpp v42, v25 row_ror:1 row_mask:0xf bank_mask:0xf
	v_mov_b32_dpp v43, v25 row_ror:2 row_mask:0xf bank_mask:0xf
	v_mov_b32_dpp v45, v26 row_ror:1 row_mask:0xf bank_mask:0xf
	v_mov_b32_dpp v44, v26 row_ror:2 row_mask:0xf bank_mask:0xf
	v_mov_b32_dpp v47, v27 row_ror:1 row_mask:0xf bank_mask:0xf
	v_mov_b32_dpp v46, v27 row_ror:2 row_mask:0xf bank_mask:0xf
	global_store_dwordx4 v[32:33], v[96:99], off
	s_and_saveexec_b64 s[42:43], s[10:11]
	s_cbranch_execz .LBB0_1368
	global_store_dwordx4 v[152:153], v[24:27], off offset:16
.LBB0_1368:
	s_or_b64 exec, exec, s[42:43]
	v_mov_b32_dpp v32, v28 row_ror:1 row_mask:0xf bank_mask:0xf
	v_mov_b32_dpp v33, v28 row_ror:2 row_mask:0xf bank_mask:0xf
	v_mov_b32_dpp v34, v29 row_ror:1 row_mask:0xf bank_mask:0xf
	v_mov_b32_dpp v35, v29 row_ror:2 row_mask:0xf bank_mask:0xf
	v_mov_b32_dpp v37, v30 row_ror:1 row_mask:0xf bank_mask:0xf
	v_mov_b32_dpp v36, v30 row_ror:2 row_mask:0xf bank_mask:0xf
	v_mov_b32_dpp v41, v31 row_ror:1 row_mask:0xf bank_mask:0xf
	v_mov_b32_dpp v38, v31 row_ror:2 row_mask:0xf bank_mask:0xf
	s_and_saveexec_b64 s[42:43], s[10:11]
	s_cbranch_execz .LBB0_1370
	v_lshl_add_u64 v[48:49], v[70:71], 2, v[130:131]
	v_add_co_u32_e32 v48, vcc, 0x2000, v48
	s_nop 1
	v_addc_co_u32_e32 v49, vcc, 0, v49, vcc
	global_store_dwordx4 v[48:49], v[28:31], off offset:3072
.LBB0_1370:
	s_or_b64 exec, exec, s[42:43]
	v_cndmask_b32_e64 v53, 0, v35, s[8:9]
	v_cndmask_b32_e64 v52, 0, v33, s[8:9]
	v_cndmask_b32_e64 v51, v34, 0, s[6:7]
	v_cndmask_b32_e64 v50, v32, 0, s[6:7]
	v_pk_fma_f32 v[52:53], v[122:123], v[52:53], v[118:119]
	v_cndmask_b32_e64 v55, 0, v38, s[8:9]
	v_pk_fma_f32 v[50:51], v[114:115], v[50:51], v[52:53]
	v_cndmask_b32_e64 v53, 0, v43, s[8:9]
	v_cndmask_b32_e64 v52, 0, v40, s[8:9]
	v_pk_fma_f32 v[28:29], v[28:29], v[100:101], v[50:51]
	v_cndmask_b32_e64 v51, v42, 0, s[6:7]
	v_cndmask_b32_e64 v50, v39, 0, s[6:7]
	v_pk_fma_f32 v[52:53], v[92:93], v[52:53], v[84:85]
	v_cndmask_b32_e64 v54, 0, v36, s[8:9]
	v_pk_fma_f32 v[50:51], v[66:67], v[50:51], v[52:53]
	v_cndmask_b32_e64 v49, v41, 0, s[6:7]
	v_pk_fma_f32 v[50:51], v[24:25], v[76:77], v[50:51]
	v_cndmask_b32_e64 v48, v37, 0, s[6:7]
	v_mul_f32_e32 v24, 0xbfb8aa3b, v50
	v_exp_f32_e32 v24, v24
	v_pk_fma_f32 v[54:55], v[124:125], v[54:55], v[120:121]
	v_mul_f32_e32 v25, 0xbfb8aa3b, v51
	v_pk_fma_f32 v[48:49], v[116:117], v[48:49], v[54:55]
	v_cndmask_b32_e64 v55, 0, v46, s[8:9]
	v_cndmask_b32_e64 v54, 0, v44, s[8:9]
	v_pk_fma_f32 v[30:31], v[30:31], v[102:103], v[48:49]
	v_cndmask_b32_e64 v49, v47, 0, s[6:7]
	v_cndmask_b32_e64 v48, v45, 0, s[6:7]
	v_pk_fma_f32 v[54:55], v[94:95], v[54:55], v[86:87]
	v_add_f32_e32 v24, 1.0, v24
	v_pk_fma_f32 v[48:49], v[68:69], v[48:49], v[54:55]
	v_exp_f32_e32 v25, v25
	v_pk_fma_f32 v[26:27], v[26:27], v[78:79], v[48:49]
	v_rcp_f32_e32 v48, v24
	v_mul_f32_e32 v49, 0xbfb8aa3b, v27
	v_add_f32_e32 v24, 1.0, v25
	v_rcp_f32_e32 v25, v24
	v_mul_f32_e32 v48, v50, v48
	v_mul_f32_e32 v28, v48, v28
	v_mul_f32_e32 v48, 0xbfb8aa3b, v26
	v_exp_f32_e32 v48, v48
	v_exp_f32_e32 v49, v49
	v_mul_f32_e32 v25, v51, v25
	v_mul_f32_e32 v25, v25, v29
	v_add_f32_e32 v29, 1.0, v48
	v_add_f32_e32 v48, 1.0, v49
	v_rcp_f32_e32 v29, v29
	v_rcp_f32_e32 v48, v48
	v_cvt_pk_bf16_f32 v90, v28, v25
; __device__ __forceinline__ unsigned cvt_pk_bf16(float lo, float hi) { unsigned r; asm volatile("v_cvt_pk_bf16_f32 %0, %1, %2" : "=v"(r) : "v"(lo), "v"(hi)); return r; }
; template <int CTRL> __device__ __forceinline__ float dpp_ror(float v) { return __builtin_bit_cast(float, __builtin_amdgcn_update_dpp(0, __builtin_bit_cast(int, v), CTRL, 0xf, 0xf, false)); }
; __device__ __forceinline__ float silu_f(float g) { return g * __builtin_amdgcn_rcpf(1.f + __builtin_amdgcn_exp2f(-g * LOG2E)); }
;     __device__ __forceinline__ void operator()(const f32x4 (&acc)[2][2][4][2], const pg8::Unit& u, int wr, int wc, int fr, int fq) const {
;     ...
;                 for (int m = 0; m < 4; ++m) {
;                     f32x4 y[2];
; #pragma unroll
;                     for (int bj = 0; bj < 2; ++bj) {
;                         const f32x4 cur = acc[ai][bj][m][n]; f32x4 r1, r2;
; #pragma unroll
;                         for (int j = 0; j < 4; ++j) { r1[j] = dpp_ror<0x121>(cur[j]); r2[j] = dpp_ror<0x122>(cur[j]); }
;                         const f32x4 s1 = (fr >= 1) ? r1 : p1[bj], s2 = (fr >= 2) ? r2 : p2[bj];
;                         y[bj] = bb[bj] + w[bj][0] * s2 + w[bj][1] * s1 + w[bj][2] * cur;
;                         p1[bj] = r1; p2[bj] = r2;
;                         if (m == 0 && fr < 2) *(f32x4*)(hf + (size_t)(wb * 2 + fr) * FFN2 + bj * FFN + f0) = cur;
;                         if (m == 3 && fr >= 14) *(f32x4*)(hl + (size_t)(wb * 2 + fr - 14) * FFN2 + bj * FFN + f0) = cur;
;                     }
;                     u32x2 o; o.x = pg8::cvt_pk_bf16(silu_f(y[0][0]) * y[1][0], silu_f(y[0][1]) * y[1][1]); o.y = pg8::cvt_pk_bf16(silu_f(y[0][2]) * y[1][2], silu_f(y[0][3]) * y[1][3]);
;                     if (n == 0) held[ai][m] = o;
;                     else *(u32x4*)(act + (size_t)(wb * 64 + m * 16 + fr) * FFN + f0 - 4) = (u32x4){held[ai][m].x, held[ai][m].y, o.x, o.y};
	v_lshl_or_b32 v24, s35, 6, v190
	v_mul_f32_e32 v25, v26, v29
	v_mul_f32_e32 v26, v27, v48
	v_mul_f32_e32 v25, v25, v30
	v_mul_f32_e32 v26, v26, v31
	v_mov_b64_e32 v[30:31], s[18:19]
	v_cvt_pk_bf16_f32 v91, v25, v26
	v_mad_i64_i32 v[26:27], s[42:43], v24, s70, v[30:31]
	v_lshl_add_u64 v[26:27], v[26:27], 0, v[56:57]
	v_mov_b32_dpp v48, v20 row_ror:2 row_mask:0xf bank_mask:0xf
	v_mov_b32_dpp v49, v21 row_ror:1 row_mask:0xf bank_mask:0xf
	v_mov_b32_dpp v50, v21 row_ror:2 row_mask:0xf bank_mask:0xf
	v_mov_b32_dpp v51, v22 row_ror:1 row_mask:0xf bank_mask:0xf
	v_mov_b32_dpp v52, v22 row_ror:2 row_mask:0xf bank_mask:0xf
	v_mov_b32_dpp v54, v23 row_ror:2 row_mask:0xf bank_mask:0xf
	global_store_dwordx4 v[26:27], v[88:91], off
	v_mov_b32_dpp v25, v20 row_ror:1 row_mask:0xf bank_mask:0xf
	v_mov_b32_dpp v53, v23 row_ror:1 row_mask:0xf bank_mask:0xf
	v_cndmask_b32_e64 v26, v51, v45, s[6:7]
	v_cndmask_b32_e64 v29, v49, v42, s[6:7]
	v_cndmask_b32_e64 v43, v43, v50, s[8:9]
	v_cndmask_b32_e64 v42, v40, v48, s[8:9]
	v_cndmask_b32_e64 v45, v46, v54, s[8:9]
	v_cndmask_b32_e64 v44, v44, v52, s[8:9]
	v_cndmask_b32_e64 v27, v53, v47, s[6:7]
	v_cndmask_b32_e64 v28, v25, v39, s[6:7]
	v_pk_fma_f32 v[44:45], v[94:95], v[44:45], v[86:87]
	v_pk_fma_f32 v[42:43], v[92:93], v[42:43], v[84:85]
	v_pk_fma_f32 v[26:27], v[68:69], v[26:27], v[44:45]
	v_pk_fma_f32 v[28:29], v[66:67], v[28:29], v[42:43]
	v_mov_b32_dpp v40, v16 row_ror:1 row_mask:0xf bank_mask:0xf
	v_mov_b32_dpp v42, v16 row_ror:2 row_mask:0xf bank_mask:0xf
	v_mov_b32_dpp v39, v17 row_ror:1 row_mask:0xf bank_mask:0xf
	v_mov_b32_dpp v45, v18 row_ror:2 row_mask:0xf bank_mask:0xf
	v_mov_b32_dpp v47, v19 row_ror:2 row_mask:0xf bank_mask:0xf
	v_pk_fma_f32 v[20:21], v[20:21], v[76:77], v[28:29]
	v_mov_b32_dpp v44, v18 row_ror:1 row_mask:0xf bank_mask:0xf
	v_mov_b32_dpp v46, v19 row_ror:1 row_mask:0xf bank_mask:0xf
	v_cndmask_b32_e64 v29, v39, v34, s[6:7]
	v_cndmask_b32_e64 v28, v40, v32, s[6:7]
	v_cndmask_b32_e64 v34, v33, v42, s[8:9]
	v_cndmask_b32_e64 v33, v38, v47, s[8:9]
	v_cndmask_b32_e64 v32, v36, v45, s[8:9]
	v_pk_fma_f32 v[22:23], v[22:23], v[78:79], v[26:27]
	v_cndmask_b32_e64 v27, v46, v41, s[6:7]
	v_cndmask_b32_e64 v26, v44, v37, s[6:7]
	v_pk_fma_f32 v[32:33], v[124:125], v[32:33], v[120:121]
	v_pk_fma_f32 v[26:27], v[116:117], v[26:27], v[32:33]
	v_mul_f32_e32 v32, 0xbfb8aa3b, v20
	v_exp_f32_e32 v32, v32
	v_mul_f32_e32 v33, 0xbfb8aa3b, v21
	v_exp_f32_e32 v33, v33
	v_pk_fma_f32 v[18:19], v[18:19], v[102:103], v[26:27]
	v_add_f32_e32 v26, 1.0, v32
	v_mov_b32_dpp v43, v17 row_ror:2 row_mask:0xf bank_mask:0xf
	v_rcp_f32_e32 v26, v26
	v_add_f32_e32 v27, 1.0, v33
	v_cndmask_b32_e64 v35, v35, v43, s[8:9]
	v_rcp_f32_e32 v27, v27
	v_pk_fma_f32 v[34:35], v[122:123], v[34:35], v[118:119]
	v_mul_f32_e32 v20, v20, v26
	v_pk_fma_f32 v[28:29], v[114:115], v[28:29], v[34:35]
	v_mul_f32_e32 v26, 0xbfb8aa3b, v23
	v_pk_fma_f32 v[16:17], v[16:17], v[100:101], v[28:29]
	v_exp_f32_e32 v26, v26
	v_mul_f32_e32 v16, v20, v16
	v_mul_f32_e32 v20, v21, v27
	v_mul_f32_e32 v21, 0xbfb8aa3b, v22
	v_exp_f32_e32 v21, v21
	v_mul_f32_e32 v17, v20, v17
	v_cvt_pk_bf16_f32 v82, v16, v17
	v_add_f32_e32 v20, 1.0, v21
	v_rcp_f32_e32 v20, v20
	v_add_f32_e32 v21, 1.0, v26
	v_rcp_f32_e32 v21, v21
	v_mul_f32_e32 v16, v22, v20
	v_mul_f32_e32 v16, v16, v18
	v_mul_f32_e32 v17, v23, v21
	v_mul_f32_e32 v17, v17, v19
	v_cvt_pk_bf16_f32 v83, v16, v17
	v_or_b32_e32 v16, 16, v24
	v_mad_i64_i32 v[16:17], s[42:43], v16, s70, v[30:31]
	v_lshl_add_u64 v[16:17], v[16:17], 0, v[56:57]
	global_store_dwordx4 v[16:17], v[80:83], off
	v_mov_b32_dpp v20, v12 row_ror:2 row_mask:0xf bank_mask:0xf
	v_mov_b32_dpp v21, v13 row_ror:2 row_mask:0xf bank_mask:0xf
	v_mov_b32_dpp v22, v14 row_ror:2 row_mask:0xf bank_mask:0xf
	v_mov_b32_dpp v23, v15 row_ror:2 row_mask:0xf bank_mask:0xf
	v_mov_b32_dpp v16, v12 row_ror:1 row_mask:0xf bank_mask:0xf
	v_mov_b32_dpp v17, v13 row_ror:1 row_mask:0xf bank_mask:0xf
	v_mov_b32_dpp v18, v14 row_ror:1 row_mask:0xf bank_mask:0xf
	v_mov_b32_dpp v19, v15 row_ror:1 row_mask:0xf bank_mask:0xf
; __device__ __forceinline__ unsigned cvt_pk_bf16(float lo, float hi) { unsigned r; asm volatile("v_cvt_pk_bf16_f32 %0, %1, %2" : "=v"(r) : "v"(lo), "v"(hi)); return r; }
; template <int CTRL> __device__ __forceinline__ float dpp_ror(float v) { return __builtin_bit_cast(float, __builtin_amdgcn_update_dpp(0, __builtin_bit_cast(int, v), CTRL, 0xf, 0xf, false)); }
; __device__ __forceinline__ float silu_f(float g) { return g * __builtin_amdgcn_rcpf(1.f + __builtin_amdgcn_exp2f(-g * LOG2E)); }
;     __device__ __forceinline__ void operator()(const f32x4 (&acc)[2][2][4][2], const pg8::Unit& u, int wr, int wc, int fr, int fq) const {
;     ...
;                 for (int m = 0; m < 4; ++m) {
;                     f32x4 y[2];
; #pragma unroll
;                     for (int bj = 0; bj < 2; ++bj) {
;                         const f32x4 cur = acc[ai][bj][m][n]; f32x4 r1, r2;
; #pragma unroll
;                         for (int j = 0; j < 4; ++j) { r1[j] = dpp_ror<0x121>(cur[j]); r2[j] = dpp_ror<0x122>(cur[j]); }
;                         const f32x4 s1 = (fr >= 1) ? r1 : p1[bj], s2 = (fr >= 2) ? r2 : p2[bj];
;                         y[bj] = bb[bj] + w[bj][0] * s2 + w[bj][1] * s1 + w[bj][2] * cur;
;                         p1[bj] = r1; p2[bj] = r2;
;                         if (m == 0 && fr < 2) *(f32x4*)(hf + (size_t)(wb * 2 + fr) * FFN2 + bj * FFN + f0) = cur;
;                         if (m == 3 && fr >= 14) *(f32x4*)(hl + (size_t)(wb * 2 + fr - 14) * FFN2 + bj * FFN + f0) = cur;
;                     }
;                     u32x2 o; o.x = pg8::cvt_pk_bf16(silu_f(y[0][0]) * y[1][0], silu_f(y[0][1]) * y[1][1]); o.y = pg8::cvt_pk_bf16(silu_f(y[0][2]) * y[1][2], silu_f(y[0][3]) * y[1][3]);
;                     if (n == 0) held[ai][m] = o;
;                     else *(u32x4*)(act + (size_t)(wb * 64 + m * 16 + fr) * FFN + f0 - 4) = (u32x4){held[ai][m].x, held[ai][m].y, o.x, o.y};
	v_cndmask_b32_e64 v33, v50, v21, s[8:9]
	v_cndmask_b32_e64 v32, v48, v20, s[8:9]
	v_cndmask_b32_e64 v35, v54, v23, s[8:9]
	v_cndmask_b32_e64 v34, v52, v22, s[8:9]
	v_cndmask_b32_e64 v27, v19, v53, s[6:7]
	v_cndmask_b32_e64 v26, v18, v51, s[6:7]
	v_cndmask_b32_e64 v29, v17, v49, s[6:7]
	v_cndmask_b32_e64 v28, v16, v25, s[6:7]
	v_pk_fma_f32 v[34:35], v[94:95], v[34:35], v[86:87]
	v_pk_fma_f32 v[32:33], v[92:93], v[32:33], v[84:85]
	v_pk_fma_f32 v[26:27], v[68:69], v[26:27], v[34:35]
	v_pk_fma_f32 v[28:29], v[66:67], v[28:29], v[32:33]
	v_pk_fma_f32 v[32:33], v[14:15], v[78:79], v[26:27]
	v_pk_fma_f32 v[34:35], v[12:13], v[76:77], v[28:29]
	v_mov_b32_dpp v12, v8 row_ror:1 row_mask:0xf bank_mask:0xf
	v_mov_b32_dpp v25, v8 row_ror:2 row_mask:0xf bank_mask:0xf
	v_mov_b32_dpp v26, v9 row_ror:2 row_mask:0xf bank_mask:0xf
	v_cndmask_b32_e64 v38, v12, v40, s[6:7]
	v_mov_b32_dpp v13, v9 row_ror:1 row_mask:0xf bank_mask:0xf
	v_cndmask_b32_e64 v41, v43, v26, s[8:9]
	v_cndmask_b32_e64 v40, v42, v25, s[8:9]
	v_cndmask_b32_e64 v39, v13, v39, s[6:7]
	v_pk_fma_f32 v[40:41], v[122:123], v[40:41], v[118:119]
	v_mul_f32_e32 v29, 0xbfb8aa3b, v34
	v_pk_fma_f32 v[38:39], v[114:115], v[38:39], v[40:41]
	v_exp_f32_e32 v29, v29
	v_mul_f32_e32 v40, 0xbfb8aa3b, v35
	v_mov_b32_dpp v27, v10 row_ror:2 row_mask:0xf bank_mask:0xf
	v_mov_b32_dpp v28, v11 row_ror:2 row_mask:0xf bank_mask:0xf
	v_exp_f32_e32 v40, v40
	v_mov_b32_dpp v14, v10 row_ror:1 row_mask:0xf bank_mask:0xf
	v_mov_b32_dpp v15, v11 row_ror:1 row_mask:0xf bank_mask:0xf
	v_cndmask_b32_e64 v43, v47, v28, s[8:9]
	v_cndmask_b32_e64 v42, v45, v27, s[8:9]
	v_cndmask_b32_e64 v37, v15, v46, s[6:7]
	v_cndmask_b32_e64 v36, v14, v44, s[6:7]
	v_pk_fma_f32 v[42:43], v[124:125], v[42:43], v[120:121]
	v_add_f32_e32 v29, 1.0, v29
	v_pk_fma_f32 v[36:37], v[116:117], v[36:37], v[42:43]
	v_rcp_f32_e32 v29, v29
	v_pk_fma_f32 v[10:11], v[10:11], v[102:103], v[36:37]
	v_add_f32_e32 v36, 1.0, v40
	v_rcp_f32_e32 v36, v36
	v_pk_fma_f32 v[8:9], v[8:9], v[100:101], v[38:39]
	v_mul_f32_e32 v29, v34, v29
	v_mul_f32_e32 v34, 0xbfb8aa3b, v32
	v_mul_f32_e32 v8, v29, v8
	v_mul_f32_e32 v29, v35, v36
	v_exp_f32_e32 v34, v34
	v_mul_f32_e32 v35, 0xbfb8aa3b, v33
	v_exp_f32_e32 v35, v35
	v_mul_f32_e32 v9, v29, v9
	v_add_f32_e32 v29, 1.0, v34
	v_rcp_f32_e32 v29, v29
	v_add_f32_e32 v34, 1.0, v35
	v_rcp_f32_e32 v34, v34
	v_cvt_pk_bf16_f32 v74, v8, v9
	v_mul_f32_e32 v8, v32, v29
	v_mul_f32_e32 v8, v8, v10
	v_mul_f32_e32 v9, v33, v34
	v_mul_f32_e32 v9, v9, v11
	v_cvt_pk_bf16_f32 v75, v8, v9
	v_or_b32_e32 v8, 32, v24
	v_mad_i64_i32 v[8:9], s[42:43], v8, s70, v[30:31]
	v_lshl_add_u64 v[8:9], v[8:9], 0, v[56:57]
	global_store_dwordx4 v[8:9], v[72:75], off
	v_mov_b32_dpp v8, v0 row_ror:1 row_mask:0xf bank_mask:0xf
	v_mov_b32_dpp v29, v0 row_ror:2 row_mask:0xf bank_mask:0xf
	v_mov_b32_dpp v9, v1 row_ror:1 row_mask:0xf bank_mask:0xf
	v_mov_b32_dpp v30, v1 row_ror:2 row_mask:0xf bank_mask:0xf
	v_mov_b32_dpp v10, v2 row_ror:1 row_mask:0xf bank_mask:0xf
	v_mov_b32_dpp v31, v2 row_ror:2 row_mask:0xf bank_mask:0xf
	v_mov_b32_dpp v11, v3 row_ror:1 row_mask:0xf bank_mask:0xf
	v_mov_b32_dpp v32, v3 row_ror:2 row_mask:0xf bank_mask:0xf
	s_and_saveexec_b64 s[42:43], s[12:13]
	s_cbranch_execz .LBB0_1372
	global_store_dwordx4 v[150:151], v[0:3], off offset:16
.LBB0_1372:
	s_or_b64 exec, exec, s[42:43]
	v_mov_b32_dpp v33, v4 row_ror:1 row_mask:0xf bank_mask:0xf
	v_mov_b32_dpp v37, v4 row_ror:2 row_mask:0xf bank_mask:0xf
	v_mov_b32_dpp v34, v5 row_ror:1 row_mask:0xf bank_mask:0xf
	v_mov_b32_dpp v38, v5 row_ror:2 row_mask:0xf bank_mask:0xf
	v_mov_b32_dpp v35, v6 row_ror:1 row_mask:0xf bank_mask:0xf
	v_mov_b32_dpp v39, v6 row_ror:2 row_mask:0xf bank_mask:0xf
	v_mov_b32_dpp v36, v7 row_ror:1 row_mask:0xf bank_mask:0xf
	v_mov_b32_dpp v40, v7 row_ror:2 row_mask:0xf bank_mask:0xf
	s_and_saveexec_b64 s[42:43], s[12:13]
	s_cbranch_execz .LBB0_1374
	v_lshl_add_u64 v[42:43], v[70:71], 2, v[128:129]
	v_add_co_u32_e32 v42, vcc, 0x2000, v42
	s_nop 1
	v_addc_co_u32_e32 v43, vcc, 0, v43, vcc
	global_store_dwordx4 v[42:43], v[4:7], off offset:3072
